# wave reductions (LayerNorm sums, top-k counts) via DPP/permlane-swap VALU instead of ds_bpermute chains; bit-identical
# speedup vs baseline: 1.0036x; 1.0036x over previous
; __device__ __forceinline__ float bf_lo(unsigned u) { return __uint_as_float(u << 16); }
; __device__ __forceinline__ float bf_hi(unsigned u) { return __uint_as_float(u & 0xffff0000u); }
; __device__ __forceinline__ float wave_sum(float v) {
; #pragma unroll
;     for (int o = 1; o < 64; o <<= 1) v += __shfl_xor(v, o);
;     return v;
; __device__ __forceinline__ void sgu_pool_chunk(KArgs A, int l, int chunk, LAS unsigned char* lds) {
;     ...
;     for (int i0 = 0; i0 < 16; i0 += 8) {
;         u32x4 x0[8], x1[8];
; #pragma unroll
;         for (int i = 0; i < 8; ++i) { const bf16_t* row = gv + (size_t)(t0 + w * 16 + i0 + i) * D_; x0[i] = *(const u32x4*)(row + lane * 8); x1[i] = *(const u32x4*)(row + 512 + lane * 8); }
; #pragma unroll
;         for (int i = 0; i < 8; ++i) {
;             float f[16] = {bf_lo(x0[i].x), bf_hi(x0[i].x), bf_lo(x0[i].y), bf_hi(x0[i].y), bf_lo(x0[i].z), bf_hi(x0[i].z), bf_lo(x0[i].w), bf_hi(x0[i].w),
;                            bf_lo(x1[i].x), bf_hi(x1[i].x), bf_lo(x1[i].y), bf_hi(x1[i].y), bf_lo(x1[i].z), bf_hi(x1[i].z), bf_lo(x1[i].w), bf_hi(x1[i].w)};
;             float s = 0.f;
; #pragma unroll
;             for (int j = 0; j < 16; ++j) s += f[j];
;             const float mean = wave_sum(s) * (1.f / D_); float s2 = 0.f;
; #pragma unroll
;             for (int j = 0; j < 16; ++j) { const float d = f[j] - mean; s2 += d * d; }
;             const float rstd = 1.f / sqrtf(wave_sum(s2) * (1.f / D_) + LN_EPS_);
;             if (lane == 0) { st_mean[w * 16 + i0 + i] = mean; st_rstd[w * 16 + i0 + i] = rstd; }
.LBB0_330:
	s_or_b32 s0, s8, s25
	s_ashr_i32 s1, s0, 31
	s_lshl_b64 s[26:27], s[0:1], 11
	v_lshl_add_u64 v[0:1], v[66:67], 0, s[26:27]
	global_load_dwordx4 v[60:63], v[0:1], off
	global_load_dwordx4 v[56:59], v[0:1], off offset:1024
	s_or_b32 s26, s0, 1
	s_ashr_i32 s27, s26, 31
	s_lshl_b64 s[26:27], s[26:27], 11
	v_lshl_add_u64 v[0:1], v[66:67], 0, s[26:27]
	s_or_b32 s26, s0, 2
	s_ashr_i32 s27, s26, 31
	s_lshl_b64 s[26:27], s[26:27], 11
	global_load_dwordx4 v[52:55], v[0:1], off
	global_load_dwordx4 v[48:51], v[0:1], off offset:1024
	v_lshl_add_u64 v[0:1], v[66:67], 0, s[26:27]
	s_or_b32 s26, s0, 3
	s_ashr_i32 s27, s26, 31
	s_lshl_b64 s[26:27], s[26:27], 11
	global_load_dwordx4 v[44:47], v[0:1], off
	global_load_dwordx4 v[40:43], v[0:1], off offset:1024
	v_lshl_add_u64 v[0:1], v[66:67], 0, s[26:27]
	s_or_b32 s26, s0, 4
	s_ashr_i32 s27, s26, 31
	s_lshl_b64 s[26:27], s[26:27], 11
	global_load_dwordx4 v[36:39], v[0:1], off
	global_load_dwordx4 v[32:35], v[0:1], off offset:1024
	v_lshl_add_u64 v[0:1], v[66:67], 0, s[26:27]
	s_or_b32 s26, s0, 5
	s_ashr_i32 s27, s26, 31
	s_lshl_b64 s[26:27], s[26:27], 11
	global_load_dwordx4 v[28:31], v[0:1], off
	global_load_dwordx4 v[24:27], v[0:1], off offset:1024
	v_lshl_add_u64 v[0:1], v[66:67], 0, s[26:27]
	s_or_b32 s26, s0, 6
	s_ashr_i32 s27, s26, 31
	s_or_b32 s0, s0, 7
	s_lshl_b64 s[26:27], s[26:27], 11
	s_ashr_i32 s1, s0, 31
	global_load_dwordx4 v[20:23], v[0:1], off
	global_load_dwordx4 v[16:19], v[0:1], off offset:1024
	v_lshl_add_u64 v[0:1], v[66:67], 0, s[26:27]
	s_lshl_b64 s[0:1], s[0:1], 11
	global_load_dwordx4 v[12:15], v[0:1], off
	global_load_dwordx4 v[8:11], v[0:1], off offset:1024
	v_lshl_add_u64 v[0:1], v[66:67], 0, s[0:1]
	global_load_dwordx4 v[4:7], v[0:1], off
	s_waitcnt lgkmcnt(0)
	global_load_dwordx4 v[0:3], v[0:1], off offset:1024
	s_or_b32 s19, s8, s5
	s_waitcnt vmcnt(0)
	v_lshlrev_b32_e32 v74, 16, v60
	v_and_b32_e32 v60, 0xffff0000, v60
	s_waitcnt vmcnt(14)
	v_lshlrev_b32_e32 v78, 16, v56
	v_and_b32_e32 v79, 0xffff0000, v56
	v_add_f32_e32 v56, 0, v74
	v_lshlrev_b32_e32 v75, 16, v61
	v_add_f32_e32 v56, v56, v60
	v_and_b32_e32 v61, 0xffff0000, v61
	v_add_f32_e32 v56, v56, v75
	v_lshlrev_b32_e32 v76, 16, v62
	v_add_f32_e32 v56, v56, v61
	v_and_b32_e32 v62, 0xffff0000, v62
	v_add_f32_e32 v56, v56, v76
	v_lshlrev_b32_e32 v77, 16, v63
	v_add_f32_e32 v56, v56, v62
	v_and_b32_e32 v63, 0xffff0000, v63
	v_add_f32_e32 v56, v56, v77
	v_add_f32_e32 v56, v56, v63
	v_add_f32_e32 v56, v56, v78
	v_lshlrev_b32_e32 v80, 16, v57
	v_add_f32_e32 v56, v56, v79
	v_and_b32_e32 v57, 0xffff0000, v57
	v_add_f32_e32 v56, v56, v80
	v_lshlrev_b32_e32 v81, 16, v58
	v_add_f32_e32 v56, v56, v57
	v_and_b32_e32 v58, 0xffff0000, v58
	v_add_f32_e32 v56, v56, v81
	v_lshlrev_b32_e32 v82, 16, v59
	v_add_f32_e32 v56, v56, v58
	v_and_b32_e32 v59, 0xffff0000, v59
	v_add_f32_e32 v56, v56, v82
	v_add_f32_e32 v56, v56, v59
	s_waitcnt lgkmcnt(0)
	s_nop 1
	v_add_f32_dpp v56, v56, v56 quad_perm:[1,0,3,2] row_mask:0xf bank_mask:0xf
	s_waitcnt lgkmcnt(0)
	s_nop 1
	v_add_f32_dpp v56, v56, v56 quad_perm:[2,3,0,1] row_mask:0xf bank_mask:0xf
	s_waitcnt lgkmcnt(0)
	s_nop 1
	v_add_f32_dpp v56, v56, v56 row_half_mirror row_mask:0xf bank_mask:0xf
	s_waitcnt lgkmcnt(0)
	s_nop 1
	v_add_f32_dpp v56, v56, v56 row_mirror row_mask:0xf bank_mask:0xf
	s_waitcnt lgkmcnt(0)
	v_mov_b32_e32 v83, v56
	s_nop 1
	v_permlane16_swap_b32 v56, v83
	v_add_f32_e32 v56, v56, v83
	s_waitcnt lgkmcnt(0)
	v_mov_b32_e32 v83, v56
	s_nop 1
	v_permlane32_swap_b32 v56, v83
	v_add_f32_e32 v56, v56, v83
	v_fmac_f32_e32 v60, 0xba800000, v56
	v_fmac_f32_e32 v74, 0xba800000, v56
	v_mul_f32_e32 v60, v60, v60
	v_fmac_f32_e32 v60, v74, v74
	v_fmac_f32_e32 v75, 0xba800000, v56
	v_fmac_f32_e32 v60, v75, v75
	v_fmac_f32_e32 v61, 0xba800000, v56
	v_fmac_f32_e32 v60, v61, v61
	v_fmac_f32_e32 v76, 0xba800000, v56
	v_fmac_f32_e32 v60, v76, v76
	v_fmac_f32_e32 v62, 0xba800000, v56
	v_fmac_f32_e32 v60, v62, v62
	v_fmac_f32_e32 v77, 0xba800000, v56
	v_fmac_f32_e32 v60, v77, v77
	v_fmac_f32_e32 v63, 0xba800000, v56
	v_fmac_f32_e32 v60, v63, v63
	v_fmac_f32_e32 v78, 0xba800000, v56
	v_fmac_f32_e32 v60, v78, v78
	v_fmac_f32_e32 v79, 0xba800000, v56
	v_fmac_f32_e32 v60, v79, v79
	v_fmac_f32_e32 v80, 0xba800000, v56
	v_fmac_f32_e32 v60, v80, v80
	v_fmac_f32_e32 v57, 0xba800000, v56
	v_fmac_f32_e32 v60, v57, v57
	v_fmac_f32_e32 v81, 0xba800000, v56
	v_fmac_f32_e32 v60, v81, v81
	v_fmac_f32_e32 v58, 0xba800000, v56
	v_fmac_f32_e32 v60, v58, v58
	v_fmac_f32_e32 v82, 0xba800000, v56
	v_fmac_f32_e32 v60, v82, v82
	v_fmac_f32_e32 v59, 0xba800000, v56
	v_fmac_f32_e32 v60, v59, v59
	s_waitcnt lgkmcnt(0)
	s_nop 1
	v_add_f32_dpp v57, v60, v60 quad_perm:[1,0,3,2] row_mask:0xf bank_mask:0xf
	s_waitcnt lgkmcnt(0)
	s_nop 1
	v_add_f32_dpp v57, v57, v57 quad_perm:[2,3,0,1] row_mask:0xf bank_mask:0xf
	s_waitcnt lgkmcnt(0)
	s_nop 1
	v_add_f32_dpp v57, v57, v57 row_half_mirror row_mask:0xf bank_mask:0xf
	s_waitcnt lgkmcnt(0)
	s_nop 1
	v_add_f32_dpp v57, v57, v57 row_mirror row_mask:0xf bank_mask:0xf
	s_waitcnt lgkmcnt(0)
	v_mov_b32_e32 v58, v57
	s_nop 1
	v_permlane16_swap_b32 v57, v58
	v_add_f32_e32 v57, v57, v58
	ds_bpermute_b32 v58, v73, v57
	s_and_saveexec_b64 s[0:1], s[6:7]
	s_cbranch_execz .LBB0_332
	s_waitcnt lgkmcnt(0)
	v_add_f32_e32 v57, v57, v58
	v_fmamk_f32 v57, v57, 0x3a800000, v227
	v_mul_f32_e32 v58, 0x4f800000, v57
	v_cmp_gt_f32_e32 vcc, s47, v57
	v_mul_f32_e32 v56, 0x3a800000, v56
	s_nop 0
	v_cndmask_b32_e32 v57, v57, v58, vcc
	v_sqrt_f32_e32 v58, v57
	s_nop 0
	v_add_u32_e32 v59, -1, v58
	v_fma_f32 v61, -v59, v58, v57
	v_add_u32_e32 v60, 1, v58
	v_cmp_ge_f32_e64 s[8:9], 0, v61
	s_nop 1
	v_cndmask_b32_e64 v59, v58, v59, s[8:9]
	v_fma_f32 v58, -v60, v58, v57
	v_cmp_lt_f32_e64 s[8:9], 0, v58
	s_nop 1
	v_cndmask_b32_e64 v58, v59, v60, s[8:9]
	v_mul_f32_e32 v59, 0x37800000, v58
	v_cndmask_b32_e32 v58, v58, v59, vcc
	v_cmp_class_f32_e32 vcc, v57, v228
	s_nop 1
	v_cndmask_b32_e32 v57, v58, v57, vcc
	v_div_scale_f32 v58, s[8:9], v57, v57, 1.0
	v_rcp_f32_e32 v59, v58
	s_lshl_b32 s8, s19, 2
	s_add_i32 s8, s8, 0
	s_add_i32 s9, s8, 0x11000
	v_fma_f32 v60, -v58, v59, 1.0
	v_fmac_f32_e32 v59, v60, v59
	v_div_scale_f32 v60, vcc, 1.0, v57, 1.0
	v_mul_f32_e32 v61, v60, v59
	v_fma_f32 v62, -v58, v61, v60
	v_fmac_f32_e32 v61, v62, v59
	v_fma_f32 v58, -v58, v61, v60
	v_div_fmas_f32 v58, v58, v59, v61
	v_div_fixup_f32 v57, v58, v57, 1.0
	v_mov_b32_e32 v58, s9
	s_add_i32 s8, s8, 0x11200
	ds_write_b32 v58, v56
	v_mov_b32_e32 v56, s8
	ds_write_b32 v56, v57
; __device__ __forceinline__ float bf_lo(unsigned u) { return __uint_as_float(u << 16); }
; __device__ __forceinline__ float bf_hi(unsigned u) { return __uint_as_float(u & 0xffff0000u); }
; __device__ __forceinline__ float wave_sum(float v) {
; #pragma unroll
;     for (int o = 1; o < 64; o <<= 1) v += __shfl_xor(v, o);
;     return v;
; __device__ __forceinline__ void sgu_pool_chunk(KArgs A, int l, int chunk, LAS unsigned char* lds) {
;     ...
;         for (int i = 0; i < 8; ++i) {
;             float f[16] = {bf_lo(x0[i].x), bf_hi(x0[i].x), bf_lo(x0[i].y), bf_hi(x0[i].y), bf_lo(x0[i].z), bf_hi(x0[i].z), bf_lo(x0[i].w), bf_hi(x0[i].w),
;                            bf_lo(x1[i].x), bf_hi(x1[i].x), bf_lo(x1[i].y), bf_hi(x1[i].y), bf_lo(x1[i].z), bf_hi(x1[i].z), bf_lo(x1[i].w), bf_hi(x1[i].w)};
;             float s = 0.f;
; #pragma unroll
;             for (int j = 0; j < 16; ++j) s += f[j];
;             const float mean = wave_sum(s) * (1.f / D_); float s2 = 0.f;
; #pragma unroll
;             for (int j = 0; j < 16; ++j) { const float d = f[j] - mean; s2 += d * d; }
;             const float rstd = 1.f / sqrtf(wave_sum(s2) * (1.f / D_) + LN_EPS_);
;             if (lane == 0) { st_mean[w * 16 + i0 + i] = mean; st_rstd[w * 16 + i0 + i] = rstd; }
.LBB0_332:
	s_or_b64 exec, exec, s[0:1]
	s_waitcnt vmcnt(13)
	v_lshlrev_b32_e32 v56, 16, v52
	v_and_b32_e32 v52, 0xffff0000, v52
	s_waitcnt vmcnt(12)
	v_lshlrev_b32_e32 v60, 16, v48
	v_and_b32_e32 v61, 0xffff0000, v48
	v_add_f32_e32 v48, 0, v56
	v_lshlrev_b32_e32 v57, 16, v53
	v_add_f32_e32 v48, v48, v52
	v_and_b32_e32 v53, 0xffff0000, v53
	v_add_f32_e32 v48, v48, v57
	s_waitcnt lgkmcnt(0)
	v_lshlrev_b32_e32 v58, 16, v54
	v_add_f32_e32 v48, v48, v53
	v_and_b32_e32 v54, 0xffff0000, v54
	v_add_f32_e32 v48, v48, v58
	v_lshlrev_b32_e32 v59, 16, v55
	v_add_f32_e32 v48, v48, v54
	v_and_b32_e32 v55, 0xffff0000, v55
	v_add_f32_e32 v48, v48, v59
	v_add_f32_e32 v48, v48, v55
	v_add_f32_e32 v48, v48, v60
	v_lshlrev_b32_e32 v62, 16, v49
	v_add_f32_e32 v48, v48, v61
	v_and_b32_e32 v49, 0xffff0000, v49
	v_add_f32_e32 v48, v48, v62
	v_lshlrev_b32_e32 v63, 16, v50
	v_add_f32_e32 v48, v48, v49
	v_and_b32_e32 v50, 0xffff0000, v50
	v_add_f32_e32 v48, v48, v63
	v_lshlrev_b32_e32 v74, 16, v51
	v_add_f32_e32 v48, v48, v50
	v_and_b32_e32 v51, 0xffff0000, v51
	v_add_f32_e32 v48, v48, v74
	v_add_f32_e32 v48, v48, v51
	s_waitcnt lgkmcnt(0)
	s_nop 1
	v_add_f32_dpp v48, v48, v48 quad_perm:[1,0,3,2] row_mask:0xf bank_mask:0xf
	s_waitcnt lgkmcnt(0)
	s_nop 1
	v_add_f32_dpp v48, v48, v48 quad_perm:[2,3,0,1] row_mask:0xf bank_mask:0xf
	s_waitcnt lgkmcnt(0)
	s_nop 1
	v_add_f32_dpp v48, v48, v48 row_half_mirror row_mask:0xf bank_mask:0xf
	s_waitcnt lgkmcnt(0)
	s_nop 1
	v_add_f32_dpp v48, v48, v48 row_mirror row_mask:0xf bank_mask:0xf
	s_waitcnt lgkmcnt(0)
	v_mov_b32_e32 v75, v48
	s_nop 1
	v_permlane16_swap_b32 v48, v75
	v_add_f32_e32 v48, v48, v75
	s_waitcnt lgkmcnt(0)
	v_mov_b32_e32 v75, v48
	s_nop 1
	v_permlane32_swap_b32 v48, v75
	v_add_f32_e32 v48, v48, v75
	v_fmac_f32_e32 v52, 0xba800000, v48
	v_fmac_f32_e32 v56, 0xba800000, v48
	v_mul_f32_e32 v52, v52, v52
	v_fmac_f32_e32 v57, 0xba800000, v48
	v_fmac_f32_e32 v52, v56, v56
	v_fmac_f32_e32 v53, 0xba800000, v48
	v_fmac_f32_e32 v52, v57, v57
	v_fmac_f32_e32 v58, 0xba800000, v48
	v_fmac_f32_e32 v52, v53, v53
	v_fmac_f32_e32 v54, 0xba800000, v48
	v_fmac_f32_e32 v52, v58, v58
	v_fmac_f32_e32 v59, 0xba800000, v48
	v_fmac_f32_e32 v52, v54, v54
	v_fmac_f32_e32 v55, 0xba800000, v48
	v_fmac_f32_e32 v52, v59, v59
	v_fmac_f32_e32 v60, 0xba800000, v48
	v_fmac_f32_e32 v52, v55, v55
	v_fmac_f32_e32 v61, 0xba800000, v48
	v_fmac_f32_e32 v52, v60, v60
	v_fmac_f32_e32 v52, v61, v61
	v_fmac_f32_e32 v62, 0xba800000, v48
	v_fmac_f32_e32 v52, v62, v62
	v_fmac_f32_e32 v49, 0xba800000, v48
	v_fmac_f32_e32 v52, v49, v49
	v_fmac_f32_e32 v63, 0xba800000, v48
	v_fmac_f32_e32 v52, v63, v63
	v_fmac_f32_e32 v50, 0xba800000, v48
	v_fmac_f32_e32 v52, v50, v50
	v_fmac_f32_e32 v74, 0xba800000, v48
	v_fmac_f32_e32 v52, v74, v74
	v_fmac_f32_e32 v51, 0xba800000, v48
	v_fmac_f32_e32 v52, v51, v51
	s_waitcnt lgkmcnt(0)
	s_nop 1
	v_add_f32_dpp v49, v52, v52 quad_perm:[1,0,3,2] row_mask:0xf bank_mask:0xf
	s_waitcnt lgkmcnt(0)
	s_nop 1
	v_add_f32_dpp v49, v49, v49 quad_perm:[2,3,0,1] row_mask:0xf bank_mask:0xf
	s_waitcnt lgkmcnt(0)
	s_nop 1
	v_add_f32_dpp v49, v49, v49 row_half_mirror row_mask:0xf bank_mask:0xf
	s_waitcnt lgkmcnt(0)
	s_nop 1
	v_add_f32_dpp v49, v49, v49 row_mirror row_mask:0xf bank_mask:0xf
	s_waitcnt lgkmcnt(0)
	v_mov_b32_e32 v50, v49
	s_nop 1
	v_permlane16_swap_b32 v49, v50
	v_add_f32_e32 v49, v49, v50
	ds_bpermute_b32 v50, v73, v49
	s_and_saveexec_b64 s[0:1], s[6:7]
	s_cbranch_execz .LBB0_334
	s_waitcnt lgkmcnt(0)
	v_add_f32_e32 v49, v49, v50
	v_fmamk_f32 v49, v49, 0x3a800000, v227
	v_mul_f32_e32 v50, 0x4f800000, v49
	v_cmp_gt_f32_e32 vcc, s47, v49
	v_mul_f32_e32 v48, 0x3a800000, v48
	s_nop 0
	v_cndmask_b32_e32 v49, v49, v50, vcc
	v_sqrt_f32_e32 v50, v49
	s_nop 0
	v_add_u32_e32 v51, -1, v50
	v_fma_f32 v53, -v51, v50, v49
	v_add_u32_e32 v52, 1, v50
	v_cmp_ge_f32_e64 s[8:9], 0, v53
	s_nop 1
	v_cndmask_b32_e64 v51, v50, v51, s[8:9]
	v_fma_f32 v50, -v52, v50, v49
	v_cmp_lt_f32_e64 s[8:9], 0, v50
	s_nop 1
	v_cndmask_b32_e64 v50, v51, v52, s[8:9]
	v_mul_f32_e32 v51, 0x37800000, v50
	v_cndmask_b32_e32 v50, v50, v51, vcc
	v_cmp_class_f32_e32 vcc, v49, v228
	s_nop 1
	v_cndmask_b32_e32 v49, v50, v49, vcc
	v_div_scale_f32 v50, s[8:9], v49, v49, 1.0
	v_rcp_f32_e32 v51, v50
	s_lshl_b32 s8, s19, 2
	s_add_i32 s8, s8, 0
	s_add_i32 s9, s8, 0x11004
	v_fma_f32 v52, -v50, v51, 1.0
	v_fmac_f32_e32 v51, v52, v51
	v_div_scale_f32 v52, vcc, 1.0, v49, 1.0
	v_mul_f32_e32 v53, v52, v51
	v_fma_f32 v54, -v50, v53, v52
	v_fmac_f32_e32 v53, v54, v51
	v_fma_f32 v50, -v50, v53, v52
	v_div_fmas_f32 v50, v50, v51, v53
	v_div_fixup_f32 v49, v50, v49, 1.0
	v_mov_b32_e32 v50, s9
	s_add_i32 s8, s8, 0x11204
	ds_write_b32 v50, v48
	v_mov_b32_e32 v48, s8
	ds_write_b32 v48, v49
; __device__ __forceinline__ float bf_lo(unsigned u) { return __uint_as_float(u << 16); }
; __device__ __forceinline__ float bf_hi(unsigned u) { return __uint_as_float(u & 0xffff0000u); }
; __device__ __forceinline__ float wave_sum(float v) {
; #pragma unroll
;     for (int o = 1; o < 64; o <<= 1) v += __shfl_xor(v, o);
;     return v;
; __device__ __forceinline__ void sgu_pool_chunk(KArgs A, int l, int chunk, LAS unsigned char* lds) {
;     ...
;         for (int i = 0; i < 8; ++i) {
;             float f[16] = {bf_lo(x0[i].x), bf_hi(x0[i].x), bf_lo(x0[i].y), bf_hi(x0[i].y), bf_lo(x0[i].z), bf_hi(x0[i].z), bf_lo(x0[i].w), bf_hi(x0[i].w),
;                            bf_lo(x1[i].x), bf_hi(x1[i].x), bf_lo(x1[i].y), bf_hi(x1[i].y), bf_lo(x1[i].z), bf_hi(x1[i].z), bf_lo(x1[i].w), bf_hi(x1[i].w)};
;             float s = 0.f;
; #pragma unroll
;             for (int j = 0; j < 16; ++j) s += f[j];
;             const float mean = wave_sum(s) * (1.f / D_); float s2 = 0.f;
; #pragma unroll
;             for (int j = 0; j < 16; ++j) { const float d = f[j] - mean; s2 += d * d; }
;             const float rstd = 1.f / sqrtf(wave_sum(s2) * (1.f / D_) + LN_EPS_);
;             if (lane == 0) { st_mean[w * 16 + i0 + i] = mean; st_rstd[w * 16 + i0 + i] = rstd; }
.LBB0_334:
	s_or_b64 exec, exec, s[0:1]
	s_waitcnt vmcnt(11)
	v_lshlrev_b32_e32 v48, 16, v44
	v_and_b32_e32 v44, 0xffff0000, v44
	s_waitcnt vmcnt(10)
	v_lshlrev_b32_e32 v52, 16, v40
	v_and_b32_e32 v53, 0xffff0000, v40
	v_add_f32_e32 v40, 0, v48
	v_lshlrev_b32_e32 v49, 16, v45
	v_add_f32_e32 v40, v40, v44
	v_and_b32_e32 v45, 0xffff0000, v45
	v_add_f32_e32 v40, v40, v49
	s_waitcnt lgkmcnt(0)
	v_lshlrev_b32_e32 v50, 16, v46
	v_add_f32_e32 v40, v40, v45
	v_and_b32_e32 v46, 0xffff0000, v46
	v_add_f32_e32 v40, v40, v50
	v_lshlrev_b32_e32 v51, 16, v47
	v_add_f32_e32 v40, v40, v46
	v_and_b32_e32 v47, 0xffff0000, v47
	v_add_f32_e32 v40, v40, v51
	v_add_f32_e32 v40, v40, v47
	v_add_f32_e32 v40, v40, v52
	v_lshlrev_b32_e32 v54, 16, v41
	v_add_f32_e32 v40, v40, v53
	v_and_b32_e32 v41, 0xffff0000, v41
	v_add_f32_e32 v40, v40, v54
	v_lshlrev_b32_e32 v55, 16, v42
	v_add_f32_e32 v40, v40, v41
	v_and_b32_e32 v42, 0xffff0000, v42
	v_add_f32_e32 v40, v40, v55
	v_lshlrev_b32_e32 v56, 16, v43
	v_add_f32_e32 v40, v40, v42
	v_and_b32_e32 v43, 0xffff0000, v43
	v_add_f32_e32 v40, v40, v56
	v_add_f32_e32 v40, v40, v43
	s_waitcnt lgkmcnt(0)
	s_nop 1
	v_add_f32_dpp v40, v40, v40 quad_perm:[1,0,3,2] row_mask:0xf bank_mask:0xf
	s_waitcnt lgkmcnt(0)
	s_nop 1
	v_add_f32_dpp v40, v40, v40 quad_perm:[2,3,0,1] row_mask:0xf bank_mask:0xf
	s_waitcnt lgkmcnt(0)
	s_nop 1
	v_add_f32_dpp v40, v40, v40 row_half_mirror row_mask:0xf bank_mask:0xf
	s_waitcnt lgkmcnt(0)
	s_nop 1
	v_add_f32_dpp v40, v40, v40 row_mirror row_mask:0xf bank_mask:0xf
	s_waitcnt lgkmcnt(0)
	v_mov_b32_e32 v57, v40
	s_nop 1
	v_permlane16_swap_b32 v40, v57
	v_add_f32_e32 v40, v40, v57
	s_waitcnt lgkmcnt(0)
	v_mov_b32_e32 v57, v40
	s_nop 1
	v_permlane32_swap_b32 v40, v57
	v_add_f32_e32 v40, v40, v57
	v_fmac_f32_e32 v44, 0xba800000, v40
	v_fmac_f32_e32 v48, 0xba800000, v40
	v_mul_f32_e32 v44, v44, v44
	v_fmac_f32_e32 v49, 0xba800000, v40
	v_fmac_f32_e32 v44, v48, v48
	v_fmac_f32_e32 v45, 0xba800000, v40
	v_fmac_f32_e32 v44, v49, v49
	v_fmac_f32_e32 v50, 0xba800000, v40
	v_fmac_f32_e32 v44, v45, v45
	v_fmac_f32_e32 v46, 0xba800000, v40
	v_fmac_f32_e32 v44, v50, v50
	v_fmac_f32_e32 v51, 0xba800000, v40
	v_fmac_f32_e32 v44, v46, v46
	v_fmac_f32_e32 v47, 0xba800000, v40
	v_fmac_f32_e32 v44, v51, v51
	v_fmac_f32_e32 v52, 0xba800000, v40
	v_fmac_f32_e32 v44, v47, v47
	v_fmac_f32_e32 v53, 0xba800000, v40
	v_fmac_f32_e32 v44, v52, v52
	v_fmac_f32_e32 v44, v53, v53
	v_fmac_f32_e32 v54, 0xba800000, v40
	v_fmac_f32_e32 v44, v54, v54
	v_fmac_f32_e32 v41, 0xba800000, v40
	v_fmac_f32_e32 v44, v41, v41
	v_fmac_f32_e32 v55, 0xba800000, v40
	v_fmac_f32_e32 v44, v55, v55
	v_fmac_f32_e32 v42, 0xba800000, v40
	v_fmac_f32_e32 v44, v42, v42
	v_fmac_f32_e32 v56, 0xba800000, v40
	v_fmac_f32_e32 v44, v56, v56
	v_fmac_f32_e32 v43, 0xba800000, v40
	v_fmac_f32_e32 v44, v43, v43
	s_waitcnt lgkmcnt(0)
	s_nop 1
	v_add_f32_dpp v41, v44, v44 quad_perm:[1,0,3,2] row_mask:0xf bank_mask:0xf
	s_waitcnt lgkmcnt(0)
	s_nop 1
	v_add_f32_dpp v41, v41, v41 quad_perm:[2,3,0,1] row_mask:0xf bank_mask:0xf
	s_waitcnt lgkmcnt(0)
	s_nop 1
	v_add_f32_dpp v41, v41, v41 row_half_mirror row_mask:0xf bank_mask:0xf
	s_waitcnt lgkmcnt(0)
	s_nop 1
	v_add_f32_dpp v41, v41, v41 row_mirror row_mask:0xf bank_mask:0xf
	s_waitcnt lgkmcnt(0)
	v_mov_b32_e32 v42, v41
	s_nop 1
	v_permlane16_swap_b32 v41, v42
	v_add_f32_e32 v41, v41, v42
	ds_bpermute_b32 v42, v73, v41
	s_and_saveexec_b64 s[0:1], s[6:7]
	s_cbranch_execz .LBB0_336
	s_waitcnt lgkmcnt(0)
	v_add_f32_e32 v41, v41, v42
	v_fmamk_f32 v41, v41, 0x3a800000, v227
	v_mul_f32_e32 v42, 0x4f800000, v41
	v_cmp_gt_f32_e32 vcc, s47, v41
	v_mul_f32_e32 v40, 0x3a800000, v40
	s_nop 0
	v_cndmask_b32_e32 v41, v41, v42, vcc
	v_sqrt_f32_e32 v42, v41
	s_nop 0
	v_add_u32_e32 v43, -1, v42
	v_fma_f32 v45, -v43, v42, v41
	v_add_u32_e32 v44, 1, v42
	v_cmp_ge_f32_e64 s[8:9], 0, v45
	s_nop 1
	v_cndmask_b32_e64 v43, v42, v43, s[8:9]
	v_fma_f32 v42, -v44, v42, v41
	v_cmp_lt_f32_e64 s[8:9], 0, v42
	s_nop 1
	v_cndmask_b32_e64 v42, v43, v44, s[8:9]
	v_mul_f32_e32 v43, 0x37800000, v42
	v_cndmask_b32_e32 v42, v42, v43, vcc
	v_cmp_class_f32_e32 vcc, v41, v228
	s_nop 1
	v_cndmask_b32_e32 v41, v42, v41, vcc
	v_div_scale_f32 v42, s[8:9], v41, v41, 1.0
	v_rcp_f32_e32 v43, v42
	s_lshl_b32 s8, s19, 2
	s_add_i32 s8, s8, 0
	s_add_i32 s9, s8, 0x11008
	v_fma_f32 v44, -v42, v43, 1.0
	v_fmac_f32_e32 v43, v44, v43
	v_div_scale_f32 v44, vcc, 1.0, v41, 1.0
	v_mul_f32_e32 v45, v44, v43
	v_fma_f32 v46, -v42, v45, v44
	v_fmac_f32_e32 v45, v46, v43
	v_fma_f32 v42, -v42, v45, v44
	v_div_fmas_f32 v42, v42, v43, v45
	v_div_fixup_f32 v41, v42, v41, 1.0
	v_mov_b32_e32 v42, s9
	s_add_i32 s8, s8, 0x11208
	ds_write_b32 v42, v40
	v_mov_b32_e32 v40, s8
	ds_write_b32 v40, v41
; __device__ __forceinline__ float bf_lo(unsigned u) { return __uint_as_float(u << 16); }
; __device__ __forceinline__ float bf_hi(unsigned u) { return __uint_as_float(u & 0xffff0000u); }
; __device__ __forceinline__ float wave_sum(float v) {
; #pragma unroll
;     for (int o = 1; o < 64; o <<= 1) v += __shfl_xor(v, o);
;     return v;
; __device__ __forceinline__ void sgu_pool_chunk(KArgs A, int l, int chunk, LAS unsigned char* lds) {
;     ...
;         for (int i = 0; i < 8; ++i) {
;             float f[16] = {bf_lo(x0[i].x), bf_hi(x0[i].x), bf_lo(x0[i].y), bf_hi(x0[i].y), bf_lo(x0[i].z), bf_hi(x0[i].z), bf_lo(x0[i].w), bf_hi(x0[i].w),
;                            bf_lo(x1[i].x), bf_hi(x1[i].x), bf_lo(x1[i].y), bf_hi(x1[i].y), bf_lo(x1[i].z), bf_hi(x1[i].z), bf_lo(x1[i].w), bf_hi(x1[i].w)};
;             float s = 0.f;
; #pragma unroll
;             for (int j = 0; j < 16; ++j) s += f[j];
;             const float mean = wave_sum(s) * (1.f / D_); float s2 = 0.f;
; #pragma unroll
;             for (int j = 0; j < 16; ++j) { const float d = f[j] - mean; s2 += d * d; }
;             const float rstd = 1.f / sqrtf(wave_sum(s2) * (1.f / D_) + LN_EPS_);
;             if (lane == 0) { st_mean[w * 16 + i0 + i] = mean; st_rstd[w * 16 + i0 + i] = rstd; }
.LBB0_336:
	s_or_b64 exec, exec, s[0:1]
	s_waitcnt vmcnt(9)
	v_lshlrev_b32_e32 v40, 16, v36
	v_and_b32_e32 v36, 0xffff0000, v36
	s_waitcnt vmcnt(8)
	v_lshlrev_b32_e32 v44, 16, v32
	v_and_b32_e32 v45, 0xffff0000, v32
	v_add_f32_e32 v32, 0, v40
	v_lshlrev_b32_e32 v41, 16, v37
	v_add_f32_e32 v32, v32, v36
	v_and_b32_e32 v37, 0xffff0000, v37
	v_add_f32_e32 v32, v32, v41
	s_waitcnt lgkmcnt(0)
	v_lshlrev_b32_e32 v42, 16, v38
	v_add_f32_e32 v32, v32, v37
	v_and_b32_e32 v38, 0xffff0000, v38
	v_add_f32_e32 v32, v32, v42
	v_lshlrev_b32_e32 v43, 16, v39
	v_add_f32_e32 v32, v32, v38
	v_and_b32_e32 v39, 0xffff0000, v39
	v_add_f32_e32 v32, v32, v43
	v_add_f32_e32 v32, v32, v39
	v_add_f32_e32 v32, v32, v44
	v_lshlrev_b32_e32 v46, 16, v33
	v_add_f32_e32 v32, v32, v45
	v_and_b32_e32 v33, 0xffff0000, v33
	v_add_f32_e32 v32, v32, v46
	v_lshlrev_b32_e32 v47, 16, v34
	v_add_f32_e32 v32, v32, v33
	v_and_b32_e32 v34, 0xffff0000, v34
	v_add_f32_e32 v32, v32, v47
	v_lshlrev_b32_e32 v48, 16, v35
	v_add_f32_e32 v32, v32, v34
	v_and_b32_e32 v35, 0xffff0000, v35
	v_add_f32_e32 v32, v32, v48
	v_add_f32_e32 v32, v32, v35
	s_waitcnt lgkmcnt(0)
	s_nop 1
	v_add_f32_dpp v32, v32, v32 quad_perm:[1,0,3,2] row_mask:0xf bank_mask:0xf
	s_waitcnt lgkmcnt(0)
	s_nop 1
	v_add_f32_dpp v32, v32, v32 quad_perm:[2,3,0,1] row_mask:0xf bank_mask:0xf
	s_waitcnt lgkmcnt(0)
	s_nop 1
	v_add_f32_dpp v32, v32, v32 row_half_mirror row_mask:0xf bank_mask:0xf
	s_waitcnt lgkmcnt(0)
	s_nop 1
	v_add_f32_dpp v32, v32, v32 row_mirror row_mask:0xf bank_mask:0xf
	s_waitcnt lgkmcnt(0)
	v_mov_b32_e32 v49, v32
	s_nop 1
	v_permlane16_swap_b32 v32, v49
	v_add_f32_e32 v32, v32, v49
	s_waitcnt lgkmcnt(0)
	v_mov_b32_e32 v49, v32
	s_nop 1
	v_permlane32_swap_b32 v32, v49
	v_add_f32_e32 v32, v32, v49
	v_fmac_f32_e32 v36, 0xba800000, v32
	v_fmac_f32_e32 v40, 0xba800000, v32
	v_mul_f32_e32 v36, v36, v36
	v_fmac_f32_e32 v41, 0xba800000, v32
	v_fmac_f32_e32 v36, v40, v40
	v_fmac_f32_e32 v37, 0xba800000, v32
	v_fmac_f32_e32 v36, v41, v41
	v_fmac_f32_e32 v42, 0xba800000, v32
	v_fmac_f32_e32 v36, v37, v37
	v_fmac_f32_e32 v38, 0xba800000, v32
	v_fmac_f32_e32 v36, v42, v42
	v_fmac_f32_e32 v43, 0xba800000, v32
	v_fmac_f32_e32 v36, v38, v38
	v_fmac_f32_e32 v39, 0xba800000, v32
	v_fmac_f32_e32 v36, v43, v43
	v_fmac_f32_e32 v44, 0xba800000, v32
	v_fmac_f32_e32 v36, v39, v39
	v_fmac_f32_e32 v45, 0xba800000, v32
	v_fmac_f32_e32 v36, v44, v44
	v_fmac_f32_e32 v36, v45, v45
	v_fmac_f32_e32 v46, 0xba800000, v32
	v_fmac_f32_e32 v36, v46, v46
	v_fmac_f32_e32 v33, 0xba800000, v32
	v_fmac_f32_e32 v36, v33, v33
	v_fmac_f32_e32 v47, 0xba800000, v32
	v_fmac_f32_e32 v36, v47, v47
	v_fmac_f32_e32 v34, 0xba800000, v32
	v_fmac_f32_e32 v36, v34, v34
	v_fmac_f32_e32 v48, 0xba800000, v32
	v_fmac_f32_e32 v36, v48, v48
	v_fmac_f32_e32 v35, 0xba800000, v32
	v_fmac_f32_e32 v36, v35, v35
	s_waitcnt lgkmcnt(0)
	s_nop 1
	v_add_f32_dpp v33, v36, v36 quad_perm:[1,0,3,2] row_mask:0xf bank_mask:0xf
	s_waitcnt lgkmcnt(0)
	s_nop 1
	v_add_f32_dpp v33, v33, v33 quad_perm:[2,3,0,1] row_mask:0xf bank_mask:0xf
	s_waitcnt lgkmcnt(0)
	s_nop 1
	v_add_f32_dpp v33, v33, v33 row_half_mirror row_mask:0xf bank_mask:0xf
	s_waitcnt lgkmcnt(0)
	s_nop 1
	v_add_f32_dpp v33, v33, v33 row_mirror row_mask:0xf bank_mask:0xf
	s_waitcnt lgkmcnt(0)
	v_mov_b32_e32 v34, v33
	s_nop 1
	v_permlane16_swap_b32 v33, v34
	v_add_f32_e32 v33, v33, v34
	ds_bpermute_b32 v34, v73, v33
	s_and_saveexec_b64 s[0:1], s[6:7]
	s_cbranch_execz .LBB0_338
	s_waitcnt lgkmcnt(0)
	v_add_f32_e32 v33, v33, v34
	v_fmamk_f32 v33, v33, 0x3a800000, v227
	v_mul_f32_e32 v34, 0x4f800000, v33
	v_cmp_gt_f32_e32 vcc, s47, v33
	v_mul_f32_e32 v32, 0x3a800000, v32
	s_nop 0
	v_cndmask_b32_e32 v33, v33, v34, vcc
	v_sqrt_f32_e32 v34, v33
	s_nop 0
	v_add_u32_e32 v35, -1, v34
	v_fma_f32 v37, -v35, v34, v33
	v_add_u32_e32 v36, 1, v34
	v_cmp_ge_f32_e64 s[8:9], 0, v37
	s_nop 1
	v_cndmask_b32_e64 v35, v34, v35, s[8:9]
	v_fma_f32 v34, -v36, v34, v33
	v_cmp_lt_f32_e64 s[8:9], 0, v34
	s_nop 1
	v_cndmask_b32_e64 v34, v35, v36, s[8:9]
	v_mul_f32_e32 v35, 0x37800000, v34
	v_cndmask_b32_e32 v34, v34, v35, vcc
	v_cmp_class_f32_e32 vcc, v33, v228
	s_nop 1
	v_cndmask_b32_e32 v33, v34, v33, vcc
	v_div_scale_f32 v34, s[8:9], v33, v33, 1.0
	v_rcp_f32_e32 v35, v34
	s_lshl_b32 s8, s19, 2
	s_add_i32 s8, s8, 0
	s_add_i32 s9, s8, 0x1100c
	v_fma_f32 v36, -v34, v35, 1.0
	v_fmac_f32_e32 v35, v36, v35
	v_div_scale_f32 v36, vcc, 1.0, v33, 1.0
	v_mul_f32_e32 v37, v36, v35
	v_fma_f32 v38, -v34, v37, v36
	v_fmac_f32_e32 v37, v38, v35
	v_fma_f32 v34, -v34, v37, v36
	v_div_fmas_f32 v34, v34, v35, v37
	v_div_fixup_f32 v33, v34, v33, 1.0
	v_mov_b32_e32 v34, s9
	s_add_i32 s8, s8, 0x1120c
	ds_write_b32 v34, v32
	v_mov_b32_e32 v32, s8
	ds_write_b32 v32, v33
; __device__ __forceinline__ float bf_lo(unsigned u) { return __uint_as_float(u << 16); }
; __device__ __forceinline__ float bf_hi(unsigned u) { return __uint_as_float(u & 0xffff0000u); }
; __device__ __forceinline__ float wave_sum(float v) {
; #pragma unroll
;     for (int o = 1; o < 64; o <<= 1) v += __shfl_xor(v, o);
;     return v;
; __device__ __forceinline__ void sgu_pool_chunk(KArgs A, int l, int chunk, LAS unsigned char* lds) {
;     ...
;         for (int i = 0; i < 8; ++i) {
;             float f[16] = {bf_lo(x0[i].x), bf_hi(x0[i].x), bf_lo(x0[i].y), bf_hi(x0[i].y), bf_lo(x0[i].z), bf_hi(x0[i].z), bf_lo(x0[i].w), bf_hi(x0[i].w),
;                            bf_lo(x1[i].x), bf_hi(x1[i].x), bf_lo(x1[i].y), bf_hi(x1[i].y), bf_lo(x1[i].z), bf_hi(x1[i].z), bf_lo(x1[i].w), bf_hi(x1[i].w)};
;             float s = 0.f;
; #pragma unroll
;             for (int j = 0; j < 16; ++j) s += f[j];
;             const float mean = wave_sum(s) * (1.f / D_); float s2 = 0.f;
; #pragma unroll
;             for (int j = 0; j < 16; ++j) { const float d = f[j] - mean; s2 += d * d; }
;             const float rstd = 1.f / sqrtf(wave_sum(s2) * (1.f / D_) + LN_EPS_);
;             if (lane == 0) { st_mean[w * 16 + i0 + i] = mean; st_rstd[w * 16 + i0 + i] = rstd; }
.LBB0_338:
	s_or_b64 exec, exec, s[0:1]
	s_waitcnt vmcnt(7)
	v_lshlrev_b32_e32 v32, 16, v28
	v_and_b32_e32 v28, 0xffff0000, v28
	s_waitcnt vmcnt(6)
	v_lshlrev_b32_e32 v36, 16, v24
	v_and_b32_e32 v37, 0xffff0000, v24
	v_add_f32_e32 v24, 0, v32
	v_lshlrev_b32_e32 v33, 16, v29
	v_add_f32_e32 v24, v24, v28
	v_and_b32_e32 v29, 0xffff0000, v29
	v_add_f32_e32 v24, v24, v33
	s_waitcnt lgkmcnt(0)
	v_lshlrev_b32_e32 v34, 16, v30
	v_add_f32_e32 v24, v24, v29
	v_and_b32_e32 v30, 0xffff0000, v30
	v_add_f32_e32 v24, v24, v34
	v_lshlrev_b32_e32 v35, 16, v31
	v_add_f32_e32 v24, v24, v30
	v_and_b32_e32 v31, 0xffff0000, v31
	v_add_f32_e32 v24, v24, v35
	v_add_f32_e32 v24, v24, v31
	v_add_f32_e32 v24, v24, v36
	v_lshlrev_b32_e32 v38, 16, v25
	v_add_f32_e32 v24, v24, v37
	v_and_b32_e32 v25, 0xffff0000, v25
	v_add_f32_e32 v24, v24, v38
	v_lshlrev_b32_e32 v39, 16, v26
	v_add_f32_e32 v24, v24, v25
	v_and_b32_e32 v26, 0xffff0000, v26
	v_add_f32_e32 v24, v24, v39
	v_lshlrev_b32_e32 v40, 16, v27
	v_add_f32_e32 v24, v24, v26
	v_and_b32_e32 v27, 0xffff0000, v27
	v_add_f32_e32 v24, v24, v40
	v_add_f32_e32 v24, v24, v27
	s_waitcnt lgkmcnt(0)
	s_nop 1
	v_add_f32_dpp v24, v24, v24 quad_perm:[1,0,3,2] row_mask:0xf bank_mask:0xf
	s_waitcnt lgkmcnt(0)
	s_nop 1
	v_add_f32_dpp v24, v24, v24 quad_perm:[2,3,0,1] row_mask:0xf bank_mask:0xf
	s_waitcnt lgkmcnt(0)
	s_nop 1
	v_add_f32_dpp v24, v24, v24 row_half_mirror row_mask:0xf bank_mask:0xf
	s_waitcnt lgkmcnt(0)
	s_nop 1
	v_add_f32_dpp v24, v24, v24 row_mirror row_mask:0xf bank_mask:0xf
	s_waitcnt lgkmcnt(0)
	v_mov_b32_e32 v41, v24
	s_nop 1
	v_permlane16_swap_b32 v24, v41
	v_add_f32_e32 v24, v24, v41
	s_waitcnt lgkmcnt(0)
	v_mov_b32_e32 v41, v24
	s_nop 1
	v_permlane32_swap_b32 v24, v41
	v_add_f32_e32 v24, v24, v41
	v_fmac_f32_e32 v28, 0xba800000, v24
	v_fmac_f32_e32 v32, 0xba800000, v24
	v_mul_f32_e32 v28, v28, v28
	v_fmac_f32_e32 v33, 0xba800000, v24
	v_fmac_f32_e32 v28, v32, v32
	v_fmac_f32_e32 v29, 0xba800000, v24
	v_fmac_f32_e32 v28, v33, v33
	v_fmac_f32_e32 v34, 0xba800000, v24
	v_fmac_f32_e32 v28, v29, v29
	v_fmac_f32_e32 v30, 0xba800000, v24
	v_fmac_f32_e32 v28, v34, v34
	v_fmac_f32_e32 v35, 0xba800000, v24
	v_fmac_f32_e32 v28, v30, v30
	v_fmac_f32_e32 v31, 0xba800000, v24
	v_fmac_f32_e32 v28, v35, v35
	v_fmac_f32_e32 v36, 0xba800000, v24
	v_fmac_f32_e32 v28, v31, v31
	v_fmac_f32_e32 v37, 0xba800000, v24
	v_fmac_f32_e32 v28, v36, v36
	v_fmac_f32_e32 v28, v37, v37
	v_fmac_f32_e32 v38, 0xba800000, v24
	v_fmac_f32_e32 v28, v38, v38
	v_fmac_f32_e32 v25, 0xba800000, v24
	v_fmac_f32_e32 v28, v25, v25
	v_fmac_f32_e32 v39, 0xba800000, v24
	v_fmac_f32_e32 v28, v39, v39
	v_fmac_f32_e32 v26, 0xba800000, v24
	v_fmac_f32_e32 v28, v26, v26
	v_fmac_f32_e32 v40, 0xba800000, v24
	v_fmac_f32_e32 v28, v40, v40
	v_fmac_f32_e32 v27, 0xba800000, v24
	v_fmac_f32_e32 v28, v27, v27
	s_waitcnt lgkmcnt(0)
	s_nop 1
	v_add_f32_dpp v25, v28, v28 quad_perm:[1,0,3,2] row_mask:0xf bank_mask:0xf
	s_waitcnt lgkmcnt(0)
	s_nop 1
	v_add_f32_dpp v25, v25, v25 quad_perm:[2,3,0,1] row_mask:0xf bank_mask:0xf
	s_waitcnt lgkmcnt(0)
	s_nop 1
	v_add_f32_dpp v25, v25, v25 row_half_mirror row_mask:0xf bank_mask:0xf
	s_waitcnt lgkmcnt(0)
	s_nop 1
	v_add_f32_dpp v25, v25, v25 row_mirror row_mask:0xf bank_mask:0xf
	s_waitcnt lgkmcnt(0)
	v_mov_b32_e32 v26, v25
	s_nop 1
	v_permlane16_swap_b32 v25, v26
	v_add_f32_e32 v25, v25, v26
	ds_bpermute_b32 v26, v73, v25
	s_and_saveexec_b64 s[0:1], s[6:7]
	s_cbranch_execz .LBB0_340
	s_waitcnt lgkmcnt(0)
	v_add_f32_e32 v25, v25, v26
	v_fmamk_f32 v25, v25, 0x3a800000, v227
	v_mul_f32_e32 v26, 0x4f800000, v25
	v_cmp_gt_f32_e32 vcc, s47, v25
	v_mul_f32_e32 v24, 0x3a800000, v24
	s_nop 0
	v_cndmask_b32_e32 v25, v25, v26, vcc
	v_sqrt_f32_e32 v26, v25
	s_nop 0
	v_add_u32_e32 v27, -1, v26
	v_fma_f32 v29, -v27, v26, v25
	v_add_u32_e32 v28, 1, v26
	v_cmp_ge_f32_e64 s[8:9], 0, v29
	s_nop 1
	v_cndmask_b32_e64 v27, v26, v27, s[8:9]
	v_fma_f32 v26, -v28, v26, v25
	v_cmp_lt_f32_e64 s[8:9], 0, v26
	s_nop 1
	v_cndmask_b32_e64 v26, v27, v28, s[8:9]
	v_mul_f32_e32 v27, 0x37800000, v26
	v_cndmask_b32_e32 v26, v26, v27, vcc
	v_cmp_class_f32_e32 vcc, v25, v228
	s_nop 1
	v_cndmask_b32_e32 v25, v26, v25, vcc
	v_div_scale_f32 v26, s[8:9], v25, v25, 1.0
	v_rcp_f32_e32 v27, v26
	s_lshl_b32 s8, s19, 2
	s_add_i32 s8, s8, 0
	s_add_i32 s9, s8, 0x11010
	v_fma_f32 v28, -v26, v27, 1.0
	v_fmac_f32_e32 v27, v28, v27
	v_div_scale_f32 v28, vcc, 1.0, v25, 1.0
	v_mul_f32_e32 v29, v28, v27
	v_fma_f32 v30, -v26, v29, v28
	v_fmac_f32_e32 v29, v30, v27
	v_fma_f32 v26, -v26, v29, v28
	v_div_fmas_f32 v26, v26, v27, v29
	v_div_fixup_f32 v25, v26, v25, 1.0
	v_mov_b32_e32 v26, s9
	s_add_i32 s8, s8, 0x11210
	ds_write_b32 v26, v24
	v_mov_b32_e32 v24, s8
	ds_write_b32 v24, v25
; __device__ __forceinline__ float bf_lo(unsigned u) { return __uint_as_float(u << 16); }
; __device__ __forceinline__ float bf_hi(unsigned u) { return __uint_as_float(u & 0xffff0000u); }
; __device__ __forceinline__ float wave_sum(float v) {
; #pragma unroll
;     for (int o = 1; o < 64; o <<= 1) v += __shfl_xor(v, o);
;     return v;
; __device__ __forceinline__ void sgu_pool_chunk(KArgs A, int l, int chunk, LAS unsigned char* lds) {
;     ...
;         for (int i = 0; i < 8; ++i) {
;             float f[16] = {bf_lo(x0[i].x), bf_hi(x0[i].x), bf_lo(x0[i].y), bf_hi(x0[i].y), bf_lo(x0[i].z), bf_hi(x0[i].z), bf_lo(x0[i].w), bf_hi(x0[i].w),
;                            bf_lo(x1[i].x), bf_hi(x1[i].x), bf_lo(x1[i].y), bf_hi(x1[i].y), bf_lo(x1[i].z), bf_hi(x1[i].z), bf_lo(x1[i].w), bf_hi(x1[i].w)};
;             float s = 0.f;
; #pragma unroll
;             for (int j = 0; j < 16; ++j) s += f[j];
;             const float mean = wave_sum(s) * (1.f / D_); float s2 = 0.f;
; #pragma unroll
;             for (int j = 0; j < 16; ++j) { const float d = f[j] - mean; s2 += d * d; }
;             const float rstd = 1.f / sqrtf(wave_sum(s2) * (1.f / D_) + LN_EPS_);
;             if (lane == 0) { st_mean[w * 16 + i0 + i] = mean; st_rstd[w * 16 + i0 + i] = rstd; }
.LBB0_340:
	s_or_b64 exec, exec, s[0:1]
	s_waitcnt vmcnt(5)
	v_lshlrev_b32_e32 v24, 16, v20
	v_and_b32_e32 v20, 0xffff0000, v20
	s_waitcnt vmcnt(4)
	v_lshlrev_b32_e32 v28, 16, v16
	v_and_b32_e32 v29, 0xffff0000, v16
	v_add_f32_e32 v16, 0, v24
	v_lshlrev_b32_e32 v25, 16, v21
	v_add_f32_e32 v16, v16, v20
	v_and_b32_e32 v21, 0xffff0000, v21
	v_add_f32_e32 v16, v16, v25
	s_waitcnt lgkmcnt(0)
	v_lshlrev_b32_e32 v26, 16, v22
	v_add_f32_e32 v16, v16, v21
	v_and_b32_e32 v22, 0xffff0000, v22
	v_add_f32_e32 v16, v16, v26
	v_lshlrev_b32_e32 v27, 16, v23
	v_add_f32_e32 v16, v16, v22
	v_and_b32_e32 v23, 0xffff0000, v23
	v_add_f32_e32 v16, v16, v27
	v_add_f32_e32 v16, v16, v23
	v_add_f32_e32 v16, v16, v28
	v_lshlrev_b32_e32 v30, 16, v17
	v_add_f32_e32 v16, v16, v29
	v_and_b32_e32 v17, 0xffff0000, v17
	v_add_f32_e32 v16, v16, v30
	v_lshlrev_b32_e32 v31, 16, v18
	v_add_f32_e32 v16, v16, v17
	v_and_b32_e32 v18, 0xffff0000, v18
	v_add_f32_e32 v16, v16, v31
	v_lshlrev_b32_e32 v32, 16, v19
	v_add_f32_e32 v16, v16, v18
	v_and_b32_e32 v19, 0xffff0000, v19
	v_add_f32_e32 v16, v16, v32
	v_add_f32_e32 v16, v16, v19
	s_waitcnt lgkmcnt(0)
	s_nop 1
	v_add_f32_dpp v16, v16, v16 quad_perm:[1,0,3,2] row_mask:0xf bank_mask:0xf
	s_waitcnt lgkmcnt(0)
	s_nop 1
	v_add_f32_dpp v16, v16, v16 quad_perm:[2,3,0,1] row_mask:0xf bank_mask:0xf
	s_waitcnt lgkmcnt(0)
	s_nop 1
	v_add_f32_dpp v16, v16, v16 row_half_mirror row_mask:0xf bank_mask:0xf
	s_waitcnt lgkmcnt(0)
	s_nop 1
	v_add_f32_dpp v16, v16, v16 row_mirror row_mask:0xf bank_mask:0xf
	s_waitcnt lgkmcnt(0)
	v_mov_b32_e32 v33, v16
	s_nop 1
	v_permlane16_swap_b32 v16, v33
	v_add_f32_e32 v16, v16, v33
	s_waitcnt lgkmcnt(0)
	v_mov_b32_e32 v33, v16
	s_nop 1
	v_permlane32_swap_b32 v16, v33
	v_add_f32_e32 v16, v16, v33
	v_fmac_f32_e32 v20, 0xba800000, v16
	v_fmac_f32_e32 v24, 0xba800000, v16
	v_mul_f32_e32 v20, v20, v20
	v_fmac_f32_e32 v25, 0xba800000, v16
	v_fmac_f32_e32 v20, v24, v24
	v_fmac_f32_e32 v21, 0xba800000, v16
	v_fmac_f32_e32 v20, v25, v25
	v_fmac_f32_e32 v26, 0xba800000, v16
	v_fmac_f32_e32 v20, v21, v21
	v_fmac_f32_e32 v22, 0xba800000, v16
	v_fmac_f32_e32 v20, v26, v26
	v_fmac_f32_e32 v27, 0xba800000, v16
	v_fmac_f32_e32 v20, v22, v22
	v_fmac_f32_e32 v23, 0xba800000, v16
	v_fmac_f32_e32 v20, v27, v27
	v_fmac_f32_e32 v28, 0xba800000, v16
	v_fmac_f32_e32 v20, v23, v23
	v_fmac_f32_e32 v29, 0xba800000, v16
	v_fmac_f32_e32 v20, v28, v28
	v_fmac_f32_e32 v20, v29, v29
	v_fmac_f32_e32 v30, 0xba800000, v16
	v_fmac_f32_e32 v20, v30, v30
	v_fmac_f32_e32 v17, 0xba800000, v16
	v_fmac_f32_e32 v20, v17, v17
	v_fmac_f32_e32 v31, 0xba800000, v16
	v_fmac_f32_e32 v20, v31, v31
	v_fmac_f32_e32 v18, 0xba800000, v16
	v_fmac_f32_e32 v20, v18, v18
	v_fmac_f32_e32 v32, 0xba800000, v16
	v_fmac_f32_e32 v20, v32, v32
	v_fmac_f32_e32 v19, 0xba800000, v16
	v_fmac_f32_e32 v20, v19, v19
	s_waitcnt lgkmcnt(0)
	s_nop 1
	v_add_f32_dpp v17, v20, v20 quad_perm:[1,0,3,2] row_mask:0xf bank_mask:0xf
	s_waitcnt lgkmcnt(0)
	s_nop 1
	v_add_f32_dpp v17, v17, v17 quad_perm:[2,3,0,1] row_mask:0xf bank_mask:0xf
	s_waitcnt lgkmcnt(0)
	s_nop 1
	v_add_f32_dpp v17, v17, v17 row_half_mirror row_mask:0xf bank_mask:0xf
	s_waitcnt lgkmcnt(0)
	s_nop 1
	v_add_f32_dpp v17, v17, v17 row_mirror row_mask:0xf bank_mask:0xf
	s_waitcnt lgkmcnt(0)
	v_mov_b32_e32 v18, v17
	s_nop 1
	v_permlane16_swap_b32 v17, v18
	v_add_f32_e32 v17, v17, v18
	ds_bpermute_b32 v18, v73, v17
	s_and_saveexec_b64 s[0:1], s[6:7]
	s_cbranch_execz .LBB0_342
	s_waitcnt lgkmcnt(0)
	v_add_f32_e32 v17, v17, v18
	v_fmamk_f32 v17, v17, 0x3a800000, v227
	v_mul_f32_e32 v18, 0x4f800000, v17
	v_cmp_gt_f32_e32 vcc, s47, v17
	v_mul_f32_e32 v16, 0x3a800000, v16
	s_nop 0
	v_cndmask_b32_e32 v17, v17, v18, vcc
	v_sqrt_f32_e32 v18, v17
	s_nop 0
	v_add_u32_e32 v19, -1, v18
	v_fma_f32 v21, -v19, v18, v17
	v_add_u32_e32 v20, 1, v18
	v_cmp_ge_f32_e64 s[8:9], 0, v21
	s_nop 1
	v_cndmask_b32_e64 v19, v18, v19, s[8:9]
	v_fma_f32 v18, -v20, v18, v17
	v_cmp_lt_f32_e64 s[8:9], 0, v18
	s_nop 1
	v_cndmask_b32_e64 v18, v19, v20, s[8:9]
	v_mul_f32_e32 v19, 0x37800000, v18
	v_cndmask_b32_e32 v18, v18, v19, vcc
	v_cmp_class_f32_e32 vcc, v17, v228
	s_nop 1
	v_cndmask_b32_e32 v17, v18, v17, vcc
	v_div_scale_f32 v18, s[8:9], v17, v17, 1.0
	v_rcp_f32_e32 v19, v18
	s_lshl_b32 s8, s19, 2
	s_add_i32 s8, s8, 0
	s_add_i32 s9, s8, 0x11014
	v_fma_f32 v20, -v18, v19, 1.0
	v_fmac_f32_e32 v19, v20, v19
	v_div_scale_f32 v20, vcc, 1.0, v17, 1.0
	v_mul_f32_e32 v21, v20, v19
	v_fma_f32 v22, -v18, v21, v20
	v_fmac_f32_e32 v21, v22, v19
	v_fma_f32 v18, -v18, v21, v20
	v_div_fmas_f32 v18, v18, v19, v21
	v_div_fixup_f32 v17, v18, v17, 1.0
	v_mov_b32_e32 v18, s9
	s_add_i32 s8, s8, 0x11214
	ds_write_b32 v18, v16
	v_mov_b32_e32 v16, s8
	ds_write_b32 v16, v17
; __device__ __forceinline__ float bf_lo(unsigned u) { return __uint_as_float(u << 16); }
; __device__ __forceinline__ float bf_hi(unsigned u) { return __uint_as_float(u & 0xffff0000u); }
; __device__ __forceinline__ float wave_sum(float v) {
; #pragma unroll
;     for (int o = 1; o < 64; o <<= 1) v += __shfl_xor(v, o);
;     return v;
; __device__ __forceinline__ void sgu_pool_chunk(KArgs A, int l, int chunk, LAS unsigned char* lds) {
;     ...
;         for (int i = 0; i < 8; ++i) {
;             float f[16] = {bf_lo(x0[i].x), bf_hi(x0[i].x), bf_lo(x0[i].y), bf_hi(x0[i].y), bf_lo(x0[i].z), bf_hi(x0[i].z), bf_lo(x0[i].w), bf_hi(x0[i].w),
;                            bf_lo(x1[i].x), bf_hi(x1[i].x), bf_lo(x1[i].y), bf_hi(x1[i].y), bf_lo(x1[i].z), bf_hi(x1[i].z), bf_lo(x1[i].w), bf_hi(x1[i].w)};
;             float s = 0.f;
; #pragma unroll
;             for (int j = 0; j < 16; ++j) s += f[j];
;             const float mean = wave_sum(s) * (1.f / D_); float s2 = 0.f;
; #pragma unroll
;             for (int j = 0; j < 16; ++j) { const float d = f[j] - mean; s2 += d * d; }
;             const float rstd = 1.f / sqrtf(wave_sum(s2) * (1.f / D_) + LN_EPS_);
;             if (lane == 0) { st_mean[w * 16 + i0 + i] = mean; st_rstd[w * 16 + i0 + i] = rstd; }
.LBB0_342:
	s_or_b64 exec, exec, s[0:1]
	s_waitcnt vmcnt(3)
	v_lshlrev_b32_e32 v16, 16, v12
	v_and_b32_e32 v12, 0xffff0000, v12
	s_waitcnt vmcnt(2)
	v_lshlrev_b32_e32 v20, 16, v8
	v_and_b32_e32 v21, 0xffff0000, v8
	v_add_f32_e32 v8, 0, v16
	v_lshlrev_b32_e32 v17, 16, v13
	v_add_f32_e32 v8, v8, v12
	v_and_b32_e32 v13, 0xffff0000, v13
	v_add_f32_e32 v8, v8, v17
	s_waitcnt lgkmcnt(0)
	v_lshlrev_b32_e32 v18, 16, v14
	v_add_f32_e32 v8, v8, v13
	v_and_b32_e32 v14, 0xffff0000, v14
	v_add_f32_e32 v8, v8, v18
	v_lshlrev_b32_e32 v19, 16, v15
	v_add_f32_e32 v8, v8, v14
	v_and_b32_e32 v15, 0xffff0000, v15
	v_add_f32_e32 v8, v8, v19
	v_add_f32_e32 v8, v8, v15
	v_add_f32_e32 v8, v8, v20
	v_lshlrev_b32_e32 v22, 16, v9
	v_add_f32_e32 v8, v8, v21
	v_and_b32_e32 v9, 0xffff0000, v9
	v_add_f32_e32 v8, v8, v22
	v_lshlrev_b32_e32 v23, 16, v10
	v_add_f32_e32 v8, v8, v9
	v_and_b32_e32 v10, 0xffff0000, v10
	v_add_f32_e32 v8, v8, v23
	v_lshlrev_b32_e32 v24, 16, v11
	v_add_f32_e32 v8, v8, v10
	v_and_b32_e32 v11, 0xffff0000, v11
	v_add_f32_e32 v8, v8, v24
	v_add_f32_e32 v8, v8, v11
	s_waitcnt lgkmcnt(0)
	s_nop 1
	v_add_f32_dpp v8, v8, v8 quad_perm:[1,0,3,2] row_mask:0xf bank_mask:0xf
	s_waitcnt lgkmcnt(0)
	s_nop 1
	v_add_f32_dpp v8, v8, v8 quad_perm:[2,3,0,1] row_mask:0xf bank_mask:0xf
	s_waitcnt lgkmcnt(0)
	s_nop 1
	v_add_f32_dpp v8, v8, v8 row_half_mirror row_mask:0xf bank_mask:0xf
	s_waitcnt lgkmcnt(0)
	s_nop 1
	v_add_f32_dpp v8, v8, v8 row_mirror row_mask:0xf bank_mask:0xf
	s_waitcnt lgkmcnt(0)
	v_mov_b32_e32 v25, v8
	s_nop 1
	v_permlane16_swap_b32 v8, v25
	v_add_f32_e32 v8, v8, v25
	s_waitcnt lgkmcnt(0)
	v_mov_b32_e32 v25, v8
	s_nop 1
	v_permlane32_swap_b32 v8, v25
	v_add_f32_e32 v8, v8, v25
	v_fmac_f32_e32 v12, 0xba800000, v8
	v_fmac_f32_e32 v16, 0xba800000, v8
	v_mul_f32_e32 v12, v12, v12
	v_fmac_f32_e32 v17, 0xba800000, v8
	v_fmac_f32_e32 v12, v16, v16
	v_fmac_f32_e32 v13, 0xba800000, v8
	v_fmac_f32_e32 v12, v17, v17
	v_fmac_f32_e32 v18, 0xba800000, v8
	v_fmac_f32_e32 v12, v13, v13
	v_fmac_f32_e32 v14, 0xba800000, v8
	v_fmac_f32_e32 v12, v18, v18
	v_fmac_f32_e32 v19, 0xba800000, v8
	v_fmac_f32_e32 v12, v14, v14
	v_fmac_f32_e32 v15, 0xba800000, v8
	v_fmac_f32_e32 v12, v19, v19
	v_fmac_f32_e32 v20, 0xba800000, v8
	v_fmac_f32_e32 v12, v15, v15
	v_fmac_f32_e32 v21, 0xba800000, v8
	v_fmac_f32_e32 v12, v20, v20
	v_fmac_f32_e32 v12, v21, v21
	v_fmac_f32_e32 v22, 0xba800000, v8
	v_fmac_f32_e32 v12, v22, v22
	v_fmac_f32_e32 v9, 0xba800000, v8
	v_fmac_f32_e32 v12, v9, v9
	v_fmac_f32_e32 v23, 0xba800000, v8
	v_fmac_f32_e32 v12, v23, v23
	v_fmac_f32_e32 v10, 0xba800000, v8
	v_fmac_f32_e32 v12, v10, v10
	v_fmac_f32_e32 v24, 0xba800000, v8
	v_fmac_f32_e32 v12, v24, v24
	v_fmac_f32_e32 v11, 0xba800000, v8
	v_fmac_f32_e32 v12, v11, v11
	s_waitcnt lgkmcnt(0)
	s_nop 1
	v_add_f32_dpp v9, v12, v12 quad_perm:[1,0,3,2] row_mask:0xf bank_mask:0xf
	s_waitcnt lgkmcnt(0)
	s_nop 1
	v_add_f32_dpp v9, v9, v9 quad_perm:[2,3,0,1] row_mask:0xf bank_mask:0xf
	s_waitcnt lgkmcnt(0)
	s_nop 1
	v_add_f32_dpp v9, v9, v9 row_half_mirror row_mask:0xf bank_mask:0xf
	s_waitcnt lgkmcnt(0)
	s_nop 1
	v_add_f32_dpp v9, v9, v9 row_mirror row_mask:0xf bank_mask:0xf
	s_waitcnt lgkmcnt(0)
	v_mov_b32_e32 v10, v9
	s_nop 1
	v_permlane16_swap_b32 v9, v10
	v_add_f32_e32 v9, v9, v10
	ds_bpermute_b32 v10, v73, v9
	s_and_saveexec_b64 s[0:1], s[6:7]
	s_cbranch_execz .LBB0_344
	s_waitcnt lgkmcnt(0)
	v_add_f32_e32 v9, v9, v10
	v_fmamk_f32 v9, v9, 0x3a800000, v227
	v_mul_f32_e32 v10, 0x4f800000, v9
	v_cmp_gt_f32_e32 vcc, s47, v9
	v_mul_f32_e32 v8, 0x3a800000, v8
	s_nop 0
	v_cndmask_b32_e32 v9, v9, v10, vcc
	v_sqrt_f32_e32 v10, v9
	s_nop 0
	v_add_u32_e32 v11, -1, v10
	v_fma_f32 v13, -v11, v10, v9
	v_add_u32_e32 v12, 1, v10
	v_cmp_ge_f32_e64 s[8:9], 0, v13
	s_nop 1
	v_cndmask_b32_e64 v11, v10, v11, s[8:9]
	v_fma_f32 v10, -v12, v10, v9
	v_cmp_lt_f32_e64 s[8:9], 0, v10
	s_nop 1
	v_cndmask_b32_e64 v10, v11, v12, s[8:9]
	v_mul_f32_e32 v11, 0x37800000, v10
	v_cndmask_b32_e32 v10, v10, v11, vcc
	v_cmp_class_f32_e32 vcc, v9, v228
	s_nop 1
	v_cndmask_b32_e32 v9, v10, v9, vcc
	v_div_scale_f32 v10, s[8:9], v9, v9, 1.0
	v_rcp_f32_e32 v11, v10
	s_lshl_b32 s8, s19, 2
	s_add_i32 s8, s8, 0
	s_add_i32 s9, s8, 0x11018
	v_fma_f32 v12, -v10, v11, 1.0
	v_fmac_f32_e32 v11, v12, v11
	v_div_scale_f32 v12, vcc, 1.0, v9, 1.0
	v_mul_f32_e32 v13, v12, v11
	v_fma_f32 v14, -v10, v13, v12
	v_fmac_f32_e32 v13, v14, v11
	v_fma_f32 v10, -v10, v13, v12
	v_div_fmas_f32 v10, v10, v11, v13
	v_div_fixup_f32 v9, v10, v9, 1.0
	v_mov_b32_e32 v10, s9
	s_add_i32 s8, s8, 0x11218
	ds_write_b32 v10, v8
	v_mov_b32_e32 v8, s8
	ds_write_b32 v8, v9
; __device__ __forceinline__ float bf_lo(unsigned u) { return __uint_as_float(u << 16); }
; __device__ __forceinline__ float bf_hi(unsigned u) { return __uint_as_float(u & 0xffff0000u); }
; __device__ __forceinline__ float wave_sum(float v) {
; #pragma unroll
;     for (int o = 1; o < 64; o <<= 1) v += __shfl_xor(v, o);
;     return v;
; __device__ __forceinline__ void sgu_pool_chunk(KArgs A, int l, int chunk, LAS unsigned char* lds) {
;     ...
;         for (int i = 0; i < 8; ++i) {
;             float f[16] = {bf_lo(x0[i].x), bf_hi(x0[i].x), bf_lo(x0[i].y), bf_hi(x0[i].y), bf_lo(x0[i].z), bf_hi(x0[i].z), bf_lo(x0[i].w), bf_hi(x0[i].w),
;                            bf_lo(x1[i].x), bf_hi(x1[i].x), bf_lo(x1[i].y), bf_hi(x1[i].y), bf_lo(x1[i].z), bf_hi(x1[i].z), bf_lo(x1[i].w), bf_hi(x1[i].w)};
;             float s = 0.f;
; #pragma unroll
;             for (int j = 0; j < 16; ++j) s += f[j];
;             const float mean = wave_sum(s) * (1.f / D_); float s2 = 0.f;
; #pragma unroll
;             for (int j = 0; j < 16; ++j) { const float d = f[j] - mean; s2 += d * d; }
;             const float rstd = 1.f / sqrtf(wave_sum(s2) * (1.f / D_) + LN_EPS_);
;             if (lane == 0) { st_mean[w * 16 + i0 + i] = mean; st_rstd[w * 16 + i0 + i] = rstd; }
.LBB0_344:
	s_or_b64 exec, exec, s[0:1]
	s_waitcnt vmcnt(1)
	v_lshlrev_b32_e32 v8, 16, v4
	v_and_b32_e32 v4, 0xffff0000, v4
	s_waitcnt vmcnt(0)
	v_lshlrev_b32_e32 v12, 16, v0
	v_and_b32_e32 v13, 0xffff0000, v0
	v_add_f32_e32 v0, 0, v8
	v_lshlrev_b32_e32 v9, 16, v5
	v_add_f32_e32 v0, v0, v4
	v_and_b32_e32 v5, 0xffff0000, v5
	v_add_f32_e32 v0, v0, v9
	s_waitcnt lgkmcnt(0)
	v_lshlrev_b32_e32 v10, 16, v6
	v_add_f32_e32 v0, v0, v5
	v_and_b32_e32 v6, 0xffff0000, v6
	v_add_f32_e32 v0, v0, v10
	v_lshlrev_b32_e32 v11, 16, v7
	v_add_f32_e32 v0, v0, v6
	v_and_b32_e32 v7, 0xffff0000, v7
	v_add_f32_e32 v0, v0, v11
	v_add_f32_e32 v0, v0, v7
	v_add_f32_e32 v0, v0, v12
	v_lshlrev_b32_e32 v14, 16, v1
	v_add_f32_e32 v0, v0, v13
	v_and_b32_e32 v1, 0xffff0000, v1
	v_add_f32_e32 v0, v0, v14
	v_lshlrev_b32_e32 v15, 16, v2
	v_add_f32_e32 v0, v0, v1
	v_and_b32_e32 v2, 0xffff0000, v2
	v_add_f32_e32 v0, v0, v15
	v_lshlrev_b32_e32 v16, 16, v3
	v_add_f32_e32 v0, v0, v2
	v_and_b32_e32 v3, 0xffff0000, v3
	v_add_f32_e32 v0, v0, v16
	v_add_f32_e32 v0, v0, v3
	s_waitcnt lgkmcnt(0)
	s_nop 1
	v_add_f32_dpp v0, v0, v0 quad_perm:[1,0,3,2] row_mask:0xf bank_mask:0xf
	s_waitcnt lgkmcnt(0)
	s_nop 1
	v_add_f32_dpp v0, v0, v0 quad_perm:[2,3,0,1] row_mask:0xf bank_mask:0xf
	s_waitcnt lgkmcnt(0)
	s_nop 1
	v_add_f32_dpp v0, v0, v0 row_half_mirror row_mask:0xf bank_mask:0xf
	s_waitcnt lgkmcnt(0)
	s_nop 1
	v_add_f32_dpp v0, v0, v0 row_mirror row_mask:0xf bank_mask:0xf
	s_waitcnt lgkmcnt(0)
	v_mov_b32_e32 v17, v0
	s_nop 1
	v_permlane16_swap_b32 v0, v17
	v_add_f32_e32 v0, v0, v17
	s_waitcnt lgkmcnt(0)
	v_mov_b32_e32 v17, v0
	s_nop 1
	v_permlane32_swap_b32 v0, v17
	v_add_f32_e32 v0, v0, v17
	v_fmac_f32_e32 v4, 0xba800000, v0
	v_fmac_f32_e32 v8, 0xba800000, v0
	v_mul_f32_e32 v4, v4, v4
	v_fmac_f32_e32 v9, 0xba800000, v0
	v_fmac_f32_e32 v4, v8, v8
	v_fmac_f32_e32 v5, 0xba800000, v0
	v_fmac_f32_e32 v4, v9, v9
	v_fmac_f32_e32 v10, 0xba800000, v0
	v_fmac_f32_e32 v4, v5, v5
	v_fmac_f32_e32 v6, 0xba800000, v0
	v_fmac_f32_e32 v4, v10, v10
	v_fmac_f32_e32 v11, 0xba800000, v0
	v_fmac_f32_e32 v4, v6, v6
	v_fmac_f32_e32 v7, 0xba800000, v0
	v_fmac_f32_e32 v4, v11, v11
	v_fmac_f32_e32 v12, 0xba800000, v0
	v_fmac_f32_e32 v4, v7, v7
	v_fmac_f32_e32 v13, 0xba800000, v0
	v_fmac_f32_e32 v4, v12, v12
	v_fmac_f32_e32 v4, v13, v13
	v_fmac_f32_e32 v14, 0xba800000, v0
	v_fmac_f32_e32 v4, v14, v14
	v_fmac_f32_e32 v1, 0xba800000, v0
	v_fmac_f32_e32 v4, v1, v1
	v_fmac_f32_e32 v15, 0xba800000, v0
	v_fmac_f32_e32 v4, v15, v15
	v_fmac_f32_e32 v2, 0xba800000, v0
	v_fmac_f32_e32 v4, v2, v2
	v_fmac_f32_e32 v16, 0xba800000, v0
	v_fmac_f32_e32 v4, v16, v16
	v_fmac_f32_e32 v3, 0xba800000, v0
	v_fmac_f32_e32 v4, v3, v3
	s_waitcnt lgkmcnt(0)
	s_nop 1
	v_add_f32_dpp v1, v4, v4 quad_perm:[1,0,3,2] row_mask:0xf bank_mask:0xf
	s_waitcnt lgkmcnt(0)
	s_nop 1
	v_add_f32_dpp v1, v1, v1 quad_perm:[2,3,0,1] row_mask:0xf bank_mask:0xf
	s_waitcnt lgkmcnt(0)
	s_nop 1
	v_add_f32_dpp v1, v1, v1 row_half_mirror row_mask:0xf bank_mask:0xf
	s_waitcnt lgkmcnt(0)
	s_nop 1
	v_add_f32_dpp v1, v1, v1 row_mirror row_mask:0xf bank_mask:0xf
	s_waitcnt lgkmcnt(0)
	v_mov_b32_e32 v2, v1
	s_nop 1
	v_permlane16_swap_b32 v1, v2
	v_add_f32_e32 v1, v1, v2
	ds_bpermute_b32 v2, v73, v1
	s_and_saveexec_b64 s[0:1], s[6:7]
	s_cbranch_execz .LBB0_329
	s_waitcnt lgkmcnt(0)
	v_add_f32_e32 v1, v1, v2
	v_fmamk_f32 v1, v1, 0x3a800000, v227
	v_mul_f32_e32 v2, 0x4f800000, v1
	v_cmp_gt_f32_e32 vcc, s47, v1
	v_mul_f32_e32 v0, 0x3a800000, v0
	s_nop 0
	v_cndmask_b32_e32 v1, v1, v2, vcc
	v_sqrt_f32_e32 v2, v1
	s_nop 0
	v_add_u32_e32 v3, -1, v2
	v_fma_f32 v5, -v3, v2, v1
	v_add_u32_e32 v4, 1, v2
	v_cmp_ge_f32_e64 s[8:9], 0, v5
	s_nop 1
	v_cndmask_b32_e64 v3, v2, v3, s[8:9]
	v_fma_f32 v2, -v4, v2, v1
	v_cmp_lt_f32_e64 s[8:9], 0, v2
	s_nop 1
	v_cndmask_b32_e64 v2, v3, v4, s[8:9]
	v_mul_f32_e32 v3, 0x37800000, v2
	v_cndmask_b32_e32 v2, v2, v3, vcc
	v_cmp_class_f32_e32 vcc, v1, v228
	s_nop 1
	v_cndmask_b32_e32 v1, v2, v1, vcc
	v_div_scale_f32 v2, s[8:9], v1, v1, 1.0
	v_rcp_f32_e32 v3, v2
	s_lshl_b32 s8, s19, 2
	s_add_i32 s8, s8, 0
	s_add_i32 s9, s8, 0x1101c
	v_fma_f32 v4, -v2, v3, 1.0
	v_fmac_f32_e32 v3, v4, v3
	v_div_scale_f32 v4, vcc, 1.0, v1, 1.0
	v_mul_f32_e32 v5, v4, v3
	v_fma_f32 v6, -v2, v5, v4
	v_fmac_f32_e32 v5, v6, v3
	v_fma_f32 v2, -v2, v5, v4
	v_div_fmas_f32 v2, v2, v3, v5
	v_div_fixup_f32 v1, v2, v1, 1.0
	v_mov_b32_e32 v2, s9
	s_add_i32 s8, s8, 0x1121c
	ds_write_b32 v2, v0
	v_mov_b32_e32 v0, s8
	ds_write_b32 v0, v1
	s_branch .LBB0_329

; __device__ __forceinline__ float bf_lo(unsigned u) { return __uint_as_float(u << 16); }
; __device__ __forceinline__ float bf_hi(unsigned u) { return __uint_as_float(u & 0xffff0000u); }
; __device__ __forceinline__ void ln1_router_tile(KArgs A, int l, int tile, int lane, const LAS bf16_t* wH) {
;     ...
;     for (int r0 = 0; r0 < 16; r0 += 8) {
;         u32x2 hr[8][4], mm[8][4];
; #pragma unroll
;         for (int i = 0; i < 8; ++i) {
; #pragma unroll
;             for (int j = 0; j < 4; ++j) { hr[i][j] = *(const u32x2*)(HB + (size_t)(r0 + i) * D_ + 4 * lane + 256 * j); mm[i][j] = __builtin_nontemporal_load((const u32x2*)(mix + (size_t)(r0 + i) * D_ + 4 * lane + 256 * j)); } }
; #pragma unroll
;         for (int i = 0; i < 8; ++i) { f32x4 hv[4];
; #pragma unroll
;             for (int j = 0; j < 4; ++j) { hv[j].x = bf_lo(hr[i][j].x) * ALPHA_ + bf_lo(mm[i][j].x); hv[j].y = bf_hi(hr[i][j].x) * ALPHA_ + bf_hi(mm[i][j].x); hv[j].z = bf_lo(hr[i][j].y) * ALPHA_ + bf_lo(mm[i][j].y); hv[j].w = bf_hi(hr[i][j].y) * ALPHA_ + bf_hi(mm[i][j].y); }
.LBB0_584:
	s_lshl_b64 s[26:27], s[86:87], 1
	v_lshl_add_u64 v[118:119], v[0:1], 0, s[26:27]
	v_lshl_add_u64 v[10:11], v[2:3], 0, s[26:27]
	global_load_dwordx2 v[150:151], v[118:119], off
	global_load_dwordx2 v[148:149], v[10:11], off nt
	global_load_dwordx2 v[146:147], v[118:119], off offset:512
	global_load_dwordx2 v[144:145], v[10:11], off offset:512 nt
	global_load_dwordx2 v[142:143], v[118:119], off offset:1024
	global_load_dwordx2 v[140:141], v[10:11], off offset:1024 nt
	global_load_dwordx2 v[136:137], v[118:119], off offset:1536
	global_load_dwordx2 v[138:139], v[10:11], off offset:1536 nt
	global_load_dwordx2 v[134:135], v[118:119], off offset:2048
	global_load_dwordx2 v[132:133], v[10:11], off offset:2048 nt
	global_load_dwordx2 v[130:131], v[118:119], off offset:2560
	global_load_dwordx2 v[128:129], v[10:11], off offset:2560 nt
	global_load_dwordx2 v[126:127], v[118:119], off offset:3072
	global_load_dwordx2 v[124:125], v[10:11], off offset:3072 nt
	global_load_dwordx2 v[120:121], v[118:119], off offset:3584
	global_load_dwordx2 v[122:123], v[10:11], off offset:3584 nt
	v_cndmask_b32_e64 v9, 0, 1, s[8:9]
	v_cmp_ne_u32_e64 s[6:7], 1, v9
	s_or_b32 s0, s86, 0x800
	s_mov_b32 s1, s87
	s_lshl_b64 s[20:21], s[0:1], 1
	s_or_b32 s0, s86, 0xc00
	s_lshl_b64 s[18:19], s[0:1], 1
	s_or_b32 s0, s86, 0x1000
	v_lshl_add_u64 v[100:101], v[0:1], 0, s[20:21]
	v_lshl_add_u64 v[10:11], v[2:3], 0, s[20:21]
	s_lshl_b64 s[16:17], s[0:1], 1
	s_or_b32 s0, s86, 0x1400
	global_load_dwordx2 v[116:117], v[100:101], off
	global_load_dwordx2 v[114:115], v[10:11], off nt
	global_load_dwordx2 v[112:113], v[100:101], off offset:512
	global_load_dwordx2 v[110:111], v[10:11], off offset:512 nt
	global_load_dwordx2 v[108:109], v[100:101], off offset:1024
	global_load_dwordx2 v[106:107], v[10:11], off offset:1024 nt
	global_load_dwordx2 v[104:105], v[100:101], off offset:1536
	global_load_dwordx2 v[102:103], v[10:11], off offset:1536 nt
	v_lshl_add_u64 v[82:83], v[0:1], 0, s[18:19]
	v_lshl_add_u64 v[10:11], v[2:3], 0, s[18:19]
	s_lshl_b64 s[8:9], s[0:1], 1
	global_load_dwordx2 v[98:99], v[82:83], off
	global_load_dwordx2 v[96:97], v[10:11], off nt
	global_load_dwordx2 v[94:95], v[82:83], off offset:512
	global_load_dwordx2 v[92:93], v[10:11], off offset:512 nt
	global_load_dwordx2 v[90:91], v[82:83], off offset:1024
	global_load_dwordx2 v[88:89], v[10:11], off offset:1024 nt
	global_load_dwordx2 v[86:87], v[82:83], off offset:1536
	global_load_dwordx2 v[84:85], v[10:11], off offset:1536 nt
	v_lshl_add_u64 v[64:65], v[0:1], 0, s[16:17]
	v_lshl_add_u64 v[10:11], v[2:3], 0, s[16:17]
	global_load_dwordx2 v[80:81], v[64:65], off
	global_load_dwordx2 v[78:79], v[10:11], off nt
	global_load_dwordx2 v[76:77], v[64:65], off offset:512
	global_load_dwordx2 v[74:75], v[10:11], off offset:512 nt
	global_load_dwordx2 v[72:73], v[64:65], off offset:1024
	global_load_dwordx2 v[70:71], v[10:11], off offset:1024 nt
	global_load_dwordx2 v[68:69], v[64:65], off offset:1536
	global_load_dwordx2 v[66:67], v[10:11], off offset:1536 nt
	v_lshl_add_u64 v[46:47], v[0:1], 0, s[8:9]
	v_lshl_add_u64 v[10:11], v[2:3], 0, s[8:9]
	s_or_b32 s0, s86, 0x1800
	s_lshl_b64 s[4:5], s[0:1], 1
	s_or_b32 s86, s86, 0x1c00
	s_lshl_b64 s[0:1], s[86:87], 1
	global_load_dwordx2 v[62:63], v[46:47], off
	global_load_dwordx2 v[60:61], v[10:11], off nt
	global_load_dwordx2 v[58:59], v[46:47], off offset:512
	global_load_dwordx2 v[56:57], v[10:11], off offset:512 nt
	global_load_dwordx2 v[54:55], v[46:47], off offset:1024
	global_load_dwordx2 v[52:53], v[10:11], off offset:1024 nt
	global_load_dwordx2 v[50:51], v[46:47], off offset:1536
	global_load_dwordx2 v[48:49], v[10:11], off offset:1536 nt
	v_lshl_add_u64 v[28:29], v[0:1], 0, s[4:5]
	v_lshl_add_u64 v[10:11], v[2:3], 0, s[4:5]
	global_load_dwordx2 v[44:45], v[28:29], off
	global_load_dwordx2 v[42:43], v[10:11], off nt
	global_load_dwordx2 v[40:41], v[28:29], off offset:512
	global_load_dwordx2 v[38:39], v[10:11], off offset:512 nt
	global_load_dwordx2 v[36:37], v[28:29], off offset:1024
	global_load_dwordx2 v[34:35], v[10:11], off offset:1024 nt
	global_load_dwordx2 v[32:33], v[28:29], off offset:1536
	global_load_dwordx2 v[30:31], v[10:11], off offset:1536 nt
	v_lshl_add_u64 v[10:11], v[0:1], 0, s[0:1]
	v_lshl_add_u64 v[12:13], v[2:3], 0, s[0:1]
	global_load_dwordx2 v[26:27], v[10:11], off
	global_load_dwordx2 v[24:25], v[12:13], off nt
	global_load_dwordx2 v[22:23], v[10:11], off offset:512
	global_load_dwordx2 v[20:21], v[12:13], off offset:512 nt
	global_load_dwordx2 v[18:19], v[10:11], off offset:1024
	global_load_dwordx2 v[16:17], v[12:13], off offset:1024 nt
	global_load_dwordx2 v[14:15], v[10:11], off offset:1536
	s_nop 0
	global_load_dwordx2 v[12:13], v[12:13], off offset:1536 nt
	s_movk_i32 s86, 0x2000
	s_waitcnt vmcnt(62)
	v_lshlrev_b32_e32 v162, 16, v150
	v_and_b32_e32 v163, 0xffff0000, v150
	v_lshlrev_b32_e32 v164, 16, v148
	v_and_b32_e32 v165, 0xffff0000, v148
	v_lshlrev_b32_e32 v150, 16, v151
	v_and_b32_e32 v151, 0xffff0000, v151
	v_lshlrev_b32_e32 v148, 16, v149
	v_and_b32_e32 v149, 0xffff0000, v149
	v_pk_fma_f32 v[162:163], v[162:163], s[78:79], v[164:165] op_sel_hi:[1,0,1]
	v_pk_fma_f32 v[148:149], v[150:151], s[78:79], v[148:149] op_sel_hi:[1,0,1]
	s_waitcnt vmcnt(61)
	v_lshlrev_b32_e32 v150, 16, v146
	v_and_b32_e32 v151, 0xffff0000, v146
	s_waitcnt vmcnt(60)
	v_lshlrev_b32_e32 v164, 16, v144
	v_and_b32_e32 v165, 0xffff0000, v144
	v_lshlrev_b32_e32 v146, 16, v147
	v_and_b32_e32 v147, 0xffff0000, v147
	v_lshlrev_b32_e32 v144, 16, v145
	v_and_b32_e32 v145, 0xffff0000, v145
	v_pk_fma_f32 v[150:151], v[150:151], s[78:79], v[164:165] op_sel_hi:[1,0,1]
	v_pk_fma_f32 v[144:145], v[146:147], s[78:79], v[144:145] op_sel_hi:[1,0,1]
	s_waitcnt vmcnt(59)
; #define LAS __attribute__((address_space(3)))
; __device__ __forceinline__ float wave_sum(float v) {
; #pragma unroll
;     for (int o = 1; o < 64; o <<= 1) v += __shfl_xor(v, o);
;     return v;
; __device__ __forceinline__ void ln_affine_l(f32x4 (&v)[4], const LAS float* gL, const LAS float* bL, int lane) {
;     float s = 0.f;
; #pragma unroll
;     for (int j = 0; j < 4; ++j) s += (v[j].x + v[j].y) + (v[j].z + v[j].w);
;     const float mean = wave_sum(s) * (1.f / D_); float s2 = 0.f;
; #pragma unroll
;     for (int j = 0; j < 4; ++j) { v[j] = v[j] - mean; s2 += (v[j].x * v[j].x + v[j].y * v[j].y) + (v[j].z * v[j].z + v[j].w * v[j].w); }
;     const float rstd = 1.f / sqrtf(wave_sum(s2) * (1.f / D_) + LN_EPS_);
; #pragma unroll
;     for (int j = 0; j < 4; ++j) v[j] = v[j] * rstd * *(const LAS f32x4*)(gL + 4 * lane + 256 * j) + *(const LAS f32x4*)(bL + 4 * lane + 256 * j);
	v_lshlrev_b32_e32 v146, 16, v142
	v_and_b32_e32 v147, 0xffff0000, v142
	s_waitcnt vmcnt(58)
	v_lshlrev_b32_e32 v164, 16, v140
	v_and_b32_e32 v165, 0xffff0000, v140
	v_lshlrev_b32_e32 v142, 16, v143
	v_and_b32_e32 v143, 0xffff0000, v143
	v_lshlrev_b32_e32 v140, 16, v141
	v_and_b32_e32 v141, 0xffff0000, v141
	v_pk_fma_f32 v[146:147], v[146:147], s[78:79], v[164:165] op_sel_hi:[1,0,1]
	v_pk_fma_f32 v[164:165], v[142:143], s[78:79], v[140:141] op_sel_hi:[1,0,1]
	s_waitcnt vmcnt(57)
	v_lshlrev_b32_e32 v140, 16, v136
	v_and_b32_e32 v141, 0xffff0000, v136
	s_waitcnt vmcnt(56)
	v_lshlrev_b32_e32 v142, 16, v138
	v_and_b32_e32 v143, 0xffff0000, v138
	v_lshlrev_b32_e32 v136, 16, v137
	v_and_b32_e32 v137, 0xffff0000, v137
	v_lshlrev_b32_e32 v138, 16, v139
	v_and_b32_e32 v139, 0xffff0000, v139
	v_pk_fma_f32 v[168:169], v[136:137], s[78:79], v[138:139] op_sel_hi:[1,0,1]
	v_mov_b32_e32 v136, v162
	v_mov_b32_e32 v137, v148
	v_mov_b32_e32 v138, v163
	v_mov_b32_e32 v139, v149
	v_pk_fma_f32 v[166:167], v[140:141], s[78:79], v[142:143] op_sel_hi:[1,0,1]
	v_pk_add_f32 v[136:137], v[136:137], v[138:139]
	v_mov_b32_e32 v138, v150
	v_mov_b32_e32 v139, v144
	v_mov_b32_e32 v140, v151
	v_mov_b32_e32 v141, v145
	v_pk_add_f32 v[138:139], v[138:139], v[140:141]
	v_add_f32_e32 v9, v136, v137
	v_pk_add_f32 v[138:139], v[138:139], v[138:139] op_sel:[0,1] op_sel_hi:[1,0]
	v_pk_add_f32 v[140:141], v[146:147], v[146:147] op_sel:[0,1] op_sel_hi:[1,0]
	v_pk_add_f32 v[142:143], v[164:165], v[164:165] op_sel:[0,1] op_sel_hi:[1,0]
	v_add_f32_e32 v136, 0, v9
	v_mov_b32_e32 v137, v166
	v_mov_b32_e32 v139, v167
	v_mov_b32_e32 v141, v168
	v_mov_b32_e32 v143, v169
	v_pk_add_f32 v[136:137], v[136:137], v[138:139]
	v_pk_add_f32 v[138:139], v[140:141], v[142:143]
	s_nop 0
	v_pk_add_f32 v[136:137], v[136:137], v[138:139]
	s_nop 0
	v_add_f32_e32 v9, v136, v137
	s_waitcnt lgkmcnt(0)
	s_nop 1
	v_add_f32_dpp v9, v9, v9 quad_perm:[1,0,3,2] row_mask:0xf bank_mask:0xf
	s_waitcnt lgkmcnt(0)
	s_nop 1
	v_add_f32_dpp v9, v9, v9 quad_perm:[2,3,0,1] row_mask:0xf bank_mask:0xf
	s_waitcnt lgkmcnt(0)
	s_nop 1
	v_add_f32_dpp v9, v9, v9 row_half_mirror row_mask:0xf bank_mask:0xf
	s_waitcnt lgkmcnt(0)
	s_nop 1
	v_add_f32_dpp v9, v9, v9 row_mirror row_mask:0xf bank_mask:0xf
	s_waitcnt lgkmcnt(0)
	v_mov_b32_e32 v136, v9
	s_nop 1
	v_permlane16_swap_b32 v9, v136
	v_add_f32_e32 v9, v9, v136
	s_waitcnt lgkmcnt(0)
	v_mov_b32_e32 v136, v9
	s_nop 1
	v_permlane32_swap_b32 v9, v136
	v_add_f32_e32 v9, v9, v136
	v_fmamk_f32 v163, v9, 0xba800000, v163
	v_fmac_f32_e32 v162, 0xba800000, v9
	v_fmamk_f32 v149, v9, 0xba800000, v149
	v_fmac_f32_e32 v148, 0xba800000, v9
	v_pk_mul_f32 v[136:137], v[148:149], v[148:149]
	v_pk_mul_f32 v[138:139], v[162:163], v[162:163]
	v_fmamk_f32 v151, v9, 0xba800000, v151
	v_pk_mov_b32 v[140:141], v[138:139], v[136:137] op_sel:[1,0]
	v_mov_b32_e32 v139, v137
	v_pk_add_f32 v[136:137], v[140:141], v[138:139]
	v_fmac_f32_e32 v150, 0xba800000, v9
	v_fmamk_f32 v145, v9, 0xba800000, v145
	v_fmac_f32_e32 v144, 0xba800000, v9
	v_pk_add_f32 v[136:137], v[136:137], v[136:137] op_sel_hi:[0,1]
	v_pk_mul_f32 v[138:139], v[144:145], v[144:145]
	v_pk_mul_f32 v[140:141], v[150:151], v[150:151]
	v_fmac_f32_e32 v146, 0xba800000, v9
	v_pk_mov_b32 v[142:143], v[140:141], v[138:139] op_sel:[1,0]
	v_mov_b32_e32 v141, v139
	v_fmamk_f32 v147, v9, 0xba800000, v147
	v_fmac_f32_e32 v164, 0xba800000, v9
	v_mul_f32_e32 v136, v146, v146
	v_pk_add_f32 v[138:139], v[142:143], v[140:141]
	v_fmamk_f32 v165, v9, 0xba800000, v165
	v_pk_fma_f32 v[140:141], v[146:147], v[146:147], v[136:137] op_sel_hi:[1,1,0]
	v_mul_f32_e32 v136, v164, v164
	v_pk_add_f32 v[138:139], v[138:139], v[138:139] op_sel_hi:[0,1]
	v_pk_fma_f32 v[142:143], v[164:165], v[164:165], v[136:137] op_sel_hi:[1,1,0]
	v_fmamk_f32 v169, v9, 0xba800000, v169
	v_fmac_f32_e32 v168, 0xba800000, v9
	v_fmamk_f32 v167, v9, 0xba800000, v167
	v_fmac_f32_e32 v166, 0xba800000, v9
	v_mul_f32_e32 v140, v166, v166
	v_mul_f32_e32 v142, v167, v167
	v_mul_f32_e32 v136, v168, v168
	v_mul_f32_e32 v138, v169, v169
	v_pk_add_f32 v[140:141], v[140:141], v[142:143]
	v_pk_add_f32 v[136:137], v[136:137], v[138:139]
	s_nop 0
	v_pk_add_f32 v[136:137], v[140:141], v[136:137]
	s_nop 0
	v_add_f32_e32 v9, v136, v137
	s_waitcnt lgkmcnt(0)
	s_nop 1
	v_add_f32_dpp v9, v9, v9 quad_perm:[1,0,3,2] row_mask:0xf bank_mask:0xf
	s_waitcnt lgkmcnt(0)
	s_nop 1
	v_add_f32_dpp v9, v9, v9 quad_perm:[2,3,0,1] row_mask:0xf bank_mask:0xf
	s_waitcnt lgkmcnt(0)
	s_nop 1
	v_add_f32_dpp v9, v9, v9 row_half_mirror row_mask:0xf bank_mask:0xf
	s_waitcnt lgkmcnt(0)
	s_nop 1
	v_add_f32_dpp v9, v9, v9 row_mirror row_mask:0xf bank_mask:0xf
	s_waitcnt lgkmcnt(0)
	v_mov_b32_e32 v136, v9
	s_nop 1
	v_permlane16_swap_b32 v9, v136
	v_add_f32_e32 v9, v9, v136
	s_waitcnt lgkmcnt(0)
	v_mov_b32_e32 v136, v9
	s_nop 1
	v_permlane32_swap_b32 v9, v136
	v_add_f32_e32 v9, v9, v136
	v_fmamk_f32 v9, v9, 0x3a800000, v227
	v_cmp_gt_f32_e32 vcc, s47, v9
	v_mul_f32_e32 v136, 0x4f800000, v9
	s_nop 0
	v_cndmask_b32_e32 v9, v9, v136, vcc
	v_sqrt_f32_e32 v136, v9
	s_nop 0
	v_add_u32_e32 v137, -1, v136
	v_fma_f32 v138, -v137, v136, v9
	v_cmp_ge_f32_e64 s[8:9], 0, v138
	v_add_u32_e32 v138, 1, v136
	s_nop 0
	v_cndmask_b32_e64 v137, v136, v137, s[8:9]
	v_fma_f32 v136, -v138, v136, v9
	v_cmp_lt_f32_e64 s[8:9], 0, v136
	s_nop 1
	v_cndmask_b32_e64 v136, v137, v138, s[8:9]
	v_mul_f32_e32 v137, 0x37800000, v136
	v_cndmask_b32_e32 v136, v136, v137, vcc
	v_cmp_class_f32_e32 vcc, v9, v228
	s_nop 1
	v_cndmask_b32_e32 v9, v136, v9, vcc
	v_div_scale_f32 v136, s[0:1], v9, v9, 1.0
	v_rcp_f32_e32 v137, v136
	s_nop 0
	v_fma_f32 v138, -v136, v137, 1.0
	v_fmac_f32_e32 v137, v138, v137
	v_div_scale_f32 v138, vcc, 1.0, v9, 1.0
	v_mul_f32_e32 v139, v138, v137
	v_fma_f32 v140, -v136, v139, v138
	v_fmac_f32_e32 v139, v140, v137
	v_fma_f32 v136, -v136, v139, v138
	v_div_fmas_f32 v136, v136, v137, v139
	v_div_fixup_f32 v170, v136, v9, 1.0
	ds_read_b128 v[136:139], v152
	ds_read_b128 v[140:143], v153
	v_pk_mul_f32 v[162:163], v[162:163], v[170:171] op_sel_hi:[1,0]
	v_pk_mul_f32 v[148:149], v[148:149], v[170:171] op_sel_hi:[1,0]
	v_pk_mul_f32 v[150:151], v[150:151], v[170:171] op_sel_hi:[1,0]
	v_pk_mul_f32 v[144:145], v[144:145], v[170:171] op_sel_hi:[1,0]
	s_waitcnt lgkmcnt(0)
; #define LAS __attribute__((address_space(3)))
; __device__ __forceinline__ float bf_lo(unsigned u) { return __uint_as_float(u << 16); }
; __device__ __forceinline__ float bf_hi(unsigned u) { return __uint_as_float(u & 0xffff0000u); }
; __device__ __forceinline__ void ln_affine_l(f32x4 (&v)[4], const LAS float* gL, const LAS float* bL, int lane) {
;     float s = 0.f;
; #pragma unroll
;     for (int j = 0; j < 4; ++j) s += (v[j].x + v[j].y) + (v[j].z + v[j].w);
;     const float mean = wave_sum(s) * (1.f / D_); float s2 = 0.f;
; #pragma unroll
;     for (int j = 0; j < 4; ++j) { v[j] = v[j] - mean; s2 += (v[j].x * v[j].x + v[j].y * v[j].y) + (v[j].z * v[j].z + v[j].w * v[j].w); }
;     const float rstd = 1.f / sqrtf(wave_sum(s2) * (1.f / D_) + LN_EPS_);
; #pragma unroll
;     for (int j = 0; j < 4; ++j) v[j] = v[j] * rstd * *(const LAS f32x4*)(gL + 4 * lane + 256 * j) + *(const LAS f32x4*)(bL + 4 * lane + 256 * j);
; }
; __device__ __forceinline__ void ln1_router_tile(KArgs A, int l, int tile, int lane, const LAS bf16_t* wH) {
;     ...
;         for (int i = 0; i < 8; ++i) { f32x4 hv[4];
; #pragma unroll
;             for (int j = 0; j < 4; ++j) { hv[j].x = bf_lo(hr[i][j].x) * ALPHA_ + bf_lo(mm[i][j].x); hv[j].y = bf_hi(hr[i][j].x) * ALPHA_ + bf_hi(mm[i][j].x); hv[j].z = bf_lo(hr[i][j].y) * ALPHA_ + bf_lo(mm[i][j].y); hv[j].w = bf_hi(hr[i][j].y) * ALPHA_ + bf_hi(mm[i][j].y); }
;             ln_affine_l(hv, gL, bL, lane); store_row_bf16(HB + (size_t)(r0 + i) * D_, hv, lane); }
	v_pk_fma_f32 v[148:149], v[138:139], v[148:149], v[142:143]
	v_pk_fma_f32 v[162:163], v[136:137], v[162:163], v[140:141]
	ds_read_b128 v[136:139], v152 offset:1024
	ds_read_b128 v[140:143], v153 offset:1024
	v_pk_mul_f32 v[146:147], v[146:147], v[170:171] op_sel_hi:[1,0]
	v_pk_mul_f32 v[164:165], v[164:165], v[170:171] op_sel_hi:[1,0]
	v_pk_mul_f32 v[166:167], v[166:167], v[170:171] op_sel_hi:[1,0]
	v_pk_mul_f32 v[168:169], v[168:169], v[170:171] op_sel_hi:[1,0]
	s_waitcnt lgkmcnt(0)
	v_pk_fma_f32 v[144:145], v[138:139], v[144:145], v[142:143]
	v_pk_fma_f32 v[150:151], v[136:137], v[150:151], v[140:141]
	ds_read_b128 v[136:139], v152 offset:2048
	ds_read_b128 v[140:143], v153 offset:2048
	s_waitcnt lgkmcnt(0)
	v_pk_fma_f32 v[164:165], v[138:139], v[164:165], v[142:143]
	v_pk_fma_f32 v[146:147], v[136:137], v[146:147], v[140:141]
	ds_read_b128 v[136:139], v152 offset:3072
	ds_read_b128 v[140:143], v153 offset:3072
	s_waitcnt lgkmcnt(0)
	v_pk_fma_f32 v[136:137], v[136:137], v[166:167], v[140:141]
	v_cvt_pk_bf16_f32 v140, v162, v163
	v_cvt_pk_bf16_f32 v141, v148, v149
	global_store_dwordx2 v[118:119], v[140:141], off
	v_cvt_pk_bf16_f32 v140, v150, v151
	v_cvt_pk_bf16_f32 v141, v144, v145
	v_pk_fma_f32 v[138:139], v[138:139], v[168:169], v[142:143]
	global_store_dwordx2 v[118:119], v[140:141], off offset:512
	v_cvt_pk_bf16_f32 v140, v146, v147
	v_cvt_pk_bf16_f32 v141, v164, v165
	global_store_dwordx2 v[118:119], v[140:141], off offset:1024
	v_cvt_pk_bf16_f32 v136, v136, v137
	v_cvt_pk_bf16_f32 v137, v138, v139
	global_store_dwordx2 v[118:119], v[136:137], off offset:1536
	s_waitcnt vmcnt(59)
	v_lshlrev_b32_e32 v136, 16, v134
	v_and_b32_e32 v137, 0xffff0000, v134
	s_waitcnt vmcnt(58)
	v_lshlrev_b32_e32 v138, 16, v132
	v_and_b32_e32 v139, 0xffff0000, v132
	v_lshlrev_b32_e32 v134, 16, v135
	v_and_b32_e32 v135, 0xffff0000, v135
	v_lshlrev_b32_e32 v132, 16, v133
	v_and_b32_e32 v133, 0xffff0000, v133
	v_pk_fma_f32 v[136:137], v[136:137], s[78:79], v[138:139] op_sel_hi:[1,0,1]
	v_pk_fma_f32 v[132:133], v[134:135], s[78:79], v[132:133] op_sel_hi:[1,0,1]
	s_waitcnt vmcnt(57)
	v_lshlrev_b32_e32 v134, 16, v130
	v_and_b32_e32 v135, 0xffff0000, v130
	s_waitcnt vmcnt(56)
	v_lshlrev_b32_e32 v138, 16, v128
	v_and_b32_e32 v139, 0xffff0000, v128
	v_lshlrev_b32_e32 v130, 16, v131
	v_and_b32_e32 v131, 0xffff0000, v131
	v_lshlrev_b32_e32 v128, 16, v129
	v_and_b32_e32 v129, 0xffff0000, v129
	v_pk_fma_f32 v[134:135], v[134:135], s[78:79], v[138:139] op_sel_hi:[1,0,1]
	v_pk_fma_f32 v[128:129], v[130:131], s[78:79], v[128:129] op_sel_hi:[1,0,1]
	s_waitcnt vmcnt(55)
	v_lshlrev_b32_e32 v130, 16, v126
	v_and_b32_e32 v131, 0xffff0000, v126
	s_waitcnt vmcnt(54)
	v_lshlrev_b32_e32 v138, 16, v124
	v_and_b32_e32 v139, 0xffff0000, v124
	v_lshlrev_b32_e32 v126, 16, v127
	v_and_b32_e32 v127, 0xffff0000, v127
	v_lshlrev_b32_e32 v124, 16, v125
	v_and_b32_e32 v125, 0xffff0000, v125
	v_pk_fma_f32 v[130:131], v[130:131], s[78:79], v[138:139] op_sel_hi:[1,0,1]
	v_pk_fma_f32 v[138:139], v[126:127], s[78:79], v[124:125] op_sel_hi:[1,0,1]
	s_waitcnt vmcnt(53)
	v_lshlrev_b32_e32 v124, 16, v120
	v_and_b32_e32 v125, 0xffff0000, v120
	s_waitcnt vmcnt(52)
	v_lshlrev_b32_e32 v126, 16, v122
	v_and_b32_e32 v127, 0xffff0000, v122
	v_lshlrev_b32_e32 v120, 16, v121
	v_and_b32_e32 v121, 0xffff0000, v121
	v_lshlrev_b32_e32 v122, 16, v123
	v_and_b32_e32 v123, 0xffff0000, v123
	v_pk_fma_f32 v[142:143], v[120:121], s[78:79], v[122:123] op_sel_hi:[1,0,1]
	v_mov_b32_e32 v120, v136
	v_mov_b32_e32 v121, v132
	v_mov_b32_e32 v122, v137
	v_mov_b32_e32 v123, v133
	v_pk_fma_f32 v[140:141], v[124:125], s[78:79], v[126:127] op_sel_hi:[1,0,1]
	v_pk_add_f32 v[120:121], v[120:121], v[122:123]
	v_mov_b32_e32 v122, v134
	v_mov_b32_e32 v123, v128
	v_mov_b32_e32 v124, v135
	v_mov_b32_e32 v125, v129
	v_pk_add_f32 v[122:123], v[122:123], v[124:125]
	v_add_f32_e32 v9, v120, v121
	v_pk_add_f32 v[122:123], v[122:123], v[122:123] op_sel:[0,1] op_sel_hi:[1,0]
	v_pk_add_f32 v[124:125], v[130:131], v[130:131] op_sel:[0,1] op_sel_hi:[1,0]
	v_pk_add_f32 v[126:127], v[138:139], v[138:139] op_sel:[0,1] op_sel_hi:[1,0]
	v_add_f32_e32 v120, 0, v9
	v_mov_b32_e32 v121, v140
	v_mov_b32_e32 v123, v141
	v_mov_b32_e32 v125, v142
	v_mov_b32_e32 v127, v143
	v_pk_add_f32 v[120:121], v[120:121], v[122:123]
	v_pk_add_f32 v[122:123], v[124:125], v[126:127]
	s_nop 0
	v_pk_add_f32 v[120:121], v[120:121], v[122:123]
	s_nop 0
	v_add_f32_e32 v9, v120, v121
	s_waitcnt lgkmcnt(0)
	s_nop 1
	v_add_f32_dpp v9, v9, v9 quad_perm:[1,0,3,2] row_mask:0xf bank_mask:0xf
	s_waitcnt lgkmcnt(0)
	s_nop 1
	v_add_f32_dpp v9, v9, v9 quad_perm:[2,3,0,1] row_mask:0xf bank_mask:0xf
	s_waitcnt lgkmcnt(0)
	s_nop 1
	v_add_f32_dpp v9, v9, v9 row_half_mirror row_mask:0xf bank_mask:0xf
	s_waitcnt lgkmcnt(0)
	s_nop 1
	v_add_f32_dpp v9, v9, v9 row_mirror row_mask:0xf bank_mask:0xf
	s_waitcnt lgkmcnt(0)
	v_mov_b32_e32 v120, v9
	s_nop 1
	v_permlane16_swap_b32 v9, v120
	v_add_f32_e32 v9, v9, v120
	s_waitcnt lgkmcnt(0)
; #define LAS __attribute__((address_space(3)))
; __device__ __forceinline__ float bf_lo(unsigned u) { return __uint_as_float(u << 16); }
; __device__ __forceinline__ float bf_hi(unsigned u) { return __uint_as_float(u & 0xffff0000u); }
; __device__ __forceinline__ void ln_affine_l(f32x4 (&v)[4], const LAS float* gL, const LAS float* bL, int lane) {
;     float s = 0.f;
; #pragma unroll
;     for (int j = 0; j < 4; ++j) s += (v[j].x + v[j].y) + (v[j].z + v[j].w);
;     const float mean = wave_sum(s) * (1.f / D_); float s2 = 0.f;
; #pragma unroll
;     for (int j = 0; j < 4; ++j) { v[j] = v[j] - mean; s2 += (v[j].x * v[j].x + v[j].y * v[j].y) + (v[j].z * v[j].z + v[j].w * v[j].w); }
;     const float rstd = 1.f / sqrtf(wave_sum(s2) * (1.f / D_) + LN_EPS_);
; #pragma unroll
;     for (int j = 0; j < 4; ++j) v[j] = v[j] * rstd * *(const LAS f32x4*)(gL + 4 * lane + 256 * j) + *(const LAS f32x4*)(bL + 4 * lane + 256 * j);
; }
; __device__ __forceinline__ void ln1_router_tile(KArgs A, int l, int tile, int lane, const LAS bf16_t* wH) {
;     ...
;         for (int i = 0; i < 8; ++i) { f32x4 hv[4];
; #pragma unroll
;             for (int j = 0; j < 4; ++j) { hv[j].x = bf_lo(hr[i][j].x) * ALPHA_ + bf_lo(mm[i][j].x); hv[j].y = bf_hi(hr[i][j].x) * ALPHA_ + bf_hi(mm[i][j].x); hv[j].z = bf_lo(hr[i][j].y) * ALPHA_ + bf_lo(mm[i][j].y); hv[j].w = bf_hi(hr[i][j].y) * ALPHA_ + bf_hi(mm[i][j].y); }
;             ln_affine_l(hv, gL, bL, lane); store_row_bf16(HB + (size_t)(r0 + i) * D_, hv, lane); }
	v_mov_b32_e32 v120, v9
	s_nop 1
	v_permlane32_swap_b32 v9, v120
	v_add_f32_e32 v9, v9, v120
	v_fmamk_f32 v137, v9, 0xba800000, v137
	v_fmac_f32_e32 v136, 0xba800000, v9
	v_fmamk_f32 v133, v9, 0xba800000, v133
	v_fmac_f32_e32 v132, 0xba800000, v9
	v_pk_mul_f32 v[120:121], v[132:133], v[132:133]
	v_pk_mul_f32 v[122:123], v[136:137], v[136:137]
	v_fmamk_f32 v135, v9, 0xba800000, v135
	v_pk_mov_b32 v[124:125], v[122:123], v[120:121] op_sel:[1,0]
	v_mov_b32_e32 v123, v121
	v_pk_add_f32 v[120:121], v[124:125], v[122:123]
	v_fmac_f32_e32 v134, 0xba800000, v9
	v_fmamk_f32 v129, v9, 0xba800000, v129
	v_fmac_f32_e32 v128, 0xba800000, v9
	v_pk_add_f32 v[120:121], v[120:121], v[120:121] op_sel_hi:[0,1]
	v_pk_mul_f32 v[122:123], v[128:129], v[128:129]
	v_pk_mul_f32 v[124:125], v[134:135], v[134:135]
	v_fmac_f32_e32 v130, 0xba800000, v9
	v_pk_mov_b32 v[126:127], v[124:125], v[122:123] op_sel:[1,0]
	v_mov_b32_e32 v125, v123
	v_fmamk_f32 v131, v9, 0xba800000, v131
	v_fmac_f32_e32 v138, 0xba800000, v9
	v_mul_f32_e32 v120, v130, v130
	v_pk_add_f32 v[122:123], v[126:127], v[124:125]
	v_fmamk_f32 v139, v9, 0xba800000, v139
	v_pk_fma_f32 v[124:125], v[130:131], v[130:131], v[120:121] op_sel_hi:[1,1,0]
	v_mul_f32_e32 v120, v138, v138
	v_pk_add_f32 v[122:123], v[122:123], v[122:123] op_sel_hi:[0,1]
	v_pk_fma_f32 v[126:127], v[138:139], v[138:139], v[120:121] op_sel_hi:[1,1,0]
	v_fmamk_f32 v143, v9, 0xba800000, v143
	v_fmac_f32_e32 v142, 0xba800000, v9
	v_fmamk_f32 v141, v9, 0xba800000, v141
	v_fmac_f32_e32 v140, 0xba800000, v9
	v_mul_f32_e32 v124, v140, v140
	v_mul_f32_e32 v126, v141, v141
	v_mul_f32_e32 v120, v142, v142
	v_mul_f32_e32 v122, v143, v143
	v_pk_add_f32 v[124:125], v[124:125], v[126:127]
	v_pk_add_f32 v[120:121], v[120:121], v[122:123]
	s_nop 0
	v_pk_add_f32 v[120:121], v[124:125], v[120:121]
	s_nop 0
	v_add_f32_e32 v9, v120, v121
	s_waitcnt lgkmcnt(0)
	s_nop 1
	v_add_f32_dpp v9, v9, v9 quad_perm:[1,0,3,2] row_mask:0xf bank_mask:0xf
	s_waitcnt lgkmcnt(0)
	s_nop 1
	v_add_f32_dpp v9, v9, v9 quad_perm:[2,3,0,1] row_mask:0xf bank_mask:0xf
	s_waitcnt lgkmcnt(0)
	s_nop 1
	v_add_f32_dpp v9, v9, v9 row_half_mirror row_mask:0xf bank_mask:0xf
	s_waitcnt lgkmcnt(0)
	s_nop 1
	v_add_f32_dpp v9, v9, v9 row_mirror row_mask:0xf bank_mask:0xf
	s_waitcnt lgkmcnt(0)
	v_mov_b32_e32 v120, v9
	s_nop 1
	v_permlane16_swap_b32 v9, v120
	v_add_f32_e32 v9, v9, v120
	s_waitcnt lgkmcnt(0)
	v_mov_b32_e32 v120, v9
	s_nop 1
	v_permlane32_swap_b32 v9, v120
	v_add_f32_e32 v9, v9, v120
	v_fmamk_f32 v9, v9, 0x3a800000, v227
	v_cmp_gt_f32_e32 vcc, s47, v9
	v_mul_f32_e32 v120, 0x4f800000, v9
	s_nop 0
	v_cndmask_b32_e32 v9, v9, v120, vcc
	v_sqrt_f32_e32 v120, v9
	s_nop 0
	v_add_u32_e32 v121, -1, v120
	v_fma_f32 v122, -v121, v120, v9
	v_cmp_ge_f32_e64 s[8:9], 0, v122
	v_add_u32_e32 v122, 1, v120
	s_nop 0
	v_cndmask_b32_e64 v121, v120, v121, s[8:9]
	v_fma_f32 v120, -v122, v120, v9
	v_cmp_lt_f32_e64 s[8:9], 0, v120
	s_nop 1
	v_cndmask_b32_e64 v120, v121, v122, s[8:9]
	v_mul_f32_e32 v121, 0x37800000, v120
	v_cndmask_b32_e32 v120, v120, v121, vcc
	v_cmp_class_f32_e32 vcc, v9, v228
	s_nop 1
	v_cndmask_b32_e32 v9, v120, v9, vcc
	v_div_scale_f32 v120, s[0:1], v9, v9, 1.0
	v_rcp_f32_e32 v121, v120
	s_nop 0
	v_fma_f32 v122, -v120, v121, 1.0
	v_fmac_f32_e32 v121, v122, v121
	v_div_scale_f32 v122, vcc, 1.0, v9, 1.0
	v_mul_f32_e32 v123, v122, v121
	v_fma_f32 v124, -v120, v123, v122
	v_fmac_f32_e32 v123, v124, v121
	v_fma_f32 v120, -v120, v123, v122
	v_div_fmas_f32 v120, v120, v121, v123
	v_div_fixup_f32 v144, v120, v9, 1.0
	ds_read_b128 v[120:123], v152
	ds_read_b128 v[124:127], v153
	v_pk_mul_f32 v[136:137], v[136:137], v[144:145] op_sel_hi:[1,0]
	v_pk_mul_f32 v[132:133], v[132:133], v[144:145] op_sel_hi:[1,0]
	v_pk_mul_f32 v[134:135], v[134:135], v[144:145] op_sel_hi:[1,0]
	v_pk_mul_f32 v[128:129], v[128:129], v[144:145] op_sel_hi:[1,0]
	s_waitcnt lgkmcnt(0)
	v_pk_fma_f32 v[132:133], v[122:123], v[132:133], v[126:127]
	v_pk_fma_f32 v[136:137], v[120:121], v[136:137], v[124:125]
	ds_read_b128 v[120:123], v152 offset:1024
	ds_read_b128 v[124:127], v153 offset:1024
	v_pk_mul_f32 v[130:131], v[130:131], v[144:145] op_sel_hi:[1,0]
	v_pk_mul_f32 v[138:139], v[138:139], v[144:145] op_sel_hi:[1,0]
	v_pk_mul_f32 v[140:141], v[140:141], v[144:145] op_sel_hi:[1,0]
	v_pk_mul_f32 v[142:143], v[142:143], v[144:145] op_sel_hi:[1,0]
	s_waitcnt lgkmcnt(0)
	v_pk_fma_f32 v[128:129], v[122:123], v[128:129], v[126:127]
	v_pk_fma_f32 v[134:135], v[120:121], v[134:135], v[124:125]
	ds_read_b128 v[120:123], v152 offset:2048
	ds_read_b128 v[124:127], v153 offset:2048
	s_waitcnt lgkmcnt(0)
	v_pk_fma_f32 v[138:139], v[122:123], v[138:139], v[126:127]
	v_pk_fma_f32 v[130:131], v[120:121], v[130:131], v[124:125]
	ds_read_b128 v[120:123], v152 offset:3072
	ds_read_b128 v[124:127], v153 offset:3072
	s_waitcnt lgkmcnt(0)
	v_pk_fma_f32 v[120:121], v[120:121], v[140:141], v[124:125]
	v_cvt_pk_bf16_f32 v124, v136, v137
	v_cvt_pk_bf16_f32 v125, v132, v133
	global_store_dwordx2 v[118:119], v[124:125], off offset:2048
	v_cvt_pk_bf16_f32 v124, v134, v135
	v_cvt_pk_bf16_f32 v125, v128, v129
	v_pk_fma_f32 v[122:123], v[122:123], v[142:143], v[126:127]
	global_store_dwordx2 v[118:119], v[124:125], off offset:2560
	v_cvt_pk_bf16_f32 v124, v130, v131
	v_cvt_pk_bf16_f32 v125, v138, v139
	global_store_dwordx2 v[118:119], v[124:125], off offset:3072
	v_cvt_pk_bf16_f32 v120, v120, v121
	v_cvt_pk_bf16_f32 v121, v122, v123
	global_store_dwordx2 v[118:119], v[120:121], off offset:3584
	s_waitcnt vmcnt(55)
	v_lshlrev_b32_e32 v118, 16, v116
	v_and_b32_e32 v119, 0xffff0000, v116
	s_waitcnt vmcnt(54)
; #define LAS __attribute__((address_space(3)))
; __device__ __forceinline__ float bf_lo(unsigned u) { return __uint_as_float(u << 16); }
; __device__ __forceinline__ float bf_hi(unsigned u) { return __uint_as_float(u & 0xffff0000u); }
; __device__ __forceinline__ void ln_affine_l(f32x4 (&v)[4], const LAS float* gL, const LAS float* bL, int lane) {
;     float s = 0.f;
; #pragma unroll
;     for (int j = 0; j < 4; ++j) s += (v[j].x + v[j].y) + (v[j].z + v[j].w);
;     const float mean = wave_sum(s) * (1.f / D_); float s2 = 0.f;
; #pragma unroll
;     for (int j = 0; j < 4; ++j) { v[j] = v[j] - mean; s2 += (v[j].x * v[j].x + v[j].y * v[j].y) + (v[j].z * v[j].z + v[j].w * v[j].w); }
;     const float rstd = 1.f / sqrtf(wave_sum(s2) * (1.f / D_) + LN_EPS_);
; #pragma unroll
;     for (int j = 0; j < 4; ++j) v[j] = v[j] * rstd * *(const LAS f32x4*)(gL + 4 * lane + 256 * j) + *(const LAS f32x4*)(bL + 4 * lane + 256 * j);
; }
; __device__ __forceinline__ void ln1_router_tile(KArgs A, int l, int tile, int lane, const LAS bf16_t* wH) {
;     ...
;         for (int i = 0; i < 8; ++i) { f32x4 hv[4];
; #pragma unroll
;             for (int j = 0; j < 4; ++j) { hv[j].x = bf_lo(hr[i][j].x) * ALPHA_ + bf_lo(mm[i][j].x); hv[j].y = bf_hi(hr[i][j].x) * ALPHA_ + bf_hi(mm[i][j].x); hv[j].z = bf_lo(hr[i][j].y) * ALPHA_ + bf_lo(mm[i][j].y); hv[j].w = bf_hi(hr[i][j].y) * ALPHA_ + bf_hi(mm[i][j].y); }
;             ln_affine_l(hv, gL, bL, lane); store_row_bf16(HB + (size_t)(r0 + i) * D_, hv, lane); }
	v_lshlrev_b32_e32 v120, 16, v114
	v_and_b32_e32 v121, 0xffff0000, v114
	v_lshlrev_b32_e32 v116, 16, v117
	v_and_b32_e32 v117, 0xffff0000, v117
	v_lshlrev_b32_e32 v114, 16, v115
	v_and_b32_e32 v115, 0xffff0000, v115
	v_pk_fma_f32 v[118:119], v[118:119], s[78:79], v[120:121] op_sel_hi:[1,0,1]
	v_pk_fma_f32 v[114:115], v[116:117], s[78:79], v[114:115] op_sel_hi:[1,0,1]
	s_waitcnt vmcnt(53)
	v_lshlrev_b32_e32 v116, 16, v112
	v_and_b32_e32 v117, 0xffff0000, v112
	s_waitcnt vmcnt(52)
	v_lshlrev_b32_e32 v120, 16, v110
	v_and_b32_e32 v121, 0xffff0000, v110
	v_lshlrev_b32_e32 v112, 16, v113
	v_and_b32_e32 v113, 0xffff0000, v113
	v_lshlrev_b32_e32 v110, 16, v111
	v_and_b32_e32 v111, 0xffff0000, v111
	v_pk_fma_f32 v[116:117], v[116:117], s[78:79], v[120:121] op_sel_hi:[1,0,1]
	v_pk_fma_f32 v[110:111], v[112:113], s[78:79], v[110:111] op_sel_hi:[1,0,1]
	s_waitcnt vmcnt(51)
	v_lshlrev_b32_e32 v112, 16, v108
	v_and_b32_e32 v113, 0xffff0000, v108
	s_waitcnt vmcnt(50)
	v_lshlrev_b32_e32 v120, 16, v106
	v_and_b32_e32 v121, 0xffff0000, v106
	v_lshlrev_b32_e32 v108, 16, v109
	v_and_b32_e32 v109, 0xffff0000, v109
	v_lshlrev_b32_e32 v106, 16, v107
	v_and_b32_e32 v107, 0xffff0000, v107
	v_pk_fma_f32 v[112:113], v[112:113], s[78:79], v[120:121] op_sel_hi:[1,0,1]
	v_pk_fma_f32 v[120:121], v[108:109], s[78:79], v[106:107] op_sel_hi:[1,0,1]
	s_waitcnt vmcnt(49)
	v_lshlrev_b32_e32 v106, 16, v104
	v_and_b32_e32 v107, 0xffff0000, v104
	s_waitcnt vmcnt(48)
	v_lshlrev_b32_e32 v108, 16, v102
	v_and_b32_e32 v109, 0xffff0000, v102
	v_lshlrev_b32_e32 v104, 16, v105
	v_and_b32_e32 v105, 0xffff0000, v105
	v_lshlrev_b32_e32 v102, 16, v103
	v_and_b32_e32 v103, 0xffff0000, v103
	v_pk_fma_f32 v[124:125], v[104:105], s[78:79], v[102:103] op_sel_hi:[1,0,1]
	v_mov_b32_e32 v102, v118
	v_mov_b32_e32 v103, v114
	v_mov_b32_e32 v104, v119
	v_mov_b32_e32 v105, v115
	v_pk_fma_f32 v[122:123], v[106:107], s[78:79], v[108:109] op_sel_hi:[1,0,1]
	v_pk_add_f32 v[102:103], v[102:103], v[104:105]
	v_mov_b32_e32 v104, v116
	v_mov_b32_e32 v105, v110
	v_mov_b32_e32 v106, v117
	v_mov_b32_e32 v107, v111
	v_pk_add_f32 v[104:105], v[104:105], v[106:107]
	v_add_f32_e32 v9, v102, v103
	v_pk_add_f32 v[104:105], v[104:105], v[104:105] op_sel:[0,1] op_sel_hi:[1,0]
	v_pk_add_f32 v[106:107], v[112:113], v[112:113] op_sel:[0,1] op_sel_hi:[1,0]
	v_pk_add_f32 v[108:109], v[120:121], v[120:121] op_sel:[0,1] op_sel_hi:[1,0]
	v_add_f32_e32 v102, 0, v9
	v_mov_b32_e32 v103, v122
	v_mov_b32_e32 v105, v123
	v_mov_b32_e32 v107, v124
	v_mov_b32_e32 v109, v125
	v_pk_add_f32 v[102:103], v[102:103], v[104:105]
	v_pk_add_f32 v[104:105], v[106:107], v[108:109]
	s_nop 0
	v_pk_add_f32 v[102:103], v[102:103], v[104:105]
	s_nop 0
	v_add_f32_e32 v9, v102, v103
	s_waitcnt lgkmcnt(0)
	s_nop 1
	v_add_f32_dpp v9, v9, v9 quad_perm:[1,0,3,2] row_mask:0xf bank_mask:0xf
	s_waitcnt lgkmcnt(0)
	s_nop 1
	v_add_f32_dpp v9, v9, v9 quad_perm:[2,3,0,1] row_mask:0xf bank_mask:0xf
	s_waitcnt lgkmcnt(0)
	s_nop 1
	v_add_f32_dpp v9, v9, v9 row_half_mirror row_mask:0xf bank_mask:0xf
	s_waitcnt lgkmcnt(0)
	s_nop 1
	v_add_f32_dpp v9, v9, v9 row_mirror row_mask:0xf bank_mask:0xf
	s_waitcnt lgkmcnt(0)
	v_mov_b32_e32 v102, v9
	s_nop 1
	v_permlane16_swap_b32 v9, v102
	v_add_f32_e32 v9, v9, v102
	s_waitcnt lgkmcnt(0)
	v_mov_b32_e32 v102, v9
	s_nop 1
	v_permlane32_swap_b32 v9, v102
	v_add_f32_e32 v9, v9, v102
	v_fmamk_f32 v119, v9, 0xba800000, v119
	v_fmac_f32_e32 v118, 0xba800000, v9
	v_fmamk_f32 v115, v9, 0xba800000, v115
	v_fmac_f32_e32 v114, 0xba800000, v9
	v_pk_mul_f32 v[102:103], v[114:115], v[114:115]
	v_pk_mul_f32 v[104:105], v[118:119], v[118:119]
	v_fmamk_f32 v117, v9, 0xba800000, v117
	v_pk_mov_b32 v[106:107], v[104:105], v[102:103] op_sel:[1,0]
	v_mov_b32_e32 v105, v103
	v_pk_add_f32 v[102:103], v[106:107], v[104:105]
	v_fmac_f32_e32 v116, 0xba800000, v9
	v_fmamk_f32 v111, v9, 0xba800000, v111
	v_fmac_f32_e32 v110, 0xba800000, v9
	v_pk_add_f32 v[102:103], v[102:103], v[102:103] op_sel_hi:[0,1]
	v_pk_mul_f32 v[104:105], v[110:111], v[110:111]
	v_pk_mul_f32 v[106:107], v[116:117], v[116:117]
	v_fmac_f32_e32 v112, 0xba800000, v9
	v_pk_mov_b32 v[108:109], v[106:107], v[104:105] op_sel:[1,0]
	v_mov_b32_e32 v107, v105
	v_fmamk_f32 v113, v9, 0xba800000, v113
	v_fmac_f32_e32 v120, 0xba800000, v9
	v_mul_f32_e32 v102, v112, v112
	v_pk_add_f32 v[104:105], v[108:109], v[106:107]
	v_fmamk_f32 v121, v9, 0xba800000, v121
	v_pk_fma_f32 v[106:107], v[112:113], v[112:113], v[102:103] op_sel_hi:[1,1,0]
	v_mul_f32_e32 v102, v120, v120
	v_pk_add_f32 v[104:105], v[104:105], v[104:105] op_sel_hi:[0,1]
	v_pk_fma_f32 v[108:109], v[120:121], v[120:121], v[102:103] op_sel_hi:[1,1,0]
	v_fmamk_f32 v125, v9, 0xba800000, v125
	v_fmac_f32_e32 v124, 0xba800000, v9
	v_fmamk_f32 v123, v9, 0xba800000, v123
	v_fmac_f32_e32 v122, 0xba800000, v9
	v_mul_f32_e32 v106, v122, v122
	v_mul_f32_e32 v108, v123, v123
	v_mul_f32_e32 v102, v124, v124
	v_mul_f32_e32 v104, v125, v125
	v_pk_add_f32 v[106:107], v[106:107], v[108:109]
	v_pk_add_f32 v[102:103], v[102:103], v[104:105]
	s_nop 0
	v_pk_add_f32 v[102:103], v[106:107], v[102:103]
	s_nop 0
	v_add_f32_e32 v9, v102, v103
	s_waitcnt lgkmcnt(0)
	s_nop 1
	v_add_f32_dpp v9, v9, v9 quad_perm:[1,0,3,2] row_mask:0xf bank_mask:0xf
	s_waitcnt lgkmcnt(0)
	s_nop 1
	v_add_f32_dpp v9, v9, v9 quad_perm:[2,3,0,1] row_mask:0xf bank_mask:0xf
	s_waitcnt lgkmcnt(0)
	s_nop 1
	v_add_f32_dpp v9, v9, v9 row_half_mirror row_mask:0xf bank_mask:0xf
	s_waitcnt lgkmcnt(0)
	s_nop 1
	v_add_f32_dpp v9, v9, v9 row_mirror row_mask:0xf bank_mask:0xf
	s_waitcnt lgkmcnt(0)
	v_mov_b32_e32 v102, v9
	s_nop 1
	v_permlane16_swap_b32 v9, v102
	v_add_f32_e32 v9, v9, v102
	s_waitcnt lgkmcnt(0)
; #define LAS __attribute__((address_space(3)))
; __device__ __forceinline__ float bf_lo(unsigned u) { return __uint_as_float(u << 16); }
; __device__ __forceinline__ float bf_hi(unsigned u) { return __uint_as_float(u & 0xffff0000u); }
; __device__ __forceinline__ void ln_affine_l(f32x4 (&v)[4], const LAS float* gL, const LAS float* bL, int lane) {
;     float s = 0.f;
; #pragma unroll
;     for (int j = 0; j < 4; ++j) s += (v[j].x + v[j].y) + (v[j].z + v[j].w);
;     const float mean = wave_sum(s) * (1.f / D_); float s2 = 0.f;
; #pragma unroll
;     for (int j = 0; j < 4; ++j) { v[j] = v[j] - mean; s2 += (v[j].x * v[j].x + v[j].y * v[j].y) + (v[j].z * v[j].z + v[j].w * v[j].w); }
;     const float rstd = 1.f / sqrtf(wave_sum(s2) * (1.f / D_) + LN_EPS_);
; #pragma unroll
;     for (int j = 0; j < 4; ++j) v[j] = v[j] * rstd * *(const LAS f32x4*)(gL + 4 * lane + 256 * j) + *(const LAS f32x4*)(bL + 4 * lane + 256 * j);
; }
; __device__ __forceinline__ void ln1_router_tile(KArgs A, int l, int tile, int lane, const LAS bf16_t* wH) {
;     ...
;         for (int i = 0; i < 8; ++i) { f32x4 hv[4];
; #pragma unroll
;             for (int j = 0; j < 4; ++j) { hv[j].x = bf_lo(hr[i][j].x) * ALPHA_ + bf_lo(mm[i][j].x); hv[j].y = bf_hi(hr[i][j].x) * ALPHA_ + bf_hi(mm[i][j].x); hv[j].z = bf_lo(hr[i][j].y) * ALPHA_ + bf_lo(mm[i][j].y); hv[j].w = bf_hi(hr[i][j].y) * ALPHA_ + bf_hi(mm[i][j].y); }
;             ln_affine_l(hv, gL, bL, lane); store_row_bf16(HB + (size_t)(r0 + i) * D_, hv, lane); }
	v_mov_b32_e32 v102, v9
	s_nop 1
	v_permlane32_swap_b32 v9, v102
	v_add_f32_e32 v9, v9, v102
	v_fmamk_f32 v9, v9, 0x3a800000, v227
	v_cmp_gt_f32_e32 vcc, s47, v9
	v_mul_f32_e32 v102, 0x4f800000, v9
	s_nop 0
	v_cndmask_b32_e32 v9, v9, v102, vcc
	v_sqrt_f32_e32 v102, v9
	s_nop 0
	v_add_u32_e32 v103, -1, v102
	v_fma_f32 v104, -v103, v102, v9
	v_cmp_ge_f32_e64 s[8:9], 0, v104
	v_add_u32_e32 v104, 1, v102
	s_nop 0
	v_cndmask_b32_e64 v103, v102, v103, s[8:9]
	v_fma_f32 v102, -v104, v102, v9
	v_cmp_lt_f32_e64 s[8:9], 0, v102
	s_nop 1
	v_cndmask_b32_e64 v102, v103, v104, s[8:9]
	v_mul_f32_e32 v103, 0x37800000, v102
	v_cndmask_b32_e32 v102, v102, v103, vcc
	v_cmp_class_f32_e32 vcc, v9, v228
	s_nop 1
	v_cndmask_b32_e32 v9, v102, v9, vcc
	v_div_scale_f32 v102, s[0:1], v9, v9, 1.0
	v_rcp_f32_e32 v103, v102
	s_nop 0
	v_fma_f32 v104, -v102, v103, 1.0
	v_fmac_f32_e32 v103, v104, v103
	v_div_scale_f32 v104, vcc, 1.0, v9, 1.0
	v_mul_f32_e32 v105, v104, v103
	v_fma_f32 v106, -v102, v105, v104
	v_fmac_f32_e32 v105, v106, v103
	v_fma_f32 v102, -v102, v105, v104
	v_div_fmas_f32 v102, v102, v103, v105
	v_div_fixup_f32 v126, v102, v9, 1.0
	ds_read_b128 v[102:105], v152
	ds_read_b128 v[106:109], v153
	v_pk_mul_f32 v[118:119], v[118:119], v[126:127] op_sel_hi:[1,0]
	v_pk_mul_f32 v[114:115], v[114:115], v[126:127] op_sel_hi:[1,0]
	v_pk_mul_f32 v[116:117], v[116:117], v[126:127] op_sel_hi:[1,0]
	v_pk_mul_f32 v[110:111], v[110:111], v[126:127] op_sel_hi:[1,0]
	s_waitcnt lgkmcnt(0)
	v_pk_fma_f32 v[114:115], v[104:105], v[114:115], v[108:109]
	v_pk_fma_f32 v[118:119], v[102:103], v[118:119], v[106:107]
	ds_read_b128 v[102:105], v152 offset:1024
	ds_read_b128 v[106:109], v153 offset:1024
	v_pk_mul_f32 v[112:113], v[112:113], v[126:127] op_sel_hi:[1,0]
	v_pk_mul_f32 v[120:121], v[120:121], v[126:127] op_sel_hi:[1,0]
	v_pk_mul_f32 v[122:123], v[122:123], v[126:127] op_sel_hi:[1,0]
	v_pk_mul_f32 v[124:125], v[124:125], v[126:127] op_sel_hi:[1,0]
	s_waitcnt lgkmcnt(0)
	v_pk_fma_f32 v[110:111], v[104:105], v[110:111], v[108:109]
	v_pk_fma_f32 v[116:117], v[102:103], v[116:117], v[106:107]
	ds_read_b128 v[102:105], v152 offset:2048
	ds_read_b128 v[106:109], v153 offset:2048
	s_waitcnt lgkmcnt(0)
	v_pk_fma_f32 v[120:121], v[104:105], v[120:121], v[108:109]
	v_pk_fma_f32 v[112:113], v[102:103], v[112:113], v[106:107]
	ds_read_b128 v[102:105], v152 offset:3072
	ds_read_b128 v[106:109], v153 offset:3072
	s_waitcnt lgkmcnt(0)
	v_pk_fma_f32 v[102:103], v[102:103], v[122:123], v[106:107]
	v_cvt_pk_bf16_f32 v106, v118, v119
	v_cvt_pk_bf16_f32 v107, v114, v115
	global_store_dwordx2 v[100:101], v[106:107], off
	v_cvt_pk_bf16_f32 v106, v116, v117
	v_cvt_pk_bf16_f32 v107, v110, v111
	v_pk_fma_f32 v[104:105], v[104:105], v[124:125], v[108:109]
	global_store_dwordx2 v[100:101], v[106:107], off offset:512
	v_cvt_pk_bf16_f32 v106, v112, v113
	v_cvt_pk_bf16_f32 v107, v120, v121
	global_store_dwordx2 v[100:101], v[106:107], off offset:1024
	v_cvt_pk_bf16_f32 v102, v102, v103
	v_cvt_pk_bf16_f32 v103, v104, v105
	global_store_dwordx2 v[100:101], v[102:103], off offset:1536
	s_waitcnt vmcnt(51)
	v_lshlrev_b32_e32 v100, 16, v98
	v_and_b32_e32 v101, 0xffff0000, v98
	s_waitcnt vmcnt(50)
	v_lshlrev_b32_e32 v102, 16, v96
	v_and_b32_e32 v103, 0xffff0000, v96
	v_lshlrev_b32_e32 v98, 16, v99
	v_and_b32_e32 v99, 0xffff0000, v99
	v_lshlrev_b32_e32 v96, 16, v97
	v_and_b32_e32 v97, 0xffff0000, v97
	v_pk_fma_f32 v[100:101], v[100:101], s[78:79], v[102:103] op_sel_hi:[1,0,1]
	v_pk_fma_f32 v[96:97], v[98:99], s[78:79], v[96:97] op_sel_hi:[1,0,1]
	s_waitcnt vmcnt(49)
	v_lshlrev_b32_e32 v98, 16, v94
	v_and_b32_e32 v99, 0xffff0000, v94
	s_waitcnt vmcnt(48)
	v_lshlrev_b32_e32 v102, 16, v92
	v_and_b32_e32 v103, 0xffff0000, v92
	v_lshlrev_b32_e32 v94, 16, v95
	v_and_b32_e32 v95, 0xffff0000, v95
	v_lshlrev_b32_e32 v92, 16, v93
	v_and_b32_e32 v93, 0xffff0000, v93
	v_pk_fma_f32 v[98:99], v[98:99], s[78:79], v[102:103] op_sel_hi:[1,0,1]
	v_pk_fma_f32 v[92:93], v[94:95], s[78:79], v[92:93] op_sel_hi:[1,0,1]
	s_waitcnt vmcnt(47)
	v_lshlrev_b32_e32 v94, 16, v90
	v_and_b32_e32 v95, 0xffff0000, v90
	s_waitcnt vmcnt(46)
	v_lshlrev_b32_e32 v102, 16, v88
	v_and_b32_e32 v103, 0xffff0000, v88
	v_lshlrev_b32_e32 v90, 16, v91
	v_and_b32_e32 v91, 0xffff0000, v91
	v_lshlrev_b32_e32 v88, 16, v89
	v_and_b32_e32 v89, 0xffff0000, v89
	v_pk_fma_f32 v[94:95], v[94:95], s[78:79], v[102:103] op_sel_hi:[1,0,1]
	v_pk_fma_f32 v[102:103], v[90:91], s[78:79], v[88:89] op_sel_hi:[1,0,1]
	s_waitcnt vmcnt(45)
	v_lshlrev_b32_e32 v88, 16, v86
	v_and_b32_e32 v89, 0xffff0000, v86
	s_waitcnt vmcnt(44)
	v_lshlrev_b32_e32 v90, 16, v84
	v_and_b32_e32 v91, 0xffff0000, v84
	v_lshlrev_b32_e32 v86, 16, v87
	v_and_b32_e32 v87, 0xffff0000, v87
	v_lshlrev_b32_e32 v84, 16, v85
	v_and_b32_e32 v85, 0xffff0000, v85
	v_pk_fma_f32 v[106:107], v[86:87], s[78:79], v[84:85] op_sel_hi:[1,0,1]
	v_mov_b32_e32 v84, v100
	v_mov_b32_e32 v85, v96
	v_mov_b32_e32 v86, v101
	v_mov_b32_e32 v87, v97
	v_pk_fma_f32 v[104:105], v[88:89], s[78:79], v[90:91] op_sel_hi:[1,0,1]
	v_pk_add_f32 v[84:85], v[84:85], v[86:87]
	v_mov_b32_e32 v86, v98
	v_mov_b32_e32 v87, v92
	v_mov_b32_e32 v88, v99
	v_mov_b32_e32 v89, v93
	v_pk_add_f32 v[86:87], v[86:87], v[88:89]
	v_add_f32_e32 v9, v84, v85
	v_pk_add_f32 v[86:87], v[86:87], v[86:87] op_sel:[0,1] op_sel_hi:[1,0]
	v_pk_add_f32 v[88:89], v[94:95], v[94:95] op_sel:[0,1] op_sel_hi:[1,0]
	v_pk_add_f32 v[90:91], v[102:103], v[102:103] op_sel:[0,1] op_sel_hi:[1,0]
	v_add_f32_e32 v84, 0, v9
	v_mov_b32_e32 v85, v104
	v_mov_b32_e32 v87, v105
	v_mov_b32_e32 v89, v106
	v_mov_b32_e32 v91, v107
	v_pk_add_f32 v[84:85], v[84:85], v[86:87]
	v_pk_add_f32 v[86:87], v[88:89], v[90:91]
	s_nop 0
	v_pk_add_f32 v[84:85], v[84:85], v[86:87]
	s_nop 0
	v_add_f32_e32 v9, v84, v85
	s_waitcnt lgkmcnt(0)
; #define LAS __attribute__((address_space(3)))
; __device__ __forceinline__ float bf_lo(unsigned u) { return __uint_as_float(u << 16); }
; __device__ __forceinline__ float bf_hi(unsigned u) { return __uint_as_float(u & 0xffff0000u); }
; __device__ __forceinline__ void ln_affine_l(f32x4 (&v)[4], const LAS float* gL, const LAS float* bL, int lane) {
;     float s = 0.f;
; #pragma unroll
;     for (int j = 0; j < 4; ++j) s += (v[j].x + v[j].y) + (v[j].z + v[j].w);
;     const float mean = wave_sum(s) * (1.f / D_); float s2 = 0.f;
; #pragma unroll
;     for (int j = 0; j < 4; ++j) { v[j] = v[j] - mean; s2 += (v[j].x * v[j].x + v[j].y * v[j].y) + (v[j].z * v[j].z + v[j].w * v[j].w); }
;     const float rstd = 1.f / sqrtf(wave_sum(s2) * (1.f / D_) + LN_EPS_);
; #pragma unroll
;     for (int j = 0; j < 4; ++j) v[j] = v[j] * rstd * *(const LAS f32x4*)(gL + 4 * lane + 256 * j) + *(const LAS f32x4*)(bL + 4 * lane + 256 * j);
; }
; __device__ __forceinline__ void ln1_router_tile(KArgs A, int l, int tile, int lane, const LAS bf16_t* wH) {
;     ...
;         for (int i = 0; i < 8; ++i) { f32x4 hv[4];
; #pragma unroll
;             for (int j = 0; j < 4; ++j) { hv[j].x = bf_lo(hr[i][j].x) * ALPHA_ + bf_lo(mm[i][j].x); hv[j].y = bf_hi(hr[i][j].x) * ALPHA_ + bf_hi(mm[i][j].x); hv[j].z = bf_lo(hr[i][j].y) * ALPHA_ + bf_lo(mm[i][j].y); hv[j].w = bf_hi(hr[i][j].y) * ALPHA_ + bf_hi(mm[i][j].y); }
;             ln_affine_l(hv, gL, bL, lane); store_row_bf16(HB + (size_t)(r0 + i) * D_, hv, lane); }
	s_nop 1
	v_add_f32_dpp v9, v9, v9 quad_perm:[1,0,3,2] row_mask:0xf bank_mask:0xf
	s_waitcnt lgkmcnt(0)
	s_nop 1
	v_add_f32_dpp v9, v9, v9 quad_perm:[2,3,0,1] row_mask:0xf bank_mask:0xf
	s_waitcnt lgkmcnt(0)
	s_nop 1
	v_add_f32_dpp v9, v9, v9 row_half_mirror row_mask:0xf bank_mask:0xf
	s_waitcnt lgkmcnt(0)
	s_nop 1
	v_add_f32_dpp v9, v9, v9 row_mirror row_mask:0xf bank_mask:0xf
	s_waitcnt lgkmcnt(0)
	v_mov_b32_e32 v84, v9
	s_nop 1
	v_permlane16_swap_b32 v9, v84
	v_add_f32_e32 v9, v9, v84
	s_waitcnt lgkmcnt(0)
	v_mov_b32_e32 v84, v9
	s_nop 1
	v_permlane32_swap_b32 v9, v84
	v_add_f32_e32 v9, v9, v84
	v_fmamk_f32 v101, v9, 0xba800000, v101
	v_fmac_f32_e32 v100, 0xba800000, v9
	v_fmamk_f32 v97, v9, 0xba800000, v97
	v_fmac_f32_e32 v96, 0xba800000, v9
	v_pk_mul_f32 v[84:85], v[96:97], v[96:97]
	v_pk_mul_f32 v[86:87], v[100:101], v[100:101]
	v_fmamk_f32 v99, v9, 0xba800000, v99
	v_pk_mov_b32 v[88:89], v[86:87], v[84:85] op_sel:[1,0]
	v_mov_b32_e32 v87, v85
	v_pk_add_f32 v[84:85], v[88:89], v[86:87]
	v_fmac_f32_e32 v98, 0xba800000, v9
	v_fmamk_f32 v93, v9, 0xba800000, v93
	v_fmac_f32_e32 v92, 0xba800000, v9
	v_pk_add_f32 v[84:85], v[84:85], v[84:85] op_sel_hi:[0,1]
	v_pk_mul_f32 v[86:87], v[92:93], v[92:93]
	v_pk_mul_f32 v[88:89], v[98:99], v[98:99]
	v_fmac_f32_e32 v94, 0xba800000, v9
	v_pk_mov_b32 v[90:91], v[88:89], v[86:87] op_sel:[1,0]
	v_mov_b32_e32 v89, v87
	v_fmamk_f32 v95, v9, 0xba800000, v95
	v_fmac_f32_e32 v102, 0xba800000, v9
	v_mul_f32_e32 v84, v94, v94
	v_pk_add_f32 v[86:87], v[90:91], v[88:89]
	v_fmamk_f32 v103, v9, 0xba800000, v103
	v_pk_fma_f32 v[88:89], v[94:95], v[94:95], v[84:85] op_sel_hi:[1,1,0]
	v_mul_f32_e32 v84, v102, v102
	v_pk_add_f32 v[86:87], v[86:87], v[86:87] op_sel_hi:[0,1]
	v_pk_fma_f32 v[90:91], v[102:103], v[102:103], v[84:85] op_sel_hi:[1,1,0]
	v_fmamk_f32 v107, v9, 0xba800000, v107
	v_fmac_f32_e32 v106, 0xba800000, v9
	v_fmamk_f32 v105, v9, 0xba800000, v105
	v_fmac_f32_e32 v104, 0xba800000, v9
	v_mul_f32_e32 v88, v104, v104
	v_mul_f32_e32 v90, v105, v105
	v_mul_f32_e32 v84, v106, v106
	v_mul_f32_e32 v86, v107, v107
	v_pk_add_f32 v[88:89], v[88:89], v[90:91]
	v_pk_add_f32 v[84:85], v[84:85], v[86:87]
	s_nop 0
	v_pk_add_f32 v[84:85], v[88:89], v[84:85]
	s_nop 0
	v_add_f32_e32 v9, v84, v85
	s_waitcnt lgkmcnt(0)
	s_nop 1
	v_add_f32_dpp v9, v9, v9 quad_perm:[1,0,3,2] row_mask:0xf bank_mask:0xf
	s_waitcnt lgkmcnt(0)
	s_nop 1
	v_add_f32_dpp v9, v9, v9 quad_perm:[2,3,0,1] row_mask:0xf bank_mask:0xf
	s_waitcnt lgkmcnt(0)
	s_nop 1
	v_add_f32_dpp v9, v9, v9 row_half_mirror row_mask:0xf bank_mask:0xf
	s_waitcnt lgkmcnt(0)
	s_nop 1
	v_add_f32_dpp v9, v9, v9 row_mirror row_mask:0xf bank_mask:0xf
	s_waitcnt lgkmcnt(0)
	v_mov_b32_e32 v84, v9
	s_nop 1
	v_permlane16_swap_b32 v9, v84
	v_add_f32_e32 v9, v9, v84
	s_waitcnt lgkmcnt(0)
	v_mov_b32_e32 v84, v9
	s_nop 1
	v_permlane32_swap_b32 v9, v84
	v_add_f32_e32 v9, v9, v84
	v_fmamk_f32 v9, v9, 0x3a800000, v227
	v_cmp_gt_f32_e32 vcc, s47, v9
	v_mul_f32_e32 v84, 0x4f800000, v9
	s_nop 0
	v_cndmask_b32_e32 v9, v9, v84, vcc
	v_sqrt_f32_e32 v84, v9
	s_nop 0
	v_add_u32_e32 v85, -1, v84
	v_fma_f32 v86, -v85, v84, v9
	v_cmp_ge_f32_e64 s[8:9], 0, v86
	v_add_u32_e32 v86, 1, v84
	s_nop 0
	v_cndmask_b32_e64 v85, v84, v85, s[8:9]
	v_fma_f32 v84, -v86, v84, v9
	v_cmp_lt_f32_e64 s[8:9], 0, v84
	s_nop 1
	v_cndmask_b32_e64 v84, v85, v86, s[8:9]
	v_mul_f32_e32 v85, 0x37800000, v84
	v_cndmask_b32_e32 v84, v84, v85, vcc
	v_cmp_class_f32_e32 vcc, v9, v228
	s_nop 1
	v_cndmask_b32_e32 v9, v84, v9, vcc
	v_div_scale_f32 v84, s[0:1], v9, v9, 1.0
	v_rcp_f32_e32 v85, v84
	s_nop 0
	v_fma_f32 v86, -v84, v85, 1.0
	v_fmac_f32_e32 v85, v86, v85
	v_div_scale_f32 v86, vcc, 1.0, v9, 1.0
	v_mul_f32_e32 v87, v86, v85
	v_fma_f32 v88, -v84, v87, v86
	v_fmac_f32_e32 v87, v88, v85
	v_fma_f32 v84, -v84, v87, v86
	v_div_fmas_f32 v84, v84, v85, v87
	v_div_fixup_f32 v108, v84, v9, 1.0
	ds_read_b128 v[84:87], v152
	ds_read_b128 v[88:91], v153
	v_pk_mul_f32 v[100:101], v[100:101], v[108:109] op_sel_hi:[1,0]
	v_pk_mul_f32 v[96:97], v[96:97], v[108:109] op_sel_hi:[1,0]
	v_pk_mul_f32 v[98:99], v[98:99], v[108:109] op_sel_hi:[1,0]
	v_pk_mul_f32 v[92:93], v[92:93], v[108:109] op_sel_hi:[1,0]
	s_waitcnt lgkmcnt(0)
	v_pk_fma_f32 v[96:97], v[86:87], v[96:97], v[90:91]
	v_pk_fma_f32 v[100:101], v[84:85], v[100:101], v[88:89]
	ds_read_b128 v[84:87], v152 offset:1024
	ds_read_b128 v[88:91], v153 offset:1024
	v_pk_mul_f32 v[94:95], v[94:95], v[108:109] op_sel_hi:[1,0]
	v_pk_mul_f32 v[102:103], v[102:103], v[108:109] op_sel_hi:[1,0]
	v_pk_mul_f32 v[104:105], v[104:105], v[108:109] op_sel_hi:[1,0]
	v_pk_mul_f32 v[106:107], v[106:107], v[108:109] op_sel_hi:[1,0]
	s_waitcnt lgkmcnt(0)
	v_pk_fma_f32 v[92:93], v[86:87], v[92:93], v[90:91]
	v_pk_fma_f32 v[98:99], v[84:85], v[98:99], v[88:89]
	ds_read_b128 v[84:87], v152 offset:2048
	ds_read_b128 v[88:91], v153 offset:2048
	s_waitcnt lgkmcnt(0)
	v_pk_fma_f32 v[102:103], v[86:87], v[102:103], v[90:91]
	v_pk_fma_f32 v[94:95], v[84:85], v[94:95], v[88:89]
	ds_read_b128 v[84:87], v152 offset:3072
	ds_read_b128 v[88:91], v153 offset:3072
	s_waitcnt lgkmcnt(0)
	v_pk_fma_f32 v[84:85], v[84:85], v[104:105], v[88:89]
	v_cvt_pk_bf16_f32 v88, v100, v101
	v_cvt_pk_bf16_f32 v89, v96, v97
	global_store_dwordx2 v[82:83], v[88:89], off
	v_cvt_pk_bf16_f32 v88, v98, v99
	v_cvt_pk_bf16_f32 v89, v92, v93
	v_pk_fma_f32 v[86:87], v[86:87], v[106:107], v[90:91]
	global_store_dwordx2 v[82:83], v[88:89], off offset:512
	v_cvt_pk_bf16_f32 v88, v94, v95
	v_cvt_pk_bf16_f32 v89, v102, v103
	global_store_dwordx2 v[82:83], v[88:89], off offset:1024
	v_cvt_pk_bf16_f32 v84, v84, v85
	v_cvt_pk_bf16_f32 v85, v86, v87
	global_store_dwordx2 v[82:83], v[84:85], off offset:1536
	s_waitcnt vmcnt(47)
; #define LAS __attribute__((address_space(3)))
; __device__ __forceinline__ float bf_lo(unsigned u) { return __uint_as_float(u << 16); }
; __device__ __forceinline__ float bf_hi(unsigned u) { return __uint_as_float(u & 0xffff0000u); }
; __device__ __forceinline__ void ln_affine_l(f32x4 (&v)[4], const LAS float* gL, const LAS float* bL, int lane) {
;     float s = 0.f;
; #pragma unroll
;     for (int j = 0; j < 4; ++j) s += (v[j].x + v[j].y) + (v[j].z + v[j].w);
;     const float mean = wave_sum(s) * (1.f / D_); float s2 = 0.f;
; #pragma unroll
;     for (int j = 0; j < 4; ++j) { v[j] = v[j] - mean; s2 += (v[j].x * v[j].x + v[j].y * v[j].y) + (v[j].z * v[j].z + v[j].w * v[j].w); }
;     const float rstd = 1.f / sqrtf(wave_sum(s2) * (1.f / D_) + LN_EPS_);
; #pragma unroll
;     for (int j = 0; j < 4; ++j) v[j] = v[j] * rstd * *(const LAS f32x4*)(gL + 4 * lane + 256 * j) + *(const LAS f32x4*)(bL + 4 * lane + 256 * j);
; }
; __device__ __forceinline__ void ln1_router_tile(KArgs A, int l, int tile, int lane, const LAS bf16_t* wH) {
;     ...
;         for (int i = 0; i < 8; ++i) { f32x4 hv[4];
; #pragma unroll
;             for (int j = 0; j < 4; ++j) { hv[j].x = bf_lo(hr[i][j].x) * ALPHA_ + bf_lo(mm[i][j].x); hv[j].y = bf_hi(hr[i][j].x) * ALPHA_ + bf_hi(mm[i][j].x); hv[j].z = bf_lo(hr[i][j].y) * ALPHA_ + bf_lo(mm[i][j].y); hv[j].w = bf_hi(hr[i][j].y) * ALPHA_ + bf_hi(mm[i][j].y); }
;             ln_affine_l(hv, gL, bL, lane); store_row_bf16(HB + (size_t)(r0 + i) * D_, hv, lane); }
	v_lshlrev_b32_e32 v82, 16, v80
	v_and_b32_e32 v83, 0xffff0000, v80
	s_waitcnt vmcnt(46)
	v_lshlrev_b32_e32 v84, 16, v78
	v_and_b32_e32 v85, 0xffff0000, v78
	v_lshlrev_b32_e32 v80, 16, v81
	v_and_b32_e32 v81, 0xffff0000, v81
	v_lshlrev_b32_e32 v78, 16, v79
	v_and_b32_e32 v79, 0xffff0000, v79
	v_pk_fma_f32 v[82:83], v[82:83], s[78:79], v[84:85] op_sel_hi:[1,0,1]
	v_pk_fma_f32 v[78:79], v[80:81], s[78:79], v[78:79] op_sel_hi:[1,0,1]
	s_waitcnt vmcnt(45)
	v_lshlrev_b32_e32 v80, 16, v76
	v_and_b32_e32 v81, 0xffff0000, v76
	s_waitcnt vmcnt(44)
	v_lshlrev_b32_e32 v84, 16, v74
	v_and_b32_e32 v85, 0xffff0000, v74
	v_lshlrev_b32_e32 v76, 16, v77
	v_and_b32_e32 v77, 0xffff0000, v77
	v_lshlrev_b32_e32 v74, 16, v75
	v_and_b32_e32 v75, 0xffff0000, v75
	v_pk_fma_f32 v[80:81], v[80:81], s[78:79], v[84:85] op_sel_hi:[1,0,1]
	v_pk_fma_f32 v[74:75], v[76:77], s[78:79], v[74:75] op_sel_hi:[1,0,1]
	s_waitcnt vmcnt(43)
	v_lshlrev_b32_e32 v76, 16, v72
	v_and_b32_e32 v77, 0xffff0000, v72
	s_waitcnt vmcnt(42)
	v_lshlrev_b32_e32 v84, 16, v70
	v_and_b32_e32 v85, 0xffff0000, v70
	v_lshlrev_b32_e32 v72, 16, v73
	v_and_b32_e32 v73, 0xffff0000, v73
	v_lshlrev_b32_e32 v70, 16, v71
	v_and_b32_e32 v71, 0xffff0000, v71
	v_pk_fma_f32 v[76:77], v[76:77], s[78:79], v[84:85] op_sel_hi:[1,0,1]
	v_pk_fma_f32 v[84:85], v[72:73], s[78:79], v[70:71] op_sel_hi:[1,0,1]
	s_waitcnt vmcnt(41)
	v_lshlrev_b32_e32 v70, 16, v68
	v_and_b32_e32 v71, 0xffff0000, v68
	s_waitcnt vmcnt(40)
	v_lshlrev_b32_e32 v72, 16, v66
	v_and_b32_e32 v73, 0xffff0000, v66
	v_lshlrev_b32_e32 v68, 16, v69
	v_and_b32_e32 v69, 0xffff0000, v69
	v_lshlrev_b32_e32 v66, 16, v67
	v_and_b32_e32 v67, 0xffff0000, v67
	v_pk_fma_f32 v[88:89], v[68:69], s[78:79], v[66:67] op_sel_hi:[1,0,1]
	v_mov_b32_e32 v66, v82
	v_mov_b32_e32 v67, v78
	v_mov_b32_e32 v68, v83
	v_mov_b32_e32 v69, v79
	v_pk_fma_f32 v[86:87], v[70:71], s[78:79], v[72:73] op_sel_hi:[1,0,1]
	v_pk_add_f32 v[66:67], v[66:67], v[68:69]
	v_mov_b32_e32 v68, v80
	v_mov_b32_e32 v69, v74
	v_mov_b32_e32 v70, v81
	v_mov_b32_e32 v71, v75
	v_pk_add_f32 v[68:69], v[68:69], v[70:71]
	v_add_f32_e32 v9, v66, v67
	v_pk_add_f32 v[68:69], v[68:69], v[68:69] op_sel:[0,1] op_sel_hi:[1,0]
	v_pk_add_f32 v[70:71], v[76:77], v[76:77] op_sel:[0,1] op_sel_hi:[1,0]
	v_pk_add_f32 v[72:73], v[84:85], v[84:85] op_sel:[0,1] op_sel_hi:[1,0]
	v_add_f32_e32 v66, 0, v9
	v_mov_b32_e32 v67, v86
	v_mov_b32_e32 v69, v87
	v_mov_b32_e32 v71, v88
	v_mov_b32_e32 v73, v89
	v_pk_add_f32 v[66:67], v[66:67], v[68:69]
	v_pk_add_f32 v[68:69], v[70:71], v[72:73]
	s_nop 0
	v_pk_add_f32 v[66:67], v[66:67], v[68:69]
	s_nop 0
	v_add_f32_e32 v9, v66, v67
	s_waitcnt lgkmcnt(0)
	s_nop 1
	v_add_f32_dpp v9, v9, v9 quad_perm:[1,0,3,2] row_mask:0xf bank_mask:0xf
	s_waitcnt lgkmcnt(0)
	s_nop 1
	v_add_f32_dpp v9, v9, v9 quad_perm:[2,3,0,1] row_mask:0xf bank_mask:0xf
	s_waitcnt lgkmcnt(0)
	s_nop 1
	v_add_f32_dpp v9, v9, v9 row_half_mirror row_mask:0xf bank_mask:0xf
	s_waitcnt lgkmcnt(0)
	s_nop 1
	v_add_f32_dpp v9, v9, v9 row_mirror row_mask:0xf bank_mask:0xf
	s_waitcnt lgkmcnt(0)
	v_mov_b32_e32 v66, v9
	s_nop 1
	v_permlane16_swap_b32 v9, v66
	v_add_f32_e32 v9, v9, v66
	s_waitcnt lgkmcnt(0)
	v_mov_b32_e32 v66, v9
	s_nop 1
	v_permlane32_swap_b32 v9, v66
	v_add_f32_e32 v9, v9, v66
	v_fmamk_f32 v83, v9, 0xba800000, v83
	v_fmac_f32_e32 v82, 0xba800000, v9
	v_fmamk_f32 v79, v9, 0xba800000, v79
	v_fmac_f32_e32 v78, 0xba800000, v9
	v_pk_mul_f32 v[66:67], v[78:79], v[78:79]
	v_pk_mul_f32 v[68:69], v[82:83], v[82:83]
	v_fmamk_f32 v81, v9, 0xba800000, v81
	v_pk_mov_b32 v[70:71], v[68:69], v[66:67] op_sel:[1,0]
	v_mov_b32_e32 v69, v67
	v_pk_add_f32 v[66:67], v[70:71], v[68:69]
	v_fmac_f32_e32 v80, 0xba800000, v9
	v_fmamk_f32 v75, v9, 0xba800000, v75
	v_fmac_f32_e32 v74, 0xba800000, v9
	v_pk_add_f32 v[66:67], v[66:67], v[66:67] op_sel_hi:[0,1]
	v_pk_mul_f32 v[68:69], v[74:75], v[74:75]
	v_pk_mul_f32 v[70:71], v[80:81], v[80:81]
	v_fmac_f32_e32 v76, 0xba800000, v9
	v_pk_mov_b32 v[72:73], v[70:71], v[68:69] op_sel:[1,0]
	v_mov_b32_e32 v71, v69
	v_fmamk_f32 v77, v9, 0xba800000, v77
	v_fmac_f32_e32 v84, 0xba800000, v9
	v_mul_f32_e32 v66, v76, v76
	v_pk_add_f32 v[68:69], v[72:73], v[70:71]
	v_fmamk_f32 v85, v9, 0xba800000, v85
	v_pk_fma_f32 v[70:71], v[76:77], v[76:77], v[66:67] op_sel_hi:[1,1,0]
	v_mul_f32_e32 v66, v84, v84
	v_pk_add_f32 v[68:69], v[68:69], v[68:69] op_sel_hi:[0,1]
	v_pk_fma_f32 v[72:73], v[84:85], v[84:85], v[66:67] op_sel_hi:[1,1,0]
	v_fmamk_f32 v89, v9, 0xba800000, v89
	v_fmac_f32_e32 v88, 0xba800000, v9
	v_fmamk_f32 v87, v9, 0xba800000, v87
	v_fmac_f32_e32 v86, 0xba800000, v9
	v_mul_f32_e32 v70, v86, v86
	v_mul_f32_e32 v72, v87, v87
	v_mul_f32_e32 v66, v88, v88
	v_mul_f32_e32 v68, v89, v89
	v_pk_add_f32 v[70:71], v[70:71], v[72:73]
	v_pk_add_f32 v[66:67], v[66:67], v[68:69]
	s_nop 0
	v_pk_add_f32 v[66:67], v[70:71], v[66:67]
	s_nop 0
	v_add_f32_e32 v9, v66, v67
	s_waitcnt lgkmcnt(0)
	s_nop 1
	v_add_f32_dpp v9, v9, v9 quad_perm:[1,0,3,2] row_mask:0xf bank_mask:0xf
	s_waitcnt lgkmcnt(0)
	s_nop 1
	v_add_f32_dpp v9, v9, v9 quad_perm:[2,3,0,1] row_mask:0xf bank_mask:0xf
	s_waitcnt lgkmcnt(0)
	s_nop 1
	v_add_f32_dpp v9, v9, v9 row_half_mirror row_mask:0xf bank_mask:0xf
	s_waitcnt lgkmcnt(0)
	s_nop 1
	v_add_f32_dpp v9, v9, v9 row_mirror row_mask:0xf bank_mask:0xf
	s_waitcnt lgkmcnt(0)
	v_mov_b32_e32 v66, v9
	s_nop 1
	v_permlane16_swap_b32 v9, v66
	v_add_f32_e32 v9, v9, v66
	s_waitcnt lgkmcnt(0)
; #define LAS __attribute__((address_space(3)))
; __device__ __forceinline__ float bf_lo(unsigned u) { return __uint_as_float(u << 16); }
; __device__ __forceinline__ float bf_hi(unsigned u) { return __uint_as_float(u & 0xffff0000u); }
; __device__ __forceinline__ void ln_affine_l(f32x4 (&v)[4], const LAS float* gL, const LAS float* bL, int lane) {
;     float s = 0.f;
; #pragma unroll
;     for (int j = 0; j < 4; ++j) s += (v[j].x + v[j].y) + (v[j].z + v[j].w);
;     const float mean = wave_sum(s) * (1.f / D_); float s2 = 0.f;
; #pragma unroll
;     for (int j = 0; j < 4; ++j) { v[j] = v[j] - mean; s2 += (v[j].x * v[j].x + v[j].y * v[j].y) + (v[j].z * v[j].z + v[j].w * v[j].w); }
;     const float rstd = 1.f / sqrtf(wave_sum(s2) * (1.f / D_) + LN_EPS_);
; #pragma unroll
;     for (int j = 0; j < 4; ++j) v[j] = v[j] * rstd * *(const LAS f32x4*)(gL + 4 * lane + 256 * j) + *(const LAS f32x4*)(bL + 4 * lane + 256 * j);
; }
; __device__ __forceinline__ void ln1_router_tile(KArgs A, int l, int tile, int lane, const LAS bf16_t* wH) {
;     ...
;         for (int i = 0; i < 8; ++i) { f32x4 hv[4];
; #pragma unroll
;             for (int j = 0; j < 4; ++j) { hv[j].x = bf_lo(hr[i][j].x) * ALPHA_ + bf_lo(mm[i][j].x); hv[j].y = bf_hi(hr[i][j].x) * ALPHA_ + bf_hi(mm[i][j].x); hv[j].z = bf_lo(hr[i][j].y) * ALPHA_ + bf_lo(mm[i][j].y); hv[j].w = bf_hi(hr[i][j].y) * ALPHA_ + bf_hi(mm[i][j].y); }
;             ln_affine_l(hv, gL, bL, lane); store_row_bf16(HB + (size_t)(r0 + i) * D_, hv, lane); }
	v_mov_b32_e32 v66, v9
	s_nop 1
	v_permlane32_swap_b32 v9, v66
	v_add_f32_e32 v9, v9, v66
	v_fmamk_f32 v9, v9, 0x3a800000, v227
	v_cmp_gt_f32_e32 vcc, s47, v9
	v_mul_f32_e32 v66, 0x4f800000, v9
	s_nop 0
	v_cndmask_b32_e32 v9, v9, v66, vcc
	v_sqrt_f32_e32 v66, v9
	s_nop 0
	v_add_u32_e32 v67, -1, v66
	v_fma_f32 v68, -v67, v66, v9
	v_cmp_ge_f32_e64 s[8:9], 0, v68
	v_add_u32_e32 v68, 1, v66
	s_nop 0
	v_cndmask_b32_e64 v67, v66, v67, s[8:9]
	v_fma_f32 v66, -v68, v66, v9
	v_cmp_lt_f32_e64 s[8:9], 0, v66
	s_nop 1
	v_cndmask_b32_e64 v66, v67, v68, s[8:9]
	v_mul_f32_e32 v67, 0x37800000, v66
	v_cndmask_b32_e32 v66, v66, v67, vcc
	v_cmp_class_f32_e32 vcc, v9, v228
	s_nop 1
	v_cndmask_b32_e32 v9, v66, v9, vcc
	v_div_scale_f32 v66, s[0:1], v9, v9, 1.0
	v_rcp_f32_e32 v67, v66
	s_nop 0
	v_fma_f32 v68, -v66, v67, 1.0
	v_fmac_f32_e32 v67, v68, v67
	v_div_scale_f32 v68, vcc, 1.0, v9, 1.0
	v_mul_f32_e32 v69, v68, v67
	v_fma_f32 v70, -v66, v69, v68
	v_fmac_f32_e32 v69, v70, v67
	v_fma_f32 v66, -v66, v69, v68
	v_div_fmas_f32 v66, v66, v67, v69
	v_div_fixup_f32 v90, v66, v9, 1.0
	ds_read_b128 v[66:69], v152
	ds_read_b128 v[70:73], v153
	v_pk_mul_f32 v[82:83], v[82:83], v[90:91] op_sel_hi:[1,0]
	v_pk_mul_f32 v[78:79], v[78:79], v[90:91] op_sel_hi:[1,0]
	v_pk_mul_f32 v[80:81], v[80:81], v[90:91] op_sel_hi:[1,0]
	v_pk_mul_f32 v[74:75], v[74:75], v[90:91] op_sel_hi:[1,0]
	s_waitcnt lgkmcnt(0)
	v_pk_fma_f32 v[78:79], v[68:69], v[78:79], v[72:73]
	v_pk_fma_f32 v[82:83], v[66:67], v[82:83], v[70:71]
	ds_read_b128 v[66:69], v152 offset:1024
	ds_read_b128 v[70:73], v153 offset:1024
	v_pk_mul_f32 v[76:77], v[76:77], v[90:91] op_sel_hi:[1,0]
	v_pk_mul_f32 v[84:85], v[84:85], v[90:91] op_sel_hi:[1,0]
	v_pk_mul_f32 v[86:87], v[86:87], v[90:91] op_sel_hi:[1,0]
	v_pk_mul_f32 v[88:89], v[88:89], v[90:91] op_sel_hi:[1,0]
	s_waitcnt lgkmcnt(0)
	v_pk_fma_f32 v[74:75], v[68:69], v[74:75], v[72:73]
	v_pk_fma_f32 v[80:81], v[66:67], v[80:81], v[70:71]
	ds_read_b128 v[66:69], v152 offset:2048
	ds_read_b128 v[70:73], v153 offset:2048
	s_waitcnt lgkmcnt(0)
	v_pk_fma_f32 v[84:85], v[68:69], v[84:85], v[72:73]
	v_pk_fma_f32 v[76:77], v[66:67], v[76:77], v[70:71]
	ds_read_b128 v[66:69], v152 offset:3072
	ds_read_b128 v[70:73], v153 offset:3072
	s_waitcnt lgkmcnt(0)
	v_pk_fma_f32 v[66:67], v[66:67], v[86:87], v[70:71]
	v_cvt_pk_bf16_f32 v70, v82, v83
	v_cvt_pk_bf16_f32 v71, v78, v79
	global_store_dwordx2 v[64:65], v[70:71], off
	v_cvt_pk_bf16_f32 v70, v80, v81
	v_cvt_pk_bf16_f32 v71, v74, v75
	v_pk_fma_f32 v[68:69], v[68:69], v[88:89], v[72:73]
	global_store_dwordx2 v[64:65], v[70:71], off offset:512
	v_cvt_pk_bf16_f32 v70, v76, v77
	v_cvt_pk_bf16_f32 v71, v84, v85
	global_store_dwordx2 v[64:65], v[70:71], off offset:1024
	v_cvt_pk_bf16_f32 v66, v66, v67
	v_cvt_pk_bf16_f32 v67, v68, v69
	global_store_dwordx2 v[64:65], v[66:67], off offset:1536
	s_waitcnt vmcnt(43)
	v_lshlrev_b32_e32 v64, 16, v62
	v_and_b32_e32 v65, 0xffff0000, v62
	s_waitcnt vmcnt(42)
	v_lshlrev_b32_e32 v66, 16, v60
	v_and_b32_e32 v67, 0xffff0000, v60
	v_lshlrev_b32_e32 v62, 16, v63
	v_and_b32_e32 v63, 0xffff0000, v63
	v_lshlrev_b32_e32 v60, 16, v61
	v_and_b32_e32 v61, 0xffff0000, v61
	v_pk_fma_f32 v[64:65], v[64:65], s[78:79], v[66:67] op_sel_hi:[1,0,1]
	v_pk_fma_f32 v[60:61], v[62:63], s[78:79], v[60:61] op_sel_hi:[1,0,1]
	s_waitcnt vmcnt(41)
	v_lshlrev_b32_e32 v62, 16, v58
	v_and_b32_e32 v63, 0xffff0000, v58
	s_waitcnt vmcnt(40)
	v_lshlrev_b32_e32 v66, 16, v56
	v_and_b32_e32 v67, 0xffff0000, v56
	v_lshlrev_b32_e32 v58, 16, v59
	v_and_b32_e32 v59, 0xffff0000, v59
	v_lshlrev_b32_e32 v56, 16, v57
	v_and_b32_e32 v57, 0xffff0000, v57
	v_pk_fma_f32 v[62:63], v[62:63], s[78:79], v[66:67] op_sel_hi:[1,0,1]
	v_pk_fma_f32 v[56:57], v[58:59], s[78:79], v[56:57] op_sel_hi:[1,0,1]
	s_waitcnt vmcnt(39)
	v_lshlrev_b32_e32 v58, 16, v54
	v_and_b32_e32 v59, 0xffff0000, v54
	s_waitcnt vmcnt(38)
	v_lshlrev_b32_e32 v66, 16, v52
	v_and_b32_e32 v67, 0xffff0000, v52
	v_lshlrev_b32_e32 v54, 16, v55
	v_and_b32_e32 v55, 0xffff0000, v55
	v_lshlrev_b32_e32 v52, 16, v53
	v_and_b32_e32 v53, 0xffff0000, v53
	v_pk_fma_f32 v[58:59], v[58:59], s[78:79], v[66:67] op_sel_hi:[1,0,1]
	v_pk_fma_f32 v[66:67], v[54:55], s[78:79], v[52:53] op_sel_hi:[1,0,1]
	s_waitcnt vmcnt(37)
	v_lshlrev_b32_e32 v52, 16, v50
	v_and_b32_e32 v53, 0xffff0000, v50
	s_waitcnt vmcnt(36)
	v_lshlrev_b32_e32 v54, 16, v48
	v_and_b32_e32 v55, 0xffff0000, v48
	v_lshlrev_b32_e32 v50, 16, v51
	v_and_b32_e32 v51, 0xffff0000, v51
	v_lshlrev_b32_e32 v48, 16, v49
	v_and_b32_e32 v49, 0xffff0000, v49
	v_pk_fma_f32 v[70:71], v[50:51], s[78:79], v[48:49] op_sel_hi:[1,0,1]
	v_mov_b32_e32 v48, v64
	v_mov_b32_e32 v49, v60
	v_mov_b32_e32 v50, v65
	v_mov_b32_e32 v51, v61
	v_pk_fma_f32 v[68:69], v[52:53], s[78:79], v[54:55] op_sel_hi:[1,0,1]
	v_pk_add_f32 v[48:49], v[48:49], v[50:51]
	v_mov_b32_e32 v50, v62
	v_mov_b32_e32 v51, v56
	v_mov_b32_e32 v52, v63
	v_mov_b32_e32 v53, v57
	v_pk_add_f32 v[50:51], v[50:51], v[52:53]
	v_add_f32_e32 v9, v48, v49
	v_pk_add_f32 v[50:51], v[50:51], v[50:51] op_sel:[0,1] op_sel_hi:[1,0]
	v_pk_add_f32 v[52:53], v[58:59], v[58:59] op_sel:[0,1] op_sel_hi:[1,0]
	v_pk_add_f32 v[54:55], v[66:67], v[66:67] op_sel:[0,1] op_sel_hi:[1,0]
	v_add_f32_e32 v48, 0, v9
	v_mov_b32_e32 v49, v68
	v_mov_b32_e32 v51, v69
	v_mov_b32_e32 v53, v70
	v_mov_b32_e32 v55, v71
	v_pk_add_f32 v[48:49], v[48:49], v[50:51]
	v_pk_add_f32 v[50:51], v[52:53], v[54:55]
	s_nop 0
	v_pk_add_f32 v[48:49], v[48:49], v[50:51]
	s_nop 0
	v_add_f32_e32 v9, v48, v49
	s_waitcnt lgkmcnt(0)
	s_nop 1
	v_add_f32_dpp v9, v9, v9 quad_perm:[1,0,3,2] row_mask:0xf bank_mask:0xf
	s_waitcnt lgkmcnt(0)
; #define LAS __attribute__((address_space(3)))
; __device__ __forceinline__ float bf_lo(unsigned u) { return __uint_as_float(u << 16); }
; __device__ __forceinline__ float bf_hi(unsigned u) { return __uint_as_float(u & 0xffff0000u); }
; __device__ __forceinline__ void ln_affine_l(f32x4 (&v)[4], const LAS float* gL, const LAS float* bL, int lane) {
;     float s = 0.f;
; #pragma unroll
;     for (int j = 0; j < 4; ++j) s += (v[j].x + v[j].y) + (v[j].z + v[j].w);
;     const float mean = wave_sum(s) * (1.f / D_); float s2 = 0.f;
; #pragma unroll
;     for (int j = 0; j < 4; ++j) { v[j] = v[j] - mean; s2 += (v[j].x * v[j].x + v[j].y * v[j].y) + (v[j].z * v[j].z + v[j].w * v[j].w); }
;     const float rstd = 1.f / sqrtf(wave_sum(s2) * (1.f / D_) + LN_EPS_);
; #pragma unroll
;     for (int j = 0; j < 4; ++j) v[j] = v[j] * rstd * *(const LAS f32x4*)(gL + 4 * lane + 256 * j) + *(const LAS f32x4*)(bL + 4 * lane + 256 * j);
; }
; __device__ __forceinline__ void ln1_router_tile(KArgs A, int l, int tile, int lane, const LAS bf16_t* wH) {
;     ...
;         for (int i = 0; i < 8; ++i) { f32x4 hv[4];
; #pragma unroll
;             for (int j = 0; j < 4; ++j) { hv[j].x = bf_lo(hr[i][j].x) * ALPHA_ + bf_lo(mm[i][j].x); hv[j].y = bf_hi(hr[i][j].x) * ALPHA_ + bf_hi(mm[i][j].x); hv[j].z = bf_lo(hr[i][j].y) * ALPHA_ + bf_lo(mm[i][j].y); hv[j].w = bf_hi(hr[i][j].y) * ALPHA_ + bf_hi(mm[i][j].y); }
;             ln_affine_l(hv, gL, bL, lane); store_row_bf16(HB + (size_t)(r0 + i) * D_, hv, lane); }
	s_nop 1
	v_add_f32_dpp v9, v9, v9 quad_perm:[2,3,0,1] row_mask:0xf bank_mask:0xf
	s_waitcnt lgkmcnt(0)
	s_nop 1
	v_add_f32_dpp v9, v9, v9 row_half_mirror row_mask:0xf bank_mask:0xf
	s_waitcnt lgkmcnt(0)
	s_nop 1
	v_add_f32_dpp v9, v9, v9 row_mirror row_mask:0xf bank_mask:0xf
	s_waitcnt lgkmcnt(0)
	v_mov_b32_e32 v48, v9
	s_nop 1
	v_permlane16_swap_b32 v9, v48
	v_add_f32_e32 v9, v9, v48
	s_waitcnt lgkmcnt(0)
	v_mov_b32_e32 v48, v9
	s_nop 1
	v_permlane32_swap_b32 v9, v48
	v_add_f32_e32 v9, v9, v48
	v_fmamk_f32 v65, v9, 0xba800000, v65
	v_fmac_f32_e32 v64, 0xba800000, v9
	v_fmamk_f32 v61, v9, 0xba800000, v61
	v_fmac_f32_e32 v60, 0xba800000, v9
	v_pk_mul_f32 v[48:49], v[60:61], v[60:61]
	v_pk_mul_f32 v[50:51], v[64:65], v[64:65]
	v_fmamk_f32 v63, v9, 0xba800000, v63
	v_pk_mov_b32 v[52:53], v[50:51], v[48:49] op_sel:[1,0]
	v_mov_b32_e32 v51, v49
	v_pk_add_f32 v[48:49], v[52:53], v[50:51]
	v_fmac_f32_e32 v62, 0xba800000, v9
	v_fmamk_f32 v57, v9, 0xba800000, v57
	v_fmac_f32_e32 v56, 0xba800000, v9
	v_pk_add_f32 v[48:49], v[48:49], v[48:49] op_sel_hi:[0,1]
	v_pk_mul_f32 v[50:51], v[56:57], v[56:57]
	v_pk_mul_f32 v[52:53], v[62:63], v[62:63]
	v_fmac_f32_e32 v58, 0xba800000, v9
	v_pk_mov_b32 v[54:55], v[52:53], v[50:51] op_sel:[1,0]
	v_mov_b32_e32 v53, v51
	v_fmamk_f32 v59, v9, 0xba800000, v59
	v_fmac_f32_e32 v66, 0xba800000, v9
	v_mul_f32_e32 v48, v58, v58
	v_pk_add_f32 v[50:51], v[54:55], v[52:53]
	v_fmamk_f32 v67, v9, 0xba800000, v67
	v_pk_fma_f32 v[52:53], v[58:59], v[58:59], v[48:49] op_sel_hi:[1,1,0]
	v_mul_f32_e32 v48, v66, v66
	v_pk_add_f32 v[50:51], v[50:51], v[50:51] op_sel_hi:[0,1]
	v_pk_fma_f32 v[54:55], v[66:67], v[66:67], v[48:49] op_sel_hi:[1,1,0]
	v_fmamk_f32 v71, v9, 0xba800000, v71
	v_fmac_f32_e32 v70, 0xba800000, v9
	v_fmamk_f32 v69, v9, 0xba800000, v69
	v_fmac_f32_e32 v68, 0xba800000, v9
	v_mul_f32_e32 v52, v68, v68
	v_mul_f32_e32 v54, v69, v69
	v_mul_f32_e32 v48, v70, v70
	v_mul_f32_e32 v50, v71, v71
	v_pk_add_f32 v[52:53], v[52:53], v[54:55]
	v_pk_add_f32 v[48:49], v[48:49], v[50:51]
	s_nop 0
	v_pk_add_f32 v[48:49], v[52:53], v[48:49]
	s_nop 0
	v_add_f32_e32 v9, v48, v49
	s_waitcnt lgkmcnt(0)
	s_nop 1
	v_add_f32_dpp v9, v9, v9 quad_perm:[1,0,3,2] row_mask:0xf bank_mask:0xf
	s_waitcnt lgkmcnt(0)
	s_nop 1
	v_add_f32_dpp v9, v9, v9 quad_perm:[2,3,0,1] row_mask:0xf bank_mask:0xf
	s_waitcnt lgkmcnt(0)
	s_nop 1
	v_add_f32_dpp v9, v9, v9 row_half_mirror row_mask:0xf bank_mask:0xf
	s_waitcnt lgkmcnt(0)
	s_nop 1
	v_add_f32_dpp v9, v9, v9 row_mirror row_mask:0xf bank_mask:0xf
	s_waitcnt lgkmcnt(0)
	v_mov_b32_e32 v48, v9
	s_nop 1
	v_permlane16_swap_b32 v9, v48
	v_add_f32_e32 v9, v9, v48
	s_waitcnt lgkmcnt(0)
	v_mov_b32_e32 v48, v9
	s_nop 1
	v_permlane32_swap_b32 v9, v48
	v_add_f32_e32 v9, v9, v48
	v_fmamk_f32 v9, v9, 0x3a800000, v227
	v_cmp_gt_f32_e32 vcc, s47, v9
	v_mul_f32_e32 v48, 0x4f800000, v9
	s_nop 0
	v_cndmask_b32_e32 v9, v9, v48, vcc
	v_sqrt_f32_e32 v48, v9
	s_nop 0
	v_add_u32_e32 v49, -1, v48
	v_fma_f32 v50, -v49, v48, v9
	v_cmp_ge_f32_e64 s[8:9], 0, v50
	v_add_u32_e32 v50, 1, v48
	s_nop 0
	v_cndmask_b32_e64 v49, v48, v49, s[8:9]
	v_fma_f32 v48, -v50, v48, v9
	v_cmp_lt_f32_e64 s[8:9], 0, v48
	s_nop 1
	v_cndmask_b32_e64 v48, v49, v50, s[8:9]
	v_mul_f32_e32 v49, 0x37800000, v48
	v_cndmask_b32_e32 v48, v48, v49, vcc
	v_cmp_class_f32_e32 vcc, v9, v228
	s_nop 1
	v_cndmask_b32_e32 v9, v48, v9, vcc
	v_div_scale_f32 v48, s[0:1], v9, v9, 1.0
	v_rcp_f32_e32 v49, v48
	s_nop 0
	v_fma_f32 v50, -v48, v49, 1.0
	v_fmac_f32_e32 v49, v50, v49
	v_div_scale_f32 v50, vcc, 1.0, v9, 1.0
	v_mul_f32_e32 v51, v50, v49
	v_fma_f32 v52, -v48, v51, v50
	v_fmac_f32_e32 v51, v52, v49
	v_fma_f32 v48, -v48, v51, v50
	v_div_fmas_f32 v48, v48, v49, v51
	v_div_fixup_f32 v72, v48, v9, 1.0
	ds_read_b128 v[48:51], v152
	ds_read_b128 v[52:55], v153
	v_pk_mul_f32 v[64:65], v[64:65], v[72:73] op_sel_hi:[1,0]
	v_pk_mul_f32 v[60:61], v[60:61], v[72:73] op_sel_hi:[1,0]
	v_pk_mul_f32 v[62:63], v[62:63], v[72:73] op_sel_hi:[1,0]
	v_pk_mul_f32 v[56:57], v[56:57], v[72:73] op_sel_hi:[1,0]
	s_waitcnt lgkmcnt(0)
	v_pk_fma_f32 v[60:61], v[50:51], v[60:61], v[54:55]
	v_pk_fma_f32 v[64:65], v[48:49], v[64:65], v[52:53]
	ds_read_b128 v[48:51], v152 offset:1024
	ds_read_b128 v[52:55], v153 offset:1024
	v_pk_mul_f32 v[58:59], v[58:59], v[72:73] op_sel_hi:[1,0]
	v_pk_mul_f32 v[66:67], v[66:67], v[72:73] op_sel_hi:[1,0]
	v_pk_mul_f32 v[68:69], v[68:69], v[72:73] op_sel_hi:[1,0]
	v_pk_mul_f32 v[70:71], v[70:71], v[72:73] op_sel_hi:[1,0]
	s_waitcnt lgkmcnt(0)
	v_pk_fma_f32 v[56:57], v[50:51], v[56:57], v[54:55]
	v_pk_fma_f32 v[62:63], v[48:49], v[62:63], v[52:53]
	ds_read_b128 v[48:51], v152 offset:2048
	ds_read_b128 v[52:55], v153 offset:2048
	s_waitcnt lgkmcnt(0)
	v_pk_fma_f32 v[66:67], v[50:51], v[66:67], v[54:55]
	v_pk_fma_f32 v[58:59], v[48:49], v[58:59], v[52:53]
	ds_read_b128 v[48:51], v152 offset:3072
	ds_read_b128 v[52:55], v153 offset:3072
	s_waitcnt lgkmcnt(0)
	v_pk_fma_f32 v[48:49], v[48:49], v[68:69], v[52:53]
	v_cvt_pk_bf16_f32 v52, v64, v65
	v_cvt_pk_bf16_f32 v53, v60, v61
	global_store_dwordx2 v[46:47], v[52:53], off
	v_cvt_pk_bf16_f32 v52, v62, v63
	v_cvt_pk_bf16_f32 v53, v56, v57
	v_pk_fma_f32 v[50:51], v[50:51], v[70:71], v[54:55]
	global_store_dwordx2 v[46:47], v[52:53], off offset:512
	v_cvt_pk_bf16_f32 v52, v58, v59
	v_cvt_pk_bf16_f32 v53, v66, v67
	global_store_dwordx2 v[46:47], v[52:53], off offset:1024
	v_cvt_pk_bf16_f32 v48, v48, v49
	v_cvt_pk_bf16_f32 v49, v50, v51
	global_store_dwordx2 v[46:47], v[48:49], off offset:1536
	s_waitcnt vmcnt(39)
	v_lshlrev_b32_e32 v46, 16, v44
	v_and_b32_e32 v47, 0xffff0000, v44
	s_waitcnt vmcnt(38)
; #define LAS __attribute__((address_space(3)))
; __device__ __forceinline__ float bf_lo(unsigned u) { return __uint_as_float(u << 16); }
; __device__ __forceinline__ float bf_hi(unsigned u) { return __uint_as_float(u & 0xffff0000u); }
; __device__ __forceinline__ void ln_affine_l(f32x4 (&v)[4], const LAS float* gL, const LAS float* bL, int lane) {
;     float s = 0.f;
; #pragma unroll
;     for (int j = 0; j < 4; ++j) s += (v[j].x + v[j].y) + (v[j].z + v[j].w);
;     const float mean = wave_sum(s) * (1.f / D_); float s2 = 0.f;
; #pragma unroll
;     for (int j = 0; j < 4; ++j) { v[j] = v[j] - mean; s2 += (v[j].x * v[j].x + v[j].y * v[j].y) + (v[j].z * v[j].z + v[j].w * v[j].w); }
;     const float rstd = 1.f / sqrtf(wave_sum(s2) * (1.f / D_) + LN_EPS_);
; #pragma unroll
;     for (int j = 0; j < 4; ++j) v[j] = v[j] * rstd * *(const LAS f32x4*)(gL + 4 * lane + 256 * j) + *(const LAS f32x4*)(bL + 4 * lane + 256 * j);
; }
; __device__ __forceinline__ void ln1_router_tile(KArgs A, int l, int tile, int lane, const LAS bf16_t* wH) {
;     ...
;         for (int i = 0; i < 8; ++i) { f32x4 hv[4];
; #pragma unroll
;             for (int j = 0; j < 4; ++j) { hv[j].x = bf_lo(hr[i][j].x) * ALPHA_ + bf_lo(mm[i][j].x); hv[j].y = bf_hi(hr[i][j].x) * ALPHA_ + bf_hi(mm[i][j].x); hv[j].z = bf_lo(hr[i][j].y) * ALPHA_ + bf_lo(mm[i][j].y); hv[j].w = bf_hi(hr[i][j].y) * ALPHA_ + bf_hi(mm[i][j].y); }
;             ln_affine_l(hv, gL, bL, lane); store_row_bf16(HB + (size_t)(r0 + i) * D_, hv, lane); }
	v_lshlrev_b32_e32 v48, 16, v42
	v_and_b32_e32 v49, 0xffff0000, v42
	v_lshlrev_b32_e32 v44, 16, v45
	v_and_b32_e32 v45, 0xffff0000, v45
	v_lshlrev_b32_e32 v42, 16, v43
	v_and_b32_e32 v43, 0xffff0000, v43
	v_pk_fma_f32 v[46:47], v[46:47], s[78:79], v[48:49] op_sel_hi:[1,0,1]
	v_pk_fma_f32 v[42:43], v[44:45], s[78:79], v[42:43] op_sel_hi:[1,0,1]
	s_waitcnt vmcnt(37)
	v_lshlrev_b32_e32 v44, 16, v40
	v_and_b32_e32 v45, 0xffff0000, v40
	s_waitcnt vmcnt(36)
	v_lshlrev_b32_e32 v48, 16, v38
	v_and_b32_e32 v49, 0xffff0000, v38
	v_lshlrev_b32_e32 v40, 16, v41
	v_and_b32_e32 v41, 0xffff0000, v41
	v_lshlrev_b32_e32 v38, 16, v39
	v_and_b32_e32 v39, 0xffff0000, v39
	v_pk_fma_f32 v[44:45], v[44:45], s[78:79], v[48:49] op_sel_hi:[1,0,1]
	v_pk_fma_f32 v[38:39], v[40:41], s[78:79], v[38:39] op_sel_hi:[1,0,1]
	s_waitcnt vmcnt(35)
	v_lshlrev_b32_e32 v40, 16, v36
	v_and_b32_e32 v41, 0xffff0000, v36
	s_waitcnt vmcnt(34)
	v_lshlrev_b32_e32 v48, 16, v34
	v_and_b32_e32 v49, 0xffff0000, v34
	v_lshlrev_b32_e32 v36, 16, v37
	v_and_b32_e32 v37, 0xffff0000, v37
	v_lshlrev_b32_e32 v34, 16, v35
	v_and_b32_e32 v35, 0xffff0000, v35
	v_pk_fma_f32 v[40:41], v[40:41], s[78:79], v[48:49] op_sel_hi:[1,0,1]
	v_pk_fma_f32 v[48:49], v[36:37], s[78:79], v[34:35] op_sel_hi:[1,0,1]
	s_waitcnt vmcnt(33)
	v_lshlrev_b32_e32 v34, 16, v32
	v_and_b32_e32 v35, 0xffff0000, v32
	s_waitcnt vmcnt(32)
	v_lshlrev_b32_e32 v36, 16, v30
	v_and_b32_e32 v37, 0xffff0000, v30
	v_lshlrev_b32_e32 v32, 16, v33
	v_and_b32_e32 v33, 0xffff0000, v33
	v_lshlrev_b32_e32 v30, 16, v31
	v_and_b32_e32 v31, 0xffff0000, v31
	v_pk_fma_f32 v[52:53], v[32:33], s[78:79], v[30:31] op_sel_hi:[1,0,1]
	v_mov_b32_e32 v30, v46
	v_mov_b32_e32 v31, v42
	v_mov_b32_e32 v32, v47
	v_mov_b32_e32 v33, v43
	v_pk_fma_f32 v[50:51], v[34:35], s[78:79], v[36:37] op_sel_hi:[1,0,1]
	v_pk_add_f32 v[30:31], v[30:31], v[32:33]
	v_mov_b32_e32 v32, v44
	v_mov_b32_e32 v33, v38
	v_mov_b32_e32 v34, v45
	v_mov_b32_e32 v35, v39
	v_pk_add_f32 v[32:33], v[32:33], v[34:35]
	v_add_f32_e32 v9, v30, v31
	v_pk_add_f32 v[32:33], v[32:33], v[32:33] op_sel:[0,1] op_sel_hi:[1,0]
	v_pk_add_f32 v[34:35], v[40:41], v[40:41] op_sel:[0,1] op_sel_hi:[1,0]
	v_pk_add_f32 v[36:37], v[48:49], v[48:49] op_sel:[0,1] op_sel_hi:[1,0]
	v_add_f32_e32 v30, 0, v9
	v_mov_b32_e32 v31, v50
	v_mov_b32_e32 v33, v51
	v_mov_b32_e32 v35, v52
	v_mov_b32_e32 v37, v53
	v_pk_add_f32 v[30:31], v[30:31], v[32:33]
	v_pk_add_f32 v[32:33], v[34:35], v[36:37]
	s_nop 0
	v_pk_add_f32 v[30:31], v[30:31], v[32:33]
	s_nop 0
	v_add_f32_e32 v9, v30, v31
	s_waitcnt lgkmcnt(0)
	s_nop 1
	v_add_f32_dpp v9, v9, v9 quad_perm:[1,0,3,2] row_mask:0xf bank_mask:0xf
	s_waitcnt lgkmcnt(0)
	s_nop 1
	v_add_f32_dpp v9, v9, v9 quad_perm:[2,3,0,1] row_mask:0xf bank_mask:0xf
	s_waitcnt lgkmcnt(0)
	s_nop 1
	v_add_f32_dpp v9, v9, v9 row_half_mirror row_mask:0xf bank_mask:0xf
	s_waitcnt lgkmcnt(0)
	s_nop 1
	v_add_f32_dpp v9, v9, v9 row_mirror row_mask:0xf bank_mask:0xf
	s_waitcnt lgkmcnt(0)
	v_mov_b32_e32 v30, v9
	s_nop 1
	v_permlane16_swap_b32 v9, v30
	v_add_f32_e32 v9, v9, v30
	s_waitcnt lgkmcnt(0)
	v_mov_b32_e32 v30, v9
	s_nop 1
	v_permlane32_swap_b32 v9, v30
	v_add_f32_e32 v9, v9, v30
	v_fmamk_f32 v47, v9, 0xba800000, v47
	v_fmac_f32_e32 v46, 0xba800000, v9
	v_fmamk_f32 v43, v9, 0xba800000, v43
	v_fmac_f32_e32 v42, 0xba800000, v9
	v_pk_mul_f32 v[30:31], v[42:43], v[42:43]
	v_pk_mul_f32 v[32:33], v[46:47], v[46:47]
	v_fmamk_f32 v45, v9, 0xba800000, v45
	v_pk_mov_b32 v[34:35], v[32:33], v[30:31] op_sel:[1,0]
	v_mov_b32_e32 v33, v31
	v_pk_add_f32 v[30:31], v[34:35], v[32:33]
	v_fmac_f32_e32 v44, 0xba800000, v9
	v_fmamk_f32 v39, v9, 0xba800000, v39
	v_fmac_f32_e32 v38, 0xba800000, v9
	v_pk_add_f32 v[30:31], v[30:31], v[30:31] op_sel_hi:[0,1]
	v_pk_mul_f32 v[32:33], v[38:39], v[38:39]
	v_pk_mul_f32 v[34:35], v[44:45], v[44:45]
	v_fmac_f32_e32 v40, 0xba800000, v9
	v_pk_mov_b32 v[36:37], v[34:35], v[32:33] op_sel:[1,0]
	v_mov_b32_e32 v35, v33
	v_fmamk_f32 v41, v9, 0xba800000, v41
	v_fmac_f32_e32 v48, 0xba800000, v9
	v_mul_f32_e32 v30, v40, v40
	v_pk_add_f32 v[32:33], v[36:37], v[34:35]
	v_fmamk_f32 v49, v9, 0xba800000, v49
	v_pk_fma_f32 v[34:35], v[40:41], v[40:41], v[30:31] op_sel_hi:[1,1,0]
	v_mul_f32_e32 v30, v48, v48
	v_pk_add_f32 v[32:33], v[32:33], v[32:33] op_sel_hi:[0,1]
	v_pk_fma_f32 v[36:37], v[48:49], v[48:49], v[30:31] op_sel_hi:[1,1,0]
	v_fmamk_f32 v53, v9, 0xba800000, v53
	v_fmac_f32_e32 v52, 0xba800000, v9
	v_fmamk_f32 v51, v9, 0xba800000, v51
	v_fmac_f32_e32 v50, 0xba800000, v9
	v_mul_f32_e32 v34, v50, v50
	v_mul_f32_e32 v36, v51, v51
	v_mul_f32_e32 v30, v52, v52
	v_mul_f32_e32 v32, v53, v53
	v_pk_add_f32 v[34:35], v[34:35], v[36:37]
	v_pk_add_f32 v[30:31], v[30:31], v[32:33]
	s_nop 0
	v_pk_add_f32 v[30:31], v[34:35], v[30:31]
	s_nop 0
	v_add_f32_e32 v9, v30, v31
	s_waitcnt lgkmcnt(0)
	s_nop 1
	v_add_f32_dpp v9, v9, v9 quad_perm:[1,0,3,2] row_mask:0xf bank_mask:0xf
	s_waitcnt lgkmcnt(0)
	s_nop 1
	v_add_f32_dpp v9, v9, v9 quad_perm:[2,3,0,1] row_mask:0xf bank_mask:0xf
	s_waitcnt lgkmcnt(0)
	s_nop 1
	v_add_f32_dpp v9, v9, v9 row_half_mirror row_mask:0xf bank_mask:0xf
	s_waitcnt lgkmcnt(0)
	s_nop 1
	v_add_f32_dpp v9, v9, v9 row_mirror row_mask:0xf bank_mask:0xf
	s_waitcnt lgkmcnt(0)
	v_mov_b32_e32 v30, v9
	s_nop 1
	v_permlane16_swap_b32 v9, v30
	v_add_f32_e32 v9, v9, v30
	s_waitcnt lgkmcnt(0)
; #define LAS __attribute__((address_space(3)))
; __device__ __forceinline__ float bf_lo(unsigned u) { return __uint_as_float(u << 16); }
; __device__ __forceinline__ float bf_hi(unsigned u) { return __uint_as_float(u & 0xffff0000u); }
; __device__ __forceinline__ void ln_affine_l(f32x4 (&v)[4], const LAS float* gL, const LAS float* bL, int lane) {
;     float s = 0.f;
; #pragma unroll
;     for (int j = 0; j < 4; ++j) s += (v[j].x + v[j].y) + (v[j].z + v[j].w);
;     const float mean = wave_sum(s) * (1.f / D_); float s2 = 0.f;
; #pragma unroll
;     for (int j = 0; j < 4; ++j) { v[j] = v[j] - mean; s2 += (v[j].x * v[j].x + v[j].y * v[j].y) + (v[j].z * v[j].z + v[j].w * v[j].w); }
;     const float rstd = 1.f / sqrtf(wave_sum(s2) * (1.f / D_) + LN_EPS_);
; #pragma unroll
;     for (int j = 0; j < 4; ++j) v[j] = v[j] * rstd * *(const LAS f32x4*)(gL + 4 * lane + 256 * j) + *(const LAS f32x4*)(bL + 4 * lane + 256 * j);
; }
; __device__ __forceinline__ void ln1_router_tile(KArgs A, int l, int tile, int lane, const LAS bf16_t* wH) {
;     ...
;         for (int i = 0; i < 8; ++i) { f32x4 hv[4];
; #pragma unroll
;             for (int j = 0; j < 4; ++j) { hv[j].x = bf_lo(hr[i][j].x) * ALPHA_ + bf_lo(mm[i][j].x); hv[j].y = bf_hi(hr[i][j].x) * ALPHA_ + bf_hi(mm[i][j].x); hv[j].z = bf_lo(hr[i][j].y) * ALPHA_ + bf_lo(mm[i][j].y); hv[j].w = bf_hi(hr[i][j].y) * ALPHA_ + bf_hi(mm[i][j].y); }
;             ln_affine_l(hv, gL, bL, lane); store_row_bf16(HB + (size_t)(r0 + i) * D_, hv, lane); }
	v_mov_b32_e32 v30, v9
	s_nop 1
	v_permlane32_swap_b32 v9, v30
	v_add_f32_e32 v9, v9, v30
	v_fmamk_f32 v9, v9, 0x3a800000, v227
	v_cmp_gt_f32_e32 vcc, s47, v9
	v_mul_f32_e32 v30, 0x4f800000, v9
	s_nop 0
	v_cndmask_b32_e32 v9, v9, v30, vcc
	v_sqrt_f32_e32 v30, v9
	s_nop 0
	v_add_u32_e32 v31, -1, v30
	v_fma_f32 v32, -v31, v30, v9
	v_cmp_ge_f32_e64 s[8:9], 0, v32
	v_add_u32_e32 v32, 1, v30
	s_nop 0
	v_cndmask_b32_e64 v31, v30, v31, s[8:9]
	v_fma_f32 v30, -v32, v30, v9
	v_cmp_lt_f32_e64 s[8:9], 0, v30
	s_nop 1
	v_cndmask_b32_e64 v30, v31, v32, s[8:9]
	v_mul_f32_e32 v31, 0x37800000, v30
	v_cndmask_b32_e32 v30, v30, v31, vcc
	v_cmp_class_f32_e32 vcc, v9, v228
	s_nop 1
	v_cndmask_b32_e32 v9, v30, v9, vcc
	v_div_scale_f32 v30, s[0:1], v9, v9, 1.0
	v_rcp_f32_e32 v31, v30
	s_nop 0
	v_fma_f32 v32, -v30, v31, 1.0
	v_fmac_f32_e32 v31, v32, v31
	v_div_scale_f32 v32, vcc, 1.0, v9, 1.0
	v_mul_f32_e32 v33, v32, v31
	v_fma_f32 v34, -v30, v33, v32
	v_fmac_f32_e32 v33, v34, v31
	v_fma_f32 v30, -v30, v33, v32
	v_div_fmas_f32 v30, v30, v31, v33
	v_div_fixup_f32 v54, v30, v9, 1.0
	ds_read_b128 v[30:33], v152
	ds_read_b128 v[34:37], v153
	v_pk_mul_f32 v[46:47], v[46:47], v[54:55] op_sel_hi:[1,0]
	v_pk_mul_f32 v[42:43], v[42:43], v[54:55] op_sel_hi:[1,0]
	v_pk_mul_f32 v[44:45], v[44:45], v[54:55] op_sel_hi:[1,0]
	v_pk_mul_f32 v[38:39], v[38:39], v[54:55] op_sel_hi:[1,0]
	s_waitcnt lgkmcnt(0)
	v_pk_fma_f32 v[42:43], v[32:33], v[42:43], v[36:37]
	v_pk_fma_f32 v[46:47], v[30:31], v[46:47], v[34:35]
	ds_read_b128 v[30:33], v152 offset:1024
	ds_read_b128 v[34:37], v153 offset:1024
	v_pk_mul_f32 v[40:41], v[40:41], v[54:55] op_sel_hi:[1,0]
	v_pk_mul_f32 v[48:49], v[48:49], v[54:55] op_sel_hi:[1,0]
	v_pk_mul_f32 v[50:51], v[50:51], v[54:55] op_sel_hi:[1,0]
	v_pk_mul_f32 v[52:53], v[52:53], v[54:55] op_sel_hi:[1,0]
	s_waitcnt lgkmcnt(0)
	v_pk_fma_f32 v[38:39], v[32:33], v[38:39], v[36:37]
	v_pk_fma_f32 v[44:45], v[30:31], v[44:45], v[34:35]
	ds_read_b128 v[30:33], v152 offset:2048
	ds_read_b128 v[34:37], v153 offset:2048
	s_waitcnt lgkmcnt(0)
	v_pk_fma_f32 v[48:49], v[32:33], v[48:49], v[36:37]
	v_pk_fma_f32 v[40:41], v[30:31], v[40:41], v[34:35]
	ds_read_b128 v[30:33], v152 offset:3072
	ds_read_b128 v[34:37], v153 offset:3072
	s_waitcnt lgkmcnt(0)
	v_pk_fma_f32 v[30:31], v[30:31], v[50:51], v[34:35]
	v_cvt_pk_bf16_f32 v34, v46, v47
	v_cvt_pk_bf16_f32 v35, v42, v43
	global_store_dwordx2 v[28:29], v[34:35], off
	v_cvt_pk_bf16_f32 v34, v44, v45
	v_cvt_pk_bf16_f32 v35, v38, v39
	v_pk_fma_f32 v[32:33], v[32:33], v[52:53], v[36:37]
	global_store_dwordx2 v[28:29], v[34:35], off offset:512
	v_cvt_pk_bf16_f32 v34, v40, v41
	v_cvt_pk_bf16_f32 v35, v48, v49
	global_store_dwordx2 v[28:29], v[34:35], off offset:1024
	v_cvt_pk_bf16_f32 v30, v30, v31
	v_cvt_pk_bf16_f32 v31, v32, v33
	global_store_dwordx2 v[28:29], v[30:31], off offset:1536
	s_waitcnt vmcnt(35)
	v_lshlrev_b32_e32 v28, 16, v26
	v_and_b32_e32 v29, 0xffff0000, v26
	s_waitcnt vmcnt(34)
	v_lshlrev_b32_e32 v30, 16, v24
	v_and_b32_e32 v31, 0xffff0000, v24
	v_lshlrev_b32_e32 v26, 16, v27
	v_and_b32_e32 v27, 0xffff0000, v27
	v_lshlrev_b32_e32 v24, 16, v25
	v_and_b32_e32 v25, 0xffff0000, v25
	v_pk_fma_f32 v[28:29], v[28:29], s[78:79], v[30:31] op_sel_hi:[1,0,1]
	v_pk_fma_f32 v[24:25], v[26:27], s[78:79], v[24:25] op_sel_hi:[1,0,1]
	s_waitcnt vmcnt(33)
	v_lshlrev_b32_e32 v26, 16, v22
	v_and_b32_e32 v27, 0xffff0000, v22
	s_waitcnt vmcnt(32)
	v_lshlrev_b32_e32 v30, 16, v20
	v_and_b32_e32 v31, 0xffff0000, v20
	v_lshlrev_b32_e32 v22, 16, v23
	v_and_b32_e32 v23, 0xffff0000, v23
	v_lshlrev_b32_e32 v20, 16, v21
	v_and_b32_e32 v21, 0xffff0000, v21
	v_pk_fma_f32 v[26:27], v[26:27], s[78:79], v[30:31] op_sel_hi:[1,0,1]
	v_pk_fma_f32 v[20:21], v[22:23], s[78:79], v[20:21] op_sel_hi:[1,0,1]
	s_waitcnt vmcnt(31)
	v_lshlrev_b32_e32 v22, 16, v18
	v_and_b32_e32 v23, 0xffff0000, v18
	s_waitcnt vmcnt(30)
	v_lshlrev_b32_e32 v30, 16, v16
	v_and_b32_e32 v31, 0xffff0000, v16
	v_lshlrev_b32_e32 v18, 16, v19
	v_and_b32_e32 v19, 0xffff0000, v19
	v_lshlrev_b32_e32 v16, 16, v17
	v_and_b32_e32 v17, 0xffff0000, v17
	v_pk_fma_f32 v[22:23], v[22:23], s[78:79], v[30:31] op_sel_hi:[1,0,1]
	v_pk_fma_f32 v[30:31], v[18:19], s[78:79], v[16:17] op_sel_hi:[1,0,1]
	s_waitcnt vmcnt(29)
	v_lshlrev_b32_e32 v16, 16, v14
	v_and_b32_e32 v17, 0xffff0000, v14
	s_waitcnt vmcnt(28)
	v_lshlrev_b32_e32 v18, 16, v12
	v_and_b32_e32 v19, 0xffff0000, v12
	v_lshlrev_b32_e32 v14, 16, v15
	v_and_b32_e32 v15, 0xffff0000, v15
	v_lshlrev_b32_e32 v12, 16, v13
	v_and_b32_e32 v13, 0xffff0000, v13
	v_pk_fma_f32 v[34:35], v[14:15], s[78:79], v[12:13] op_sel_hi:[1,0,1]
	v_mov_b32_e32 v12, v28
	v_mov_b32_e32 v13, v24
	v_mov_b32_e32 v14, v29
	v_mov_b32_e32 v15, v25
	v_pk_fma_f32 v[32:33], v[16:17], s[78:79], v[18:19] op_sel_hi:[1,0,1]
	v_pk_add_f32 v[12:13], v[12:13], v[14:15]
	v_mov_b32_e32 v14, v26
	v_mov_b32_e32 v15, v20
	v_mov_b32_e32 v16, v27
	v_mov_b32_e32 v17, v21
	v_pk_add_f32 v[14:15], v[14:15], v[16:17]
	v_add_f32_e32 v9, v12, v13
	v_pk_add_f32 v[14:15], v[14:15], v[14:15] op_sel:[0,1] op_sel_hi:[1,0]
	v_pk_add_f32 v[16:17], v[22:23], v[22:23] op_sel:[0,1] op_sel_hi:[1,0]
	v_pk_add_f32 v[18:19], v[30:31], v[30:31] op_sel:[0,1] op_sel_hi:[1,0]
	v_add_f32_e32 v12, 0, v9
	v_mov_b32_e32 v13, v32
	v_mov_b32_e32 v15, v33
	v_mov_b32_e32 v17, v34
	v_mov_b32_e32 v19, v35
	v_pk_add_f32 v[12:13], v[12:13], v[14:15]
	v_pk_add_f32 v[14:15], v[16:17], v[18:19]
	s_nop 0
	v_pk_add_f32 v[12:13], v[12:13], v[14:15]
	s_nop 0
	v_add_f32_e32 v9, v12, v13
	s_waitcnt lgkmcnt(0)
	s_nop 1
	v_add_f32_dpp v9, v9, v9 quad_perm:[1,0,3,2] row_mask:0xf bank_mask:0xf
	s_waitcnt lgkmcnt(0)
; #define LAS __attribute__((address_space(3)))
; __device__ __forceinline__ float bf_lo(unsigned u) { return __uint_as_float(u << 16); }
; __device__ __forceinline__ float bf_hi(unsigned u) { return __uint_as_float(u & 0xffff0000u); }
; __device__ __forceinline__ void ln_affine_l(f32x4 (&v)[4], const LAS float* gL, const LAS float* bL, int lane) {
;     float s = 0.f;
; #pragma unroll
;     for (int j = 0; j < 4; ++j) s += (v[j].x + v[j].y) + (v[j].z + v[j].w);
;     const float mean = wave_sum(s) * (1.f / D_); float s2 = 0.f;
; #pragma unroll
;     for (int j = 0; j < 4; ++j) { v[j] = v[j] - mean; s2 += (v[j].x * v[j].x + v[j].y * v[j].y) + (v[j].z * v[j].z + v[j].w * v[j].w); }
;     const float rstd = 1.f / sqrtf(wave_sum(s2) * (1.f / D_) + LN_EPS_);
; #pragma unroll
;     for (int j = 0; j < 4; ++j) v[j] = v[j] * rstd * *(const LAS f32x4*)(gL + 4 * lane + 256 * j) + *(const LAS f32x4*)(bL + 4 * lane + 256 * j);
; }
; __device__ __forceinline__ void ln1_router_tile(KArgs A, int l, int tile, int lane, const LAS bf16_t* wH) {
;     ...
;         for (int i = 0; i < 8; ++i) { f32x4 hv[4];
; #pragma unroll
;             for (int j = 0; j < 4; ++j) { hv[j].x = bf_lo(hr[i][j].x) * ALPHA_ + bf_lo(mm[i][j].x); hv[j].y = bf_hi(hr[i][j].x) * ALPHA_ + bf_hi(mm[i][j].x); hv[j].z = bf_lo(hr[i][j].y) * ALPHA_ + bf_lo(mm[i][j].y); hv[j].w = bf_hi(hr[i][j].y) * ALPHA_ + bf_hi(mm[i][j].y); }
;             ln_affine_l(hv, gL, bL, lane); store_row_bf16(HB + (size_t)(r0 + i) * D_, hv, lane); }
;     }
;     asm volatile("s_waitcnt vmcnt(0)" ::: "memory");
;     const bf16_t* hb = HB + (size_t)(lane & 15) * D_ + 8 * (lane >> 4);
;     const LAS bf16_t* wb = wH + (lane & 15) * RW_LD + 8 * (lane >> 4);
;     f32x4 acc = (f32x4){0.f, 0.f, 0.f, 0.f};
	s_nop 1
	v_add_f32_dpp v9, v9, v9 quad_perm:[2,3,0,1] row_mask:0xf bank_mask:0xf
	s_waitcnt lgkmcnt(0)
	s_nop 1
	v_add_f32_dpp v9, v9, v9 row_half_mirror row_mask:0xf bank_mask:0xf
	s_waitcnt lgkmcnt(0)
	s_nop 1
	v_add_f32_dpp v9, v9, v9 row_mirror row_mask:0xf bank_mask:0xf
	s_waitcnt lgkmcnt(0)
	v_mov_b32_e32 v12, v9
	s_nop 1
	v_permlane16_swap_b32 v9, v12
	v_add_f32_e32 v9, v9, v12
	s_waitcnt lgkmcnt(0)
	v_mov_b32_e32 v12, v9
	s_nop 1
	v_permlane32_swap_b32 v9, v12
	v_add_f32_e32 v9, v9, v12
	v_fmamk_f32 v29, v9, 0xba800000, v29
	v_fmac_f32_e32 v28, 0xba800000, v9
	v_fmamk_f32 v25, v9, 0xba800000, v25
	v_fmac_f32_e32 v24, 0xba800000, v9
	v_pk_mul_f32 v[12:13], v[24:25], v[24:25]
	v_pk_mul_f32 v[14:15], v[28:29], v[28:29]
	v_fmamk_f32 v27, v9, 0xba800000, v27
	v_pk_mov_b32 v[16:17], v[14:15], v[12:13] op_sel:[1,0]
	v_mov_b32_e32 v15, v13
	v_pk_add_f32 v[12:13], v[16:17], v[14:15]
	v_fmac_f32_e32 v26, 0xba800000, v9
	v_fmamk_f32 v21, v9, 0xba800000, v21
	v_fmac_f32_e32 v20, 0xba800000, v9
	v_pk_add_f32 v[12:13], v[12:13], v[12:13] op_sel_hi:[0,1]
	v_pk_mul_f32 v[14:15], v[20:21], v[20:21]
	v_pk_mul_f32 v[16:17], v[26:27], v[26:27]
	v_fmac_f32_e32 v22, 0xba800000, v9
	v_pk_mov_b32 v[18:19], v[16:17], v[14:15] op_sel:[1,0]
	v_mov_b32_e32 v17, v15
	v_fmamk_f32 v23, v9, 0xba800000, v23
	v_fmac_f32_e32 v30, 0xba800000, v9
	v_mul_f32_e32 v12, v22, v22
	v_pk_add_f32 v[14:15], v[18:19], v[16:17]
	v_fmamk_f32 v31, v9, 0xba800000, v31
	v_pk_fma_f32 v[16:17], v[22:23], v[22:23], v[12:13] op_sel_hi:[1,1,0]
	v_mul_f32_e32 v12, v30, v30
	v_pk_add_f32 v[14:15], v[14:15], v[14:15] op_sel_hi:[0,1]
	v_pk_fma_f32 v[18:19], v[30:31], v[30:31], v[12:13] op_sel_hi:[1,1,0]
	v_fmamk_f32 v35, v9, 0xba800000, v35
	v_fmac_f32_e32 v34, 0xba800000, v9
	v_fmamk_f32 v33, v9, 0xba800000, v33
	v_fmac_f32_e32 v32, 0xba800000, v9
	v_mul_f32_e32 v16, v32, v32
	v_mul_f32_e32 v18, v33, v33
	v_mul_f32_e32 v12, v34, v34
	v_mul_f32_e32 v14, v35, v35
	v_pk_add_f32 v[16:17], v[16:17], v[18:19]
	v_pk_add_f32 v[12:13], v[12:13], v[14:15]
	s_nop 0
	v_pk_add_f32 v[12:13], v[16:17], v[12:13]
	s_nop 0
	v_add_f32_e32 v9, v12, v13
	s_waitcnt lgkmcnt(0)
	s_nop 1
	v_add_f32_dpp v9, v9, v9 quad_perm:[1,0,3,2] row_mask:0xf bank_mask:0xf
	s_waitcnt lgkmcnt(0)
	s_nop 1
	v_add_f32_dpp v9, v9, v9 quad_perm:[2,3,0,1] row_mask:0xf bank_mask:0xf
	s_waitcnt lgkmcnt(0)
	s_nop 1
	v_add_f32_dpp v9, v9, v9 row_half_mirror row_mask:0xf bank_mask:0xf
	s_waitcnt lgkmcnt(0)
	s_nop 1
	v_add_f32_dpp v9, v9, v9 row_mirror row_mask:0xf bank_mask:0xf
	s_waitcnt lgkmcnt(0)
	v_mov_b32_e32 v12, v9
	s_nop 1
	v_permlane16_swap_b32 v9, v12
	v_add_f32_e32 v9, v9, v12
	s_waitcnt lgkmcnt(0)
	v_mov_b32_e32 v12, v9
	s_nop 1
	v_permlane32_swap_b32 v9, v12
	v_add_f32_e32 v9, v9, v12
	v_fmamk_f32 v9, v9, 0x3a800000, v227
	v_cmp_gt_f32_e32 vcc, s47, v9
	v_mul_f32_e32 v12, 0x4f800000, v9
	s_nop 0
	v_cndmask_b32_e32 v9, v9, v12, vcc
	v_sqrt_f32_e32 v12, v9
	s_nop 0
	v_add_u32_e32 v13, -1, v12
	v_fma_f32 v14, -v13, v12, v9
	v_cmp_ge_f32_e64 s[8:9], 0, v14
	v_add_u32_e32 v14, 1, v12
	s_nop 0
	v_cndmask_b32_e64 v13, v12, v13, s[8:9]
	v_fma_f32 v12, -v14, v12, v9
	v_cmp_lt_f32_e64 s[8:9], 0, v12
	s_nop 1
	v_cndmask_b32_e64 v12, v13, v14, s[8:9]
	v_mul_f32_e32 v13, 0x37800000, v12
	v_cndmask_b32_e32 v12, v12, v13, vcc
	v_cmp_class_f32_e32 vcc, v9, v228
	s_mov_b64 s[8:9], 0
	s_nop 0
	v_cndmask_b32_e32 v9, v12, v9, vcc
	v_div_scale_f32 v12, s[0:1], v9, v9, 1.0
	v_rcp_f32_e32 v13, v12
	s_nop 0
	v_fma_f32 v14, -v12, v13, 1.0
	v_fmac_f32_e32 v13, v14, v13
	v_div_scale_f32 v14, vcc, 1.0, v9, 1.0
	v_mul_f32_e32 v15, v14, v13
	v_fma_f32 v16, -v12, v15, v14
	v_fmac_f32_e32 v15, v16, v13
	v_fma_f32 v12, -v12, v15, v14
	v_div_fmas_f32 v12, v12, v13, v15
	v_div_fixup_f32 v36, v12, v9, 1.0
	ds_read_b128 v[12:15], v152
	ds_read_b128 v[16:19], v153
	v_pk_mul_f32 v[28:29], v[28:29], v[36:37] op_sel_hi:[1,0]
	v_pk_mul_f32 v[24:25], v[24:25], v[36:37] op_sel_hi:[1,0]
	v_pk_mul_f32 v[26:27], v[26:27], v[36:37] op_sel_hi:[1,0]
	v_pk_mul_f32 v[20:21], v[20:21], v[36:37] op_sel_hi:[1,0]
	s_waitcnt lgkmcnt(0)
	v_pk_fma_f32 v[24:25], v[14:15], v[24:25], v[18:19]
	v_pk_fma_f32 v[28:29], v[12:13], v[28:29], v[16:17]
	ds_read_b128 v[12:15], v152 offset:1024
	ds_read_b128 v[16:19], v153 offset:1024
	v_pk_mul_f32 v[22:23], v[22:23], v[36:37] op_sel_hi:[1,0]
	v_pk_mul_f32 v[30:31], v[30:31], v[36:37] op_sel_hi:[1,0]
	v_pk_mul_f32 v[32:33], v[32:33], v[36:37] op_sel_hi:[1,0]
	v_pk_mul_f32 v[34:35], v[34:35], v[36:37] op_sel_hi:[1,0]
	s_waitcnt lgkmcnt(0)
	v_pk_fma_f32 v[20:21], v[14:15], v[20:21], v[18:19]
	v_pk_fma_f32 v[26:27], v[12:13], v[26:27], v[16:17]
	ds_read_b128 v[12:15], v152 offset:2048
	ds_read_b128 v[16:19], v153 offset:2048
	s_and_b64 vcc, exec, s[6:7]
	s_waitcnt lgkmcnt(0)
	v_pk_fma_f32 v[30:31], v[14:15], v[30:31], v[18:19]
	v_pk_fma_f32 v[22:23], v[12:13], v[22:23], v[16:17]
	ds_read_b128 v[12:15], v152 offset:3072
	ds_read_b128 v[16:19], v153 offset:3072
	s_waitcnt lgkmcnt(0)
	v_pk_fma_f32 v[12:13], v[12:13], v[32:33], v[16:17]
	v_cvt_pk_bf16_f32 v16, v28, v29
	v_cvt_pk_bf16_f32 v17, v24, v25
	global_store_dwordx2 v[10:11], v[16:17], off
	v_cvt_pk_bf16_f32 v16, v26, v27
	v_cvt_pk_bf16_f32 v17, v20, v21
	v_pk_fma_f32 v[14:15], v[14:15], v[34:35], v[18:19]
	global_store_dwordx2 v[10:11], v[16:17], off offset:512
	v_cvt_pk_bf16_f32 v16, v22, v23
	v_cvt_pk_bf16_f32 v17, v30, v31
	global_store_dwordx2 v[10:11], v[16:17], off offset:1024
	v_cvt_pk_bf16_f32 v12, v12, v13
	v_cvt_pk_bf16_f32 v13, v14, v15
	global_store_dwordx2 v[10:11], v[12:13], off offset:1536
	s_cbranch_vccz .LBB0_584
	s_ashr_i32 s13, s12, 31
	s_waitcnt vmcnt(0)
	s_lshl_b64 s[0:1], s[12:13], 11
	v_mov_b32_e32 v0, 0
	v_lshl_add_u64 v[10:11], v[6:7], 0, s[0:1]
	s_mov_b32 s0, 0
	v_mov_b32_e32 v1, v0
	v_mov_b32_e32 v2, v0
	v_mov_b32_e32 v3, v0

; #define LAS __attribute__((address_space(3)))
; __device__ __forceinline__ void topk_item(KArgs A, int it, LAS unsigned char* lds) {
;     ...
;     for (int it = 0; it < 15; ++it) {
;         const int bit = 28 - 2 * it;
;         const unsigned c1 = T | (1u << bit), c2 = T | (2u << bit), c3 = T | (3u << bit);
;         int c = 0;
; #pragma unroll
;         for (int j = 0; j < 8; ++j) c += ((k[j] >= c1) ? 1 : 0) + ((k[j] >= c2) ? (1 << 10) : 0) + ((k[j] >= c3) ? (1 << 20) : 0);
; #pragma unroll
;         for (int o = 1; o < 64; o <<= 1) c += __shfl_xor(c, o);
;         LAS int* rr = red + (it & 1) * 8;
;         if (lane == 0) rr[w] = c;
.LBB0_648:
	s_lshl_b32 s6, 1, s9
	s_or_b32 s10, s6, s5
	s_lshl_b32 s6, 2, s9
	s_or_b32 s11, s6, s5
	s_lshl_b32 s6, 3, s9
	s_waitcnt vmcnt(0)
	v_cmp_le_u32_e32 vcc, s10, v4
	s_or_b32 s14, s6, s5
	s_and_b32 s6, s8, 8
	v_cndmask_b32_e64 v18, 0, 1, vcc
	v_cmp_gt_u32_e32 vcc, s11, v4
	s_lshl_b32 s6, s6, 2
	s_add_i32 s15, s6, 0
	v_cndmask_b32_e64 v19, v233, 0, vcc
	v_cmp_gt_u32_e32 vcc, s14, v4
	v_or_b32_e32 v18, v19, v18
	s_nop 0
	v_cndmask_b32_e64 v19, v234, 0, vcc
	v_cmp_gt_u32_e32 vcc, s11, v5
	s_nop 1
	v_cndmask_b32_e64 v20, v233, 0, vcc
	v_cmp_gt_u32_e32 vcc, s14, v5
	s_nop 1
	v_cndmask_b32_e64 v21, v234, 0, vcc
	v_cmp_gt_u32_e32 vcc, s11, v6
	s_nop 1
	v_cndmask_b32_e64 v22, v233, 0, vcc
	v_cmp_gt_u32_e32 vcc, s14, v6
	s_nop 1
	v_cndmask_b32_e64 v23, v234, 0, vcc
	v_cmp_gt_u32_e32 vcc, s11, v7
	s_nop 1
	v_cndmask_b32_e64 v24, v233, 0, vcc
	v_cmp_gt_u32_e32 vcc, s14, v7
	s_nop 1
	v_cndmask_b32_e64 v25, v234, 0, vcc
	v_cmp_gt_u32_e32 vcc, s11, v0
	s_nop 1
	v_cndmask_b32_e64 v26, v233, 0, vcc
	v_cmp_gt_u32_e32 vcc, s14, v0
	s_nop 1
	v_cndmask_b32_e64 v27, v234, 0, vcc
	v_cmp_gt_u32_e32 vcc, s11, v1
	s_nop 1
	v_cndmask_b32_e64 v28, v233, 0, vcc
	v_cmp_gt_u32_e32 vcc, s14, v1
	s_nop 1
	v_cndmask_b32_e64 v29, v234, 0, vcc
	v_cmp_le_u32_e32 vcc, s10, v2
	s_nop 1
	v_cndmask_b32_e64 v30, 0, 1, vcc
	v_cmp_gt_u32_e32 vcc, s11, v2
	s_nop 1
	v_cndmask_b32_e64 v31, v233, 0, vcc
	v_cmp_gt_u32_e32 vcc, s14, v2
	v_or_b32_e32 v30, v31, v30
	s_nop 0
	v_cndmask_b32_e64 v32, v234, 0, vcc
	v_cmp_le_u32_e32 vcc, s10, v3
	s_nop 1
	v_cndmask_b32_e64 v33, 0, 1, vcc
	v_cmp_gt_u32_e32 vcc, s11, v3
	s_nop 1
	v_cndmask_b32_e64 v34, v233, 0, vcc
	v_cmp_gt_u32_e32 vcc, s14, v3
	v_or_b32_e32 v33, v34, v33
	s_nop 0
	v_cndmask_b32_e64 v34, v234, 0, vcc
	v_cmp_le_u32_e32 vcc, s10, v1
	s_nop 1
	v_addc_co_u32_e32 v30, vcc, 0, v30, vcc
	v_cmp_le_u32_e32 vcc, s10, v0
	s_nop 1
	v_addc_co_u32_e32 v28, vcc, v30, v28, vcc
	v_cmp_le_u32_e32 vcc, s10, v7
	s_nop 1
	v_addc_co_u32_e32 v26, vcc, v28, v26, vcc
	v_cmp_le_u32_e32 vcc, s10, v6
	s_nop 1
	v_addc_co_u32_e32 v24, vcc, v26, v24, vcc
	v_cmp_le_u32_e32 vcc, s10, v5
	s_nop 1
	v_addc_co_u32_e32 v22, vcc, v24, v22, vcc
	v_add_u32_e32 v20, v22, v20
	v_add3_u32 v19, v20, v19, v21
	v_add3_u32 v19, v19, v23, v25
	v_add3_u32 v19, v19, v27, v29
	v_add3_u32 v19, v19, v32, v34
	v_add3_u32 v18, v19, v18, v33
	s_waitcnt lgkmcnt(0)
	s_nop 1
	v_add_u32_dpp v18, v18, v18 quad_perm:[1,0,3,2] row_mask:0xf bank_mask:0xf
	s_waitcnt lgkmcnt(0)
	s_nop 1
	v_add_u32_dpp v18, v18, v18 quad_perm:[2,3,0,1] row_mask:0xf bank_mask:0xf
	s_waitcnt lgkmcnt(0)
	s_nop 1
	v_add_u32_dpp v18, v18, v18 row_half_mirror row_mask:0xf bank_mask:0xf
	s_waitcnt lgkmcnt(0)
	s_nop 1
	v_add_u32_dpp v18, v18, v18 row_mirror row_mask:0xf bank_mask:0xf
	s_waitcnt lgkmcnt(0)
	v_mov_b32_e32 v19, v18
	s_nop 1
	v_permlane16_swap_b32 v18, v19
	v_add_u32_e32 v18, v18, v19
	ds_bpermute_b32 v19, v17, v18
	s_and_saveexec_b64 s[6:7], s[12:13]
	s_cbranch_execz .LBB0_647
	v_lshl_add_u32 v20, v10, 2, s15
	s_waitcnt lgkmcnt(0)
	v_add_u32_e32 v18, v18, v19
	ds_write_b32 v20, v18
	s_branch .LBB0_647

; #define LAS __attribute__((address_space(3)))
; __device__ __forceinline__ float bf_lo(unsigned u) { return __uint_as_float(u << 16); }
; __device__ __forceinline__ float bf_hi(unsigned u) { return __uint_as_float(u & 0xffff0000u); }
; __device__ __forceinline__ void ln_affine_l(f32x4 (&v)[4], const LAS float* gL, const LAS float* bL, int lane) {
;     float s = 0.f;
; #pragma unroll
;     for (int j = 0; j < 4; ++j) s += (v[j].x + v[j].y) + (v[j].z + v[j].w);
;     const float mean = wave_sum(s) * (1.f / D_); float s2 = 0.f;
; #pragma unroll
;     for (int j = 0; j < 4; ++j) { v[j] = v[j] - mean; s2 += (v[j].x * v[j].x + v[j].y * v[j].y) + (v[j].z * v[j].z + v[j].w * v[j].w); }
;     const float rstd = 1.f / sqrtf(wave_sum(s2) * (1.f / D_) + LN_EPS_);
; #pragma unroll
;     for (int j = 0; j < 4; ++j) v[j] = v[j] * rstd * *(const LAS f32x4*)(gL + 4 * lane + 256 * j) + *(const LAS f32x4*)(bL + 4 * lane + 256 * j);
; }
; __device__ __forceinline__ void combine_ln2_tile(KArgs A, int l, int tile, int lane, const LAS float* gL, const LAS float* bL) {
;     ...
;         for (int i = 0; i < 4; ++i) {
; #pragma unroll
;             for (int j = 0; j < 4; ++j) { f32x4 v = (f32x4){bf_lo(hr[i][j].x), bf_hi(hr[i][j].x), bf_lo(hr[i][j].y), bf_hi(hr[i][j].y)} * ALPHA_;
; #pragma unroll
;                 for (int k = 0; k < 4; ++k) { v.x += bf_lo(q[i][k][j].x); v.y += bf_hi(q[i][k][j].x); v.z += bf_lo(q[i][k][j].y); v.w += bf_hi(q[i][k][j].y); }
;                 hv[i][j] = v; }
;             unsigned m = msk[i];
;             while (m) { const int e = __builtin_ctz(m); m &= m - 1u; add_ye_row(hv[i], ye + ((size_t)e * NB * CAP + __builtin_amdgcn_readlane(slk, 16 * i + e)) * D_, lane); }
;             ln_affine_l(hv[i], gL, bL, lane);
;             if (l == DEPTH_ - 1) store_row_f32_nt(O + (size_t)(r0 + i) * D_, hv[i], lane);
;             else store_row_bf16(HB + (size_t)(r0 + i) * D_, hv[i], lane);
.LBB0_978:
	v_mov_b32_e32 v3, v164
	v_mov_b32_e32 v2, v183
	v_mov_b32_e32 v164, v182
	v_pk_add_f32 v[4:5], v[2:3], v[164:165]
	v_mov_b32_e32 v1, v162
	v_mov_b32_e32 v0, v171
	v_mov_b32_e32 v162, v170
	v_add_f32_e32 v4, v4, v5
	v_add_f32_e32 v160, 0, v4
	v_pk_add_f32 v[4:5], v[0:1], v[162:163]
	v_mov_b32_e32 v159, v14
	v_pk_add_f32 v[4:5], v[4:5], v[4:5] op_sel:[0,1] op_sel_hi:[1,0]
	v_mov_b32_e32 v161, v12
	v_add_f32_e32 v158, v10, v11
	v_add_f32_e32 v14, v8, v9
	v_mov_b32_e32 v5, v13
	v_pk_add_f32 v[4:5], v[160:161], v[4:5]
	v_pk_add_f32 v[6:7], v[158:159], v[14:15]
	s_mov_b32 s17, s87
	v_pk_add_f32 v[4:5], v[4:5], v[6:7]
	s_mov_b32 s11, s87
	v_add_f32_e32 v4, v4, v5
	s_waitcnt lgkmcnt(0)
	s_nop 1
	v_add_f32_dpp v4, v4, v4 quad_perm:[1,0,3,2] row_mask:0xf bank_mask:0xf
	s_waitcnt lgkmcnt(0)
	s_nop 1
	v_add_f32_dpp v4, v4, v4 quad_perm:[2,3,0,1] row_mask:0xf bank_mask:0xf
	s_waitcnt lgkmcnt(0)
	s_nop 1
	v_add_f32_dpp v4, v4, v4 row_half_mirror row_mask:0xf bank_mask:0xf
	s_waitcnt lgkmcnt(0)
	s_nop 1
	v_add_f32_dpp v4, v4, v4 row_mirror row_mask:0xf bank_mask:0xf
	s_waitcnt lgkmcnt(0)
	v_mov_b32_e32 v5, v4
	s_nop 1
	v_permlane16_swap_b32 v4, v5
	v_add_f32_e32 v4, v4, v5
	s_waitcnt lgkmcnt(0)
	v_mov_b32_e32 v5, v4
	v_mov_b32_e32 v12, v4
	s_nop 1
	v_permlane32_swap_b32 v12, v5
	v_add_f32_e32 v12, v12, v5
	v_fmac_f32_e32 v2, 0xba800000, v12
	v_fmac_f32_e32 v165, 0xba800000, v12
	v_fmac_f32_e32 v3, 0xba800000, v12
	v_fmac_f32_e32 v164, 0xba800000, v12
	v_mov_b32_e32 v6, v3
	v_mov_b32_e32 v7, v165
	v_mov_b32_e32 v165, v2
	v_pk_mul_f32 v[4:5], v[6:7], v[6:7]
	v_pk_mul_f32 v[2:3], v[164:165], v[164:165]
	v_fmac_f32_e32 v0, 0xba800000, v12
	v_fmac_f32_e32 v163, 0xba800000, v12
	v_fmac_f32_e32 v1, 0xba800000, v12
	v_pk_mov_b32 v[166:167], v[2:3], v[4:5] op_sel:[1,0]
	v_mov_b32_e32 v3, v5
	v_fmac_f32_e32 v162, 0xba800000, v12
	v_mov_b32_e32 v4, v1
	v_mov_b32_e32 v5, v163
	v_mov_b32_e32 v163, v0
	v_pk_add_f32 v[2:3], v[166:167], v[2:3]
	v_pk_mul_f32 v[166:167], v[4:5], v[4:5]
	v_pk_mul_f32 v[0:1], v[162:163], v[162:163]
	v_fmac_f32_e32 v10, 0xba800000, v12
	v_pk_mov_b32 v[168:169], v[0:1], v[166:167] op_sel:[1,0]
	v_mov_b32_e32 v1, v167
	v_pk_add_f32 v[0:1], v[168:169], v[0:1]
	v_fmac_f32_e32 v11, 0xba800000, v12
	v_pk_add_f32 v[0:1], v[0:1], v[0:1] op_sel_hi:[0,1]
	v_fmac_f32_e32 v8, 0xba800000, v12
	v_mul_f32_e32 v0, v10, v10
	v_fmac_f32_e32 v9, 0xba800000, v12
	v_pk_fma_f32 v[166:167], v[10:11], v[10:11], v[0:1] op_sel_hi:[1,1,0]
	v_mul_f32_e32 v0, v8, v8
	v_pk_add_f32 v[2:3], v[2:3], v[2:3] op_sel_hi:[0,1]
	v_pk_fma_f32 v[168:169], v[8:9], v[8:9], v[0:1] op_sel_hi:[1,1,0]
	v_fmac_f32_e32 v15, 0xba800000, v12
	v_fmac_f32_e32 v159, 0xba800000, v12
	v_fmac_f32_e32 v13, 0xba800000, v12
	v_fmac_f32_e32 v161, 0xba800000, v12
	v_mul_f32_e32 v166, v161, v161
	v_mul_f32_e32 v168, v13, v13
	v_mul_f32_e32 v2, v159, v159
	v_mul_f32_e32 v0, v15, v15
	v_pk_add_f32 v[166:167], v[166:167], v[168:169]
	v_pk_add_f32 v[0:1], v[2:3], v[0:1]
	s_nop 0
	v_pk_add_f32 v[0:1], v[166:167], v[0:1]
	s_nop 0
	v_add_f32_e32 v0, v0, v1
	s_waitcnt lgkmcnt(0)
	s_nop 1
	v_add_f32_dpp v0, v0, v0 quad_perm:[1,0,3,2] row_mask:0xf bank_mask:0xf
	s_waitcnt lgkmcnt(0)
	s_nop 1
	v_add_f32_dpp v0, v0, v0 quad_perm:[2,3,0,1] row_mask:0xf bank_mask:0xf
	s_waitcnt lgkmcnt(0)
	s_nop 1
	v_add_f32_dpp v0, v0, v0 row_half_mirror row_mask:0xf bank_mask:0xf
	s_waitcnt lgkmcnt(0)
	s_nop 1
	v_add_f32_dpp v0, v0, v0 row_mirror row_mask:0xf bank_mask:0xf
	s_waitcnt lgkmcnt(0)
	v_mov_b32_e32 v1, v0
	s_nop 1
	v_permlane16_swap_b32 v0, v1
	v_add_f32_e32 v0, v0, v1
	s_waitcnt lgkmcnt(0)
	v_mov_b32_e32 v1, v0
	s_nop 1
	v_permlane32_swap_b32 v0, v1
	v_add_f32_e32 v0, v0, v1
	v_fmamk_f32 v0, v0, 0x3a800000, v227
	v_cmp_gt_f32_e32 vcc, s47, v0
	v_mul_f32_e32 v1, 0x4f800000, v0
	s_nop 0
	v_cndmask_b32_e32 v0, v0, v1, vcc
	v_sqrt_f32_e32 v1, v0
	s_nop 0
	v_add_u32_e32 v2, -1, v1
	v_fma_f32 v3, -v2, v1, v0
	v_cmp_ge_f32_e64 s[6:7], 0, v3
	v_add_u32_e32 v3, 1, v1
	s_nop 0
	v_cndmask_b32_e64 v2, v1, v2, s[6:7]
	v_fma_f32 v1, -v3, v1, v0
	v_cmp_lt_f32_e64 s[6:7], 0, v1
	s_nop 1
	v_cndmask_b32_e64 v1, v2, v3, s[6:7]
	v_mul_f32_e32 v2, 0x37800000, v1
	v_cndmask_b32_e32 v1, v1, v2, vcc
	v_cmp_class_f32_e32 vcc, v0, v228
	s_nop 1
	v_cndmask_b32_e32 v0, v1, v0, vcc
	v_div_scale_f32 v1, s[0:1], v0, v0, 1.0
	v_rcp_f32_e32 v2, v1
	s_mov_b64 s[0:1], -1
	v_fma_f32 v3, -v1, v2, 1.0
	v_fmac_f32_e32 v2, v3, v2
	v_div_scale_f32 v3, vcc, 1.0, v0, 1.0
	v_mul_f32_e32 v12, v3, v2
	v_fma_f32 v14, -v1, v12, v3
	v_fmac_f32_e32 v12, v14, v2
	v_fma_f32 v1, -v1, v12, v3
	v_div_fmas_f32 v1, v1, v2, v12
	v_div_fixup_f32 v158, v1, v0, 1.0
	v_pk_mul_f32 v[168:169], v[164:165], v[158:159] op_sel_hi:[1,0]
	ds_read_b128 v[0:3], v190
	ds_read_b128 v[164:167], v190 offset:4096
	v_pk_mul_f32 v[6:7], v[6:7], v[158:159] op_sel_hi:[1,0]
	v_mov_b32_e32 v12, v161
	v_mov_b32_e32 v14, v159
	s_andn2_b64 vcc, exec, s[84:85]
	s_waitcnt lgkmcnt(0)
	v_pk_fma_f32 v[2:3], v[2:3], v[6:7], v[166:167]
	v_pk_fma_f32 v[0:1], v[0:1], v[168:169], v[164:165]
	v_pk_mul_f32 v[166:167], v[162:163], v[158:159] op_sel_hi:[1,0]
	v_pk_mul_f32 v[168:169], v[4:5], v[158:159] op_sel_hi:[1,0]
	ds_read_b128 v[4:7], v190 offset:1024
	ds_read_b128 v[162:165], v190 offset:5120
	s_waitcnt lgkmcnt(0)
	v_pk_fma_f32 v[6:7], v[6:7], v[168:169], v[164:165]
	v_pk_fma_f32 v[4:5], v[4:5], v[166:167], v[162:163]
	v_pk_mul_f32 v[166:167], v[10:11], v[158:159] op_sel_hi:[1,0]
	v_pk_mul_f32 v[168:169], v[8:9], v[158:159] op_sel_hi:[1,0]
	ds_read_b128 v[8:11], v190 offset:2048
	ds_read_b128 v[162:165], v190 offset:6144
	s_waitcnt lgkmcnt(0)
	v_pk_fma_f32 v[10:11], v[10:11], v[168:169], v[164:165]
	v_pk_fma_f32 v[8:9], v[8:9], v[166:167], v[162:163]
	v_pk_mul_f32 v[162:163], v[12:13], v[158:159] op_sel_hi:[1,0]
	v_pk_mul_f32 v[164:165], v[14:15], v[158:159] op_sel_hi:[1,0]
	ds_read_b128 v[12:15], v190 offset:3072
	ds_read_b128 v[158:161], v190 offset:7168
	s_waitcnt lgkmcnt(0)
	v_pk_fma_f32 v[12:13], v[12:13], v[162:163], v[158:159]
	v_cndmask_b32_e64 v158, 0, 1, s[84:85]
	v_pk_fma_f32 v[14:15], v[14:15], v[164:165], v[160:161]
	v_cmp_ne_u32_e64 s[6:7], 1, v158
	s_cbranch_vccnz .LBB0_980
	v_lshl_add_u64 v[158:159], s[86:87], 2, v[30:31]
	s_mov_b64 s[0:1], 0
	global_store_dwordx4 v[158:159], v[0:3], off nt
	global_store_dwordx4 v[158:159], v[4:7], off offset:1024 nt
	global_store_dwordx4 v[158:159], v[8:11], off offset:2048 nt
	global_store_dwordx4 v[158:159], v[12:15], off offset:3072 nt

; #define LAS __attribute__((address_space(3)))
; __device__ __forceinline__ float bf_lo(unsigned u) { return __uint_as_float(u << 16); }
; __device__ __forceinline__ float bf_hi(unsigned u) { return __uint_as_float(u & 0xffff0000u); }
; __device__ __forceinline__ void ln_affine_l(f32x4 (&v)[4], const LAS float* gL, const LAS float* bL, int lane) {
;     float s = 0.f;
; #pragma unroll
;     for (int j = 0; j < 4; ++j) s += (v[j].x + v[j].y) + (v[j].z + v[j].w);
;     const float mean = wave_sum(s) * (1.f / D_); float s2 = 0.f;
; #pragma unroll
;     for (int j = 0; j < 4; ++j) { v[j] = v[j] - mean; s2 += (v[j].x * v[j].x + v[j].y * v[j].y) + (v[j].z * v[j].z + v[j].w * v[j].w); }
;     const float rstd = 1.f / sqrtf(wave_sum(s2) * (1.f / D_) + LN_EPS_);
; #pragma unroll
;     for (int j = 0; j < 4; ++j) v[j] = v[j] * rstd * *(const LAS f32x4*)(gL + 4 * lane + 256 * j) + *(const LAS f32x4*)(bL + 4 * lane + 256 * j);
; }
; __device__ __forceinline__ void combine_ln2_tile(KArgs A, int l, int tile, int lane, const LAS float* gL, const LAS float* bL) {
;     ...
;         for (int i = 0; i < 4; ++i) {
; #pragma unroll
;             for (int j = 0; j < 4; ++j) { f32x4 v = (f32x4){bf_lo(hr[i][j].x), bf_hi(hr[i][j].x), bf_lo(hr[i][j].y), bf_hi(hr[i][j].y)} * ALPHA_;
; #pragma unroll
;                 for (int k = 0; k < 4; ++k) { v.x += bf_lo(q[i][k][j].x); v.y += bf_hi(q[i][k][j].x); v.z += bf_lo(q[i][k][j].y); v.w += bf_hi(q[i][k][j].y); }
;                 hv[i][j] = v; }
;             unsigned m = msk[i];
;             while (m) { const int e = __builtin_ctz(m); m &= m - 1u; add_ye_row(hv[i], ye + ((size_t)e * NB * CAP + __builtin_amdgcn_readlane(slk, 16 * i + e)) * D_, lane); }
;             ln_affine_l(hv[i], gL, bL, lane);
;             if (l == DEPTH_ - 1) store_row_f32_nt(O + (size_t)(r0 + i) * D_, hv[i], lane);
;             else store_row_bf16(HB + (size_t)(r0 + i) * D_, hv[i], lane);
.LBB0_984:
	v_mov_b32_e32 v123, v4
	v_mov_b32_e32 v122, v7
	v_mov_b32_e32 v4, v6
	v_mov_b32_e32 v7, v0
	v_mov_b32_e32 v6, v3
	v_mov_b32_e32 v0, v2
	v_pk_add_f32 v[2:3], v[6:7], v[0:1]
	v_mov_b32_e32 v119, v14
	v_add_f32_e32 v2, v2, v3
	v_add_f32_e32 v120, 0, v2
	v_pk_add_f32 v[2:3], v[122:123], v[4:5]
	v_mov_b32_e32 v121, v12
	v_pk_add_f32 v[2:3], v[2:3], v[2:3] op_sel:[0,1] op_sel_hi:[1,0]
	v_add_f32_e32 v118, v8, v9
	v_add_f32_e32 v14, v10, v11
	v_mov_b32_e32 v3, v13
	v_pk_add_f32 v[2:3], v[120:121], v[2:3]
	v_pk_add_f32 v[124:125], v[118:119], v[14:15]
	s_nop 0
	v_pk_add_f32 v[2:3], v[2:3], v[124:125]
	s_nop 0
	v_add_f32_e32 v2, v2, v3
	s_waitcnt lgkmcnt(0)
	s_nop 1
	v_add_f32_dpp v2, v2, v2 quad_perm:[1,0,3,2] row_mask:0xf bank_mask:0xf
	s_waitcnt lgkmcnt(0)
	s_nop 1
	v_add_f32_dpp v2, v2, v2 quad_perm:[2,3,0,1] row_mask:0xf bank_mask:0xf
	s_waitcnt lgkmcnt(0)
	s_nop 1
	v_add_f32_dpp v2, v2, v2 row_half_mirror row_mask:0xf bank_mask:0xf
	s_waitcnt lgkmcnt(0)
	s_nop 1
	v_add_f32_dpp v2, v2, v2 row_mirror row_mask:0xf bank_mask:0xf
	s_waitcnt lgkmcnt(0)
	v_mov_b32_e32 v3, v2
	s_nop 1
	v_permlane16_swap_b32 v2, v3
	v_add_f32_e32 v2, v2, v3
	s_waitcnt lgkmcnt(0)
	v_mov_b32_e32 v3, v2
	v_mov_b32_e32 v14, v2
	s_nop 1
	v_permlane32_swap_b32 v14, v3
	v_add_f32_e32 v14, v14, v3
	v_fmac_f32_e32 v6, 0xba800000, v14
	v_fmac_f32_e32 v1, 0xba800000, v14
	v_fmac_f32_e32 v7, 0xba800000, v14
	v_fmac_f32_e32 v0, 0xba800000, v14
	v_mov_b32_e32 v2, v7
	v_mov_b32_e32 v3, v1
	v_mov_b32_e32 v1, v6
	v_pk_mul_f32 v[124:125], v[2:3], v[2:3]
	v_pk_mul_f32 v[6:7], v[0:1], v[0:1]
	v_fmac_f32_e32 v122, 0xba800000, v14
	v_pk_mov_b32 v[126:127], v[6:7], v[124:125] op_sel:[1,0]
	v_mov_b32_e32 v7, v125
	v_pk_add_f32 v[6:7], v[126:127], v[6:7]
	v_fmac_f32_e32 v5, 0xba800000, v14
	v_fmac_f32_e32 v123, 0xba800000, v14
	v_pk_add_f32 v[124:125], v[6:7], v[6:7] op_sel_hi:[0,1]
	v_fmac_f32_e32 v4, 0xba800000, v14
	v_mov_b32_e32 v6, v123
	v_mov_b32_e32 v7, v5
	v_mov_b32_e32 v5, v122
	v_pk_mul_f32 v[126:127], v[6:7], v[6:7]
	v_pk_mul_f32 v[122:123], v[4:5], v[4:5]
	v_fmac_f32_e32 v8, 0xba800000, v14
	v_pk_mov_b32 v[128:129], v[122:123], v[126:127] op_sel:[1,0]
	v_mov_b32_e32 v123, v127
	v_fmac_f32_e32 v9, 0xba800000, v14
	v_fmac_f32_e32 v10, 0xba800000, v14
	v_mul_f32_e32 v12, v8, v8
	v_pk_add_f32 v[122:123], v[128:129], v[122:123]
	v_fmac_f32_e32 v11, 0xba800000, v14
	v_pk_fma_f32 v[126:127], v[8:9], v[8:9], v[12:13] op_sel_hi:[1,1,0]
	v_mul_f32_e32 v12, v10, v10
	v_pk_add_f32 v[122:123], v[122:123], v[122:123] op_sel_hi:[0,1]
	v_pk_fma_f32 v[128:129], v[10:11], v[10:11], v[12:13] op_sel_hi:[1,1,0]
	v_fmac_f32_e32 v15, 0xba800000, v14
	v_fmac_f32_e32 v119, 0xba800000, v14
	v_fmac_f32_e32 v13, 0xba800000, v14
	v_fmac_f32_e32 v121, 0xba800000, v14
	v_mul_f32_e32 v126, v121, v121
	v_mul_f32_e32 v128, v13, v13
	v_mul_f32_e32 v124, v119, v119
	v_mul_f32_e32 v122, v15, v15
	v_pk_add_f32 v[126:127], v[126:127], v[128:129]
	v_pk_add_f32 v[122:123], v[124:125], v[122:123]
	s_nop 0
	v_pk_add_f32 v[122:123], v[126:127], v[122:123]
	s_nop 0
	v_add_f32_e32 v12, v122, v123
	s_waitcnt lgkmcnt(0)
	s_nop 1
	v_add_f32_dpp v12, v12, v12 quad_perm:[1,0,3,2] row_mask:0xf bank_mask:0xf
	s_waitcnt lgkmcnt(0)
	s_nop 1
	v_add_f32_dpp v12, v12, v12 quad_perm:[2,3,0,1] row_mask:0xf bank_mask:0xf
	s_waitcnt lgkmcnt(0)
	s_nop 1
	v_add_f32_dpp v12, v12, v12 row_half_mirror row_mask:0xf bank_mask:0xf
	s_waitcnt lgkmcnt(0)
	s_nop 1
	v_add_f32_dpp v12, v12, v12 row_mirror row_mask:0xf bank_mask:0xf
	s_waitcnt lgkmcnt(0)
	v_mov_b32_e32 v14, v12
	s_nop 1
	v_permlane16_swap_b32 v12, v14
	v_add_f32_e32 v12, v12, v14
	s_waitcnt lgkmcnt(0)
	v_mov_b32_e32 v14, v12
	s_nop 1
	v_permlane32_swap_b32 v12, v14
	v_add_f32_e32 v12, v12, v14
	v_fmamk_f32 v12, v12, 0x3a800000, v227
	v_cmp_gt_f32_e32 vcc, s47, v12
	v_mul_f32_e32 v14, 0x4f800000, v12
	s_nop 0
	v_cndmask_b32_e32 v12, v12, v14, vcc
	v_sqrt_f32_e32 v14, v12
	s_nop 0
	v_add_u32_e32 v118, -1, v14
	v_fma_f32 v120, -v118, v14, v12
	v_cmp_ge_f32_e64 s[8:9], 0, v120
	v_add_u32_e32 v120, 1, v14
	s_nop 0
	v_cndmask_b32_e64 v118, v14, v118, s[8:9]
	v_fma_f32 v14, -v120, v14, v12
	v_cmp_lt_f32_e64 s[8:9], 0, v14
	s_nop 1
	v_cndmask_b32_e64 v14, v118, v120, s[8:9]
	v_mul_f32_e32 v118, 0x37800000, v14
	v_cndmask_b32_e32 v14, v14, v118, vcc
	v_cmp_class_f32_e32 vcc, v12, v228
	s_nop 1
	v_cndmask_b32_e32 v12, v14, v12, vcc
	v_div_scale_f32 v14, s[0:1], v12, v12, 1.0
	v_rcp_f32_e32 v118, v14
	s_mov_b64 s[0:1], -1
	v_fma_f32 v120, -v14, v118, 1.0
	v_fmac_f32_e32 v118, v120, v118
	v_div_scale_f32 v120, vcc, 1.0, v12, 1.0
	v_mul_f32_e32 v122, v120, v118
	v_fma_f32 v123, -v14, v122, v120
	v_fmac_f32_e32 v122, v123, v118
	v_fma_f32 v14, -v14, v122, v120
	v_div_fmas_f32 v14, v14, v118, v122
	v_div_fixup_f32 v118, v14, v12, 1.0
	v_pk_mul_f32 v[126:127], v[0:1], v[118:119] op_sel_hi:[1,0]
	v_pk_mul_f32 v[128:129], v[2:3], v[118:119] op_sel_hi:[1,0]
	ds_read_b128 v[0:3], v190
	ds_read_b128 v[122:125], v190 offset:4096
	v_mov_b32_e32 v12, v121
	v_mov_b32_e32 v14, v119
	s_and_b64 vcc, exec, s[6:7]
	s_waitcnt lgkmcnt(0)
	v_pk_fma_f32 v[2:3], v[2:3], v[128:129], v[124:125]
	v_pk_fma_f32 v[0:1], v[0:1], v[126:127], v[122:123]
	v_pk_mul_f32 v[126:127], v[4:5], v[118:119] op_sel_hi:[1,0]
	v_pk_mul_f32 v[128:129], v[6:7], v[118:119] op_sel_hi:[1,0]
	ds_read_b128 v[4:7], v190 offset:1024
	ds_read_b128 v[122:125], v190 offset:5120
	s_waitcnt lgkmcnt(0)
	v_pk_fma_f32 v[6:7], v[6:7], v[128:129], v[124:125]
	v_pk_fma_f32 v[4:5], v[4:5], v[126:127], v[122:123]
	v_pk_mul_f32 v[126:127], v[8:9], v[118:119] op_sel_hi:[1,0]
	v_pk_mul_f32 v[128:129], v[10:11], v[118:119] op_sel_hi:[1,0]
	ds_read_b128 v[8:11], v190 offset:2048
	ds_read_b128 v[122:125], v190 offset:6144
	s_waitcnt lgkmcnt(0)
	v_pk_fma_f32 v[10:11], v[10:11], v[128:129], v[124:125]
	v_pk_fma_f32 v[8:9], v[8:9], v[126:127], v[122:123]
	v_pk_mul_f32 v[122:123], v[12:13], v[118:119] op_sel_hi:[1,0]
	v_pk_mul_f32 v[124:125], v[14:15], v[118:119] op_sel_hi:[1,0]
	ds_read_b128 v[12:15], v190 offset:3072
	ds_read_b128 v[118:121], v190 offset:7168
	s_waitcnt lgkmcnt(0)
	v_pk_fma_f32 v[14:15], v[14:15], v[124:125], v[120:121]
	v_pk_fma_f32 v[12:13], v[12:13], v[122:123], v[118:119]
	s_cbranch_vccnz .LBB0_986
	s_bitset1_b32 s86, 10
	v_lshl_add_u64 v[118:119], s[86:87], 2, v[30:31]
	s_mov_b64 s[0:1], 0
	global_store_dwordx4 v[118:119], v[0:3], off nt
	global_store_dwordx4 v[118:119], v[4:7], off offset:1024 nt
	global_store_dwordx4 v[118:119], v[8:11], off offset:2048 nt
	global_store_dwordx4 v[118:119], v[12:15], off offset:3072 nt

; #define LAS __attribute__((address_space(3)))
; __device__ __forceinline__ float bf_lo(unsigned u) { return __uint_as_float(u << 16); }
; __device__ __forceinline__ float bf_hi(unsigned u) { return __uint_as_float(u & 0xffff0000u); }
; __device__ __forceinline__ void ln_affine_l(f32x4 (&v)[4], const LAS float* gL, const LAS float* bL, int lane) {
;     float s = 0.f;
; #pragma unroll
;     for (int j = 0; j < 4; ++j) s += (v[j].x + v[j].y) + (v[j].z + v[j].w);
;     const float mean = wave_sum(s) * (1.f / D_); float s2 = 0.f;
; #pragma unroll
;     for (int j = 0; j < 4; ++j) { v[j] = v[j] - mean; s2 += (v[j].x * v[j].x + v[j].y * v[j].y) + (v[j].z * v[j].z + v[j].w * v[j].w); }
;     const float rstd = 1.f / sqrtf(wave_sum(s2) * (1.f / D_) + LN_EPS_);
; #pragma unroll
;     for (int j = 0; j < 4; ++j) v[j] = v[j] * rstd * *(const LAS f32x4*)(gL + 4 * lane + 256 * j) + *(const LAS f32x4*)(bL + 4 * lane + 256 * j);
; }
; __device__ __forceinline__ void combine_ln2_tile(KArgs A, int l, int tile, int lane, const LAS float* gL, const LAS float* bL) {
;     ...
;         for (int i = 0; i < 4; ++i) {
; #pragma unroll
;             for (int j = 0; j < 4; ++j) { f32x4 v = (f32x4){bf_lo(hr[i][j].x), bf_hi(hr[i][j].x), bf_lo(hr[i][j].y), bf_hi(hr[i][j].y)} * ALPHA_;
; #pragma unroll
;                 for (int k = 0; k < 4; ++k) { v.x += bf_lo(q[i][k][j].x); v.y += bf_hi(q[i][k][j].x); v.z += bf_lo(q[i][k][j].y); v.w += bf_hi(q[i][k][j].y); }
;                 hv[i][j] = v; }
;             unsigned m = msk[i];
;             while (m) { const int e = __builtin_ctz(m); m &= m - 1u; add_ye_row(hv[i], ye + ((size_t)e * NB * CAP + __builtin_amdgcn_readlane(slk, 16 * i + e)) * D_, lane); }
;             ln_affine_l(hv[i], gL, bL, lane);
;             if (l == DEPTH_ - 1) store_row_f32_nt(O + (size_t)(r0 + i) * D_, hv[i], lane);
;             else store_row_bf16(HB + (size_t)(r0 + i) * D_, hv[i], lane);
.LBB0_990:
	v_mov_b32_e32 v81, v4
	v_mov_b32_e32 v80, v7
	v_mov_b32_e32 v4, v6
	v_mov_b32_e32 v7, v0
	v_mov_b32_e32 v6, v3
	v_mov_b32_e32 v0, v2
	v_pk_add_f32 v[2:3], v[6:7], v[0:1]
	v_mov_b32_e32 v77, v14
	v_add_f32_e32 v2, v2, v3
	v_add_f32_e32 v78, 0, v2
	v_pk_add_f32 v[2:3], v[80:81], v[4:5]
	v_mov_b32_e32 v79, v12
	v_pk_add_f32 v[2:3], v[2:3], v[2:3] op_sel:[0,1] op_sel_hi:[1,0]
	v_add_f32_e32 v76, v8, v9
	v_add_f32_e32 v14, v10, v11
	v_mov_b32_e32 v3, v13
	v_pk_add_f32 v[2:3], v[78:79], v[2:3]
	v_pk_add_f32 v[82:83], v[76:77], v[14:15]
	s_nop 0
	v_pk_add_f32 v[2:3], v[2:3], v[82:83]
	s_nop 0
	v_add_f32_e32 v2, v2, v3
	s_waitcnt lgkmcnt(0)
	s_nop 1
	v_add_f32_dpp v2, v2, v2 quad_perm:[1,0,3,2] row_mask:0xf bank_mask:0xf
	s_waitcnt lgkmcnt(0)
	s_nop 1
	v_add_f32_dpp v2, v2, v2 quad_perm:[2,3,0,1] row_mask:0xf bank_mask:0xf
	s_waitcnt lgkmcnt(0)
	s_nop 1
	v_add_f32_dpp v2, v2, v2 row_half_mirror row_mask:0xf bank_mask:0xf
	s_waitcnt lgkmcnt(0)
	s_nop 1
	v_add_f32_dpp v2, v2, v2 row_mirror row_mask:0xf bank_mask:0xf
	s_waitcnt lgkmcnt(0)
	v_mov_b32_e32 v3, v2
	s_nop 1
	v_permlane16_swap_b32 v2, v3
	v_add_f32_e32 v2, v2, v3
	s_waitcnt lgkmcnt(0)
	v_mov_b32_e32 v3, v2
	v_mov_b32_e32 v14, v2
	s_nop 1
	v_permlane32_swap_b32 v14, v3
	v_add_f32_e32 v14, v14, v3
	v_fmac_f32_e32 v6, 0xba800000, v14
	v_fmac_f32_e32 v1, 0xba800000, v14
	v_fmac_f32_e32 v7, 0xba800000, v14
	v_fmac_f32_e32 v0, 0xba800000, v14
	v_mov_b32_e32 v2, v7
	v_mov_b32_e32 v3, v1
	v_mov_b32_e32 v1, v6
	v_pk_mul_f32 v[82:83], v[2:3], v[2:3]
	v_pk_mul_f32 v[6:7], v[0:1], v[0:1]
	v_fmac_f32_e32 v80, 0xba800000, v14
	v_pk_mov_b32 v[84:85], v[6:7], v[82:83] op_sel:[1,0]
	v_mov_b32_e32 v7, v83
	v_pk_add_f32 v[6:7], v[84:85], v[6:7]
	v_fmac_f32_e32 v5, 0xba800000, v14
	v_fmac_f32_e32 v81, 0xba800000, v14
	v_pk_add_f32 v[82:83], v[6:7], v[6:7] op_sel_hi:[0,1]
	v_fmac_f32_e32 v4, 0xba800000, v14
	v_mov_b32_e32 v6, v81
	v_mov_b32_e32 v7, v5
	v_mov_b32_e32 v5, v80
	v_pk_mul_f32 v[84:85], v[6:7], v[6:7]
	v_pk_mul_f32 v[80:81], v[4:5], v[4:5]
	v_fmac_f32_e32 v8, 0xba800000, v14
	v_pk_mov_b32 v[86:87], v[80:81], v[84:85] op_sel:[1,0]
	v_mov_b32_e32 v81, v85
	v_fmac_f32_e32 v9, 0xba800000, v14
	v_fmac_f32_e32 v10, 0xba800000, v14
	v_mul_f32_e32 v12, v8, v8
	v_pk_add_f32 v[80:81], v[86:87], v[80:81]
	v_fmac_f32_e32 v11, 0xba800000, v14
	v_pk_fma_f32 v[84:85], v[8:9], v[8:9], v[12:13] op_sel_hi:[1,1,0]
	v_mul_f32_e32 v12, v10, v10
	v_pk_add_f32 v[80:81], v[80:81], v[80:81] op_sel_hi:[0,1]
	v_pk_fma_f32 v[86:87], v[10:11], v[10:11], v[12:13] op_sel_hi:[1,1,0]
	v_fmac_f32_e32 v15, 0xba800000, v14
	v_fmac_f32_e32 v77, 0xba800000, v14
	v_fmac_f32_e32 v13, 0xba800000, v14
	v_fmac_f32_e32 v79, 0xba800000, v14
	v_mul_f32_e32 v84, v79, v79
	v_mul_f32_e32 v86, v13, v13
	v_mul_f32_e32 v82, v77, v77
	v_mul_f32_e32 v80, v15, v15
	v_pk_add_f32 v[84:85], v[84:85], v[86:87]
	v_pk_add_f32 v[80:81], v[82:83], v[80:81]
	s_nop 0
	v_pk_add_f32 v[80:81], v[84:85], v[80:81]
	s_nop 0
	v_add_f32_e32 v12, v80, v81
	s_waitcnt lgkmcnt(0)
	s_nop 1
	v_add_f32_dpp v12, v12, v12 quad_perm:[1,0,3,2] row_mask:0xf bank_mask:0xf
	s_waitcnt lgkmcnt(0)
	s_nop 1
	v_add_f32_dpp v12, v12, v12 quad_perm:[2,3,0,1] row_mask:0xf bank_mask:0xf
	s_waitcnt lgkmcnt(0)
	s_nop 1
	v_add_f32_dpp v12, v12, v12 row_half_mirror row_mask:0xf bank_mask:0xf
	s_waitcnt lgkmcnt(0)
	s_nop 1
	v_add_f32_dpp v12, v12, v12 row_mirror row_mask:0xf bank_mask:0xf
	s_waitcnt lgkmcnt(0)
	v_mov_b32_e32 v14, v12
	s_nop 1
	v_permlane16_swap_b32 v12, v14
	v_add_f32_e32 v12, v12, v14
	s_waitcnt lgkmcnt(0)
	v_mov_b32_e32 v14, v12
	s_nop 1
	v_permlane32_swap_b32 v12, v14
	v_add_f32_e32 v12, v12, v14
	v_fmamk_f32 v12, v12, 0x3a800000, v227
	v_cmp_gt_f32_e32 vcc, s47, v12
	v_mul_f32_e32 v14, 0x4f800000, v12
	s_nop 0
	v_cndmask_b32_e32 v12, v12, v14, vcc
	v_sqrt_f32_e32 v14, v12
	s_nop 0
	v_add_u32_e32 v76, -1, v14
	v_fma_f32 v78, -v76, v14, v12
	v_cmp_ge_f32_e64 s[8:9], 0, v78
	v_add_u32_e32 v78, 1, v14
	s_nop 0
	v_cndmask_b32_e64 v76, v14, v76, s[8:9]
	v_fma_f32 v14, -v78, v14, v12
	v_cmp_lt_f32_e64 s[8:9], 0, v14
	s_nop 1
	v_cndmask_b32_e64 v14, v76, v78, s[8:9]
	v_mul_f32_e32 v76, 0x37800000, v14
	v_cndmask_b32_e32 v14, v14, v76, vcc
	v_cmp_class_f32_e32 vcc, v12, v228
	s_nop 1
	v_cndmask_b32_e32 v12, v14, v12, vcc
	v_div_scale_f32 v14, s[0:1], v12, v12, 1.0
	v_rcp_f32_e32 v76, v14
	s_mov_b64 s[0:1], -1
	v_fma_f32 v78, -v14, v76, 1.0
	v_fmac_f32_e32 v76, v78, v76
	v_div_scale_f32 v78, vcc, 1.0, v12, 1.0
	v_mul_f32_e32 v80, v78, v76
	v_fma_f32 v81, -v14, v80, v78
	v_fmac_f32_e32 v80, v81, v76
	v_fma_f32 v14, -v14, v80, v78
	v_div_fmas_f32 v14, v14, v76, v80
	v_div_fixup_f32 v76, v14, v12, 1.0
	v_pk_mul_f32 v[84:85], v[0:1], v[76:77] op_sel_hi:[1,0]
	v_pk_mul_f32 v[86:87], v[2:3], v[76:77] op_sel_hi:[1,0]
	ds_read_b128 v[0:3], v190
	ds_read_b128 v[80:83], v190 offset:4096
	v_mov_b32_e32 v12, v79
	v_mov_b32_e32 v14, v77
	s_and_b64 vcc, exec, s[6:7]
	s_waitcnt lgkmcnt(0)
	v_pk_fma_f32 v[2:3], v[2:3], v[86:87], v[82:83]
	v_pk_fma_f32 v[0:1], v[0:1], v[84:85], v[80:81]
	v_pk_mul_f32 v[84:85], v[4:5], v[76:77] op_sel_hi:[1,0]
	v_pk_mul_f32 v[86:87], v[6:7], v[76:77] op_sel_hi:[1,0]
	ds_read_b128 v[4:7], v190 offset:1024
	ds_read_b128 v[80:83], v190 offset:5120
	s_waitcnt lgkmcnt(0)
	v_pk_fma_f32 v[6:7], v[6:7], v[86:87], v[82:83]
	v_pk_fma_f32 v[4:5], v[4:5], v[84:85], v[80:81]
	v_pk_mul_f32 v[84:85], v[8:9], v[76:77] op_sel_hi:[1,0]
	v_pk_mul_f32 v[86:87], v[10:11], v[76:77] op_sel_hi:[1,0]
	ds_read_b128 v[8:11], v190 offset:2048
	ds_read_b128 v[80:83], v190 offset:6144
	s_waitcnt lgkmcnt(0)
	v_pk_fma_f32 v[10:11], v[10:11], v[86:87], v[82:83]
	v_pk_fma_f32 v[8:9], v[8:9], v[84:85], v[80:81]
	v_pk_mul_f32 v[80:81], v[12:13], v[76:77] op_sel_hi:[1,0]
	v_pk_mul_f32 v[82:83], v[14:15], v[76:77] op_sel_hi:[1,0]
	ds_read_b128 v[12:15], v190 offset:3072
	ds_read_b128 v[76:79], v190 offset:7168
	s_waitcnt lgkmcnt(0)
	v_pk_fma_f32 v[14:15], v[14:15], v[82:83], v[78:79]
	v_pk_fma_f32 v[12:13], v[12:13], v[80:81], v[76:77]
	s_cbranch_vccnz .LBB0_992
	v_lshl_add_u64 v[76:77], s[16:17], 2, v[30:31]
	s_mov_b64 s[0:1], 0
	global_store_dwordx4 v[76:77], v[0:3], off nt
	global_store_dwordx4 v[76:77], v[4:7], off offset:1024 nt
	global_store_dwordx4 v[76:77], v[8:11], off offset:2048 nt
	global_store_dwordx4 v[76:77], v[12:15], off offset:3072 nt

; #define LAS __attribute__((address_space(3)))
; __device__ __forceinline__ float bf_lo(unsigned u) { return __uint_as_float(u << 16); }
; __device__ __forceinline__ float bf_hi(unsigned u) { return __uint_as_float(u & 0xffff0000u); }
; __device__ __forceinline__ void ln_affine_l(f32x4 (&v)[4], const LAS float* gL, const LAS float* bL, int lane) {
;     float s = 0.f;
; #pragma unroll
;     for (int j = 0; j < 4; ++j) s += (v[j].x + v[j].y) + (v[j].z + v[j].w);
;     const float mean = wave_sum(s) * (1.f / D_); float s2 = 0.f;
; #pragma unroll
;     for (int j = 0; j < 4; ++j) { v[j] = v[j] - mean; s2 += (v[j].x * v[j].x + v[j].y * v[j].y) + (v[j].z * v[j].z + v[j].w * v[j].w); }
;     const float rstd = 1.f / sqrtf(wave_sum(s2) * (1.f / D_) + LN_EPS_);
; #pragma unroll
;     for (int j = 0; j < 4; ++j) v[j] = v[j] * rstd * *(const LAS f32x4*)(gL + 4 * lane + 256 * j) + *(const LAS f32x4*)(bL + 4 * lane + 256 * j);
; }
; __device__ __forceinline__ void combine_ln2_tile(KArgs A, int l, int tile, int lane, const LAS float* gL, const LAS float* bL) {
;     ...
;         for (int i = 0; i < 4; ++i) {
; #pragma unroll
;             for (int j = 0; j < 4; ++j) { f32x4 v = (f32x4){bf_lo(hr[i][j].x), bf_hi(hr[i][j].x), bf_lo(hr[i][j].y), bf_hi(hr[i][j].y)} * ALPHA_;
; #pragma unroll
;                 for (int k = 0; k < 4; ++k) { v.x += bf_lo(q[i][k][j].x); v.y += bf_hi(q[i][k][j].x); v.z += bf_lo(q[i][k][j].y); v.w += bf_hi(q[i][k][j].y); }
;                 hv[i][j] = v; }
;             unsigned m = msk[i];
;             while (m) { const int e = __builtin_ctz(m); m &= m - 1u; add_ye_row(hv[i], ye + ((size_t)e * NB * CAP + __builtin_amdgcn_readlane(slk, 16 * i + e)) * D_, lane); }
;             ln_affine_l(hv[i], gL, bL, lane);
;             if (l == DEPTH_ - 1) store_row_f32_nt(O + (size_t)(r0 + i) * D_, hv[i], lane);
;             else store_row_bf16(HB + (size_t)(r0 + i) * D_, hv[i], lane);
.LBB0_996:
	v_mov_b32_e32 v39, v4
	v_mov_b32_e32 v38, v7
	v_mov_b32_e32 v4, v6
	v_mov_b32_e32 v7, v0
	v_mov_b32_e32 v6, v3
	v_mov_b32_e32 v0, v2
	v_pk_add_f32 v[2:3], v[6:7], v[0:1]
	v_mov_b32_e32 v35, v14
	v_add_f32_e32 v2, v2, v3
	v_add_f32_e32 v36, 0, v2
	v_pk_add_f32 v[2:3], v[38:39], v[4:5]
	v_mov_b32_e32 v37, v12
	v_pk_add_f32 v[2:3], v[2:3], v[2:3] op_sel:[0,1] op_sel_hi:[1,0]
	v_add_f32_e32 v34, v8, v9
	v_add_f32_e32 v14, v10, v11
	v_mov_b32_e32 v3, v13
	v_pk_add_f32 v[2:3], v[36:37], v[2:3]
	v_pk_add_f32 v[40:41], v[34:35], v[14:15]
	s_nop 0
	v_pk_add_f32 v[2:3], v[2:3], v[40:41]
	s_nop 0
	v_add_f32_e32 v2, v2, v3
	s_waitcnt lgkmcnt(0)
	s_nop 1
	v_add_f32_dpp v2, v2, v2 quad_perm:[1,0,3,2] row_mask:0xf bank_mask:0xf
	s_waitcnt lgkmcnt(0)
	s_nop 1
	v_add_f32_dpp v2, v2, v2 quad_perm:[2,3,0,1] row_mask:0xf bank_mask:0xf
	s_waitcnt lgkmcnt(0)
	s_nop 1
	v_add_f32_dpp v2, v2, v2 row_half_mirror row_mask:0xf bank_mask:0xf
	s_waitcnt lgkmcnt(0)
	s_nop 1
	v_add_f32_dpp v2, v2, v2 row_mirror row_mask:0xf bank_mask:0xf
	s_waitcnt lgkmcnt(0)
	v_mov_b32_e32 v3, v2
	s_nop 1
	v_permlane16_swap_b32 v2, v3
	v_add_f32_e32 v2, v2, v3
	s_waitcnt lgkmcnt(0)
	v_mov_b32_e32 v3, v2
	v_mov_b32_e32 v14, v2
	s_nop 1
	v_permlane32_swap_b32 v14, v3
	v_add_f32_e32 v14, v14, v3
	v_fmac_f32_e32 v6, 0xba800000, v14
	v_fmac_f32_e32 v1, 0xba800000, v14
	v_fmac_f32_e32 v7, 0xba800000, v14
	v_fmac_f32_e32 v0, 0xba800000, v14
	v_mov_b32_e32 v2, v7
	v_mov_b32_e32 v3, v1
	v_mov_b32_e32 v1, v6
	v_pk_mul_f32 v[40:41], v[2:3], v[2:3]
	v_pk_mul_f32 v[6:7], v[0:1], v[0:1]
	v_fmac_f32_e32 v38, 0xba800000, v14
	v_pk_mov_b32 v[42:43], v[6:7], v[40:41] op_sel:[1,0]
	v_mov_b32_e32 v7, v41
	v_pk_add_f32 v[6:7], v[42:43], v[6:7]
	v_fmac_f32_e32 v5, 0xba800000, v14
	v_fmac_f32_e32 v39, 0xba800000, v14
	v_pk_add_f32 v[40:41], v[6:7], v[6:7] op_sel_hi:[0,1]
	v_fmac_f32_e32 v4, 0xba800000, v14
	v_mov_b32_e32 v6, v39
	v_mov_b32_e32 v7, v5
	v_mov_b32_e32 v5, v38
	v_pk_mul_f32 v[42:43], v[6:7], v[6:7]
	v_pk_mul_f32 v[38:39], v[4:5], v[4:5]
	v_fmac_f32_e32 v8, 0xba800000, v14
	v_pk_mov_b32 v[44:45], v[38:39], v[42:43] op_sel:[1,0]
	v_mov_b32_e32 v39, v43
	v_fmac_f32_e32 v9, 0xba800000, v14
	v_fmac_f32_e32 v10, 0xba800000, v14
	v_mul_f32_e32 v12, v8, v8
	v_pk_add_f32 v[38:39], v[44:45], v[38:39]
	v_fmac_f32_e32 v11, 0xba800000, v14
	v_pk_fma_f32 v[42:43], v[8:9], v[8:9], v[12:13] op_sel_hi:[1,1,0]
	v_mul_f32_e32 v12, v10, v10
	v_pk_add_f32 v[38:39], v[38:39], v[38:39] op_sel_hi:[0,1]
	v_pk_fma_f32 v[44:45], v[10:11], v[10:11], v[12:13] op_sel_hi:[1,1,0]
	v_fmac_f32_e32 v15, 0xba800000, v14
	v_fmac_f32_e32 v35, 0xba800000, v14
	v_fmac_f32_e32 v13, 0xba800000, v14
	v_fmac_f32_e32 v37, 0xba800000, v14
	v_mul_f32_e32 v42, v37, v37
	v_mul_f32_e32 v44, v13, v13
	v_mul_f32_e32 v40, v35, v35
	v_mul_f32_e32 v38, v15, v15
	v_pk_add_f32 v[42:43], v[42:43], v[44:45]
	v_pk_add_f32 v[38:39], v[40:41], v[38:39]
	s_nop 0
	v_pk_add_f32 v[38:39], v[42:43], v[38:39]
	s_nop 0
	v_add_f32_e32 v12, v38, v39
	s_waitcnt lgkmcnt(0)
	s_nop 1
	v_add_f32_dpp v12, v12, v12 quad_perm:[1,0,3,2] row_mask:0xf bank_mask:0xf
	s_waitcnt lgkmcnt(0)
	s_nop 1
	v_add_f32_dpp v12, v12, v12 quad_perm:[2,3,0,1] row_mask:0xf bank_mask:0xf
	s_waitcnt lgkmcnt(0)
	s_nop 1
	v_add_f32_dpp v12, v12, v12 row_half_mirror row_mask:0xf bank_mask:0xf
	s_waitcnt lgkmcnt(0)
	s_nop 1
	v_add_f32_dpp v12, v12, v12 row_mirror row_mask:0xf bank_mask:0xf
	s_waitcnt lgkmcnt(0)
	v_mov_b32_e32 v14, v12
	s_nop 1
	v_permlane16_swap_b32 v12, v14
	v_add_f32_e32 v12, v12, v14
	s_waitcnt lgkmcnt(0)
	v_mov_b32_e32 v14, v12
	s_nop 1
	v_permlane32_swap_b32 v12, v14
	v_add_f32_e32 v12, v12, v14
	v_fmamk_f32 v12, v12, 0x3a800000, v227
	v_cmp_gt_f32_e32 vcc, s47, v12
	v_mul_f32_e32 v14, 0x4f800000, v12
	s_nop 0
	v_cndmask_b32_e32 v12, v12, v14, vcc
	v_sqrt_f32_e32 v14, v12
	s_nop 0
	v_add_u32_e32 v34, -1, v14
	v_fma_f32 v36, -v34, v14, v12
	v_cmp_ge_f32_e64 s[8:9], 0, v36
	v_add_u32_e32 v36, 1, v14
	s_nop 0
	v_cndmask_b32_e64 v34, v14, v34, s[8:9]
	v_fma_f32 v14, -v36, v14, v12
	v_cmp_lt_f32_e64 s[8:9], 0, v14
	s_nop 1
	v_cndmask_b32_e64 v14, v34, v36, s[8:9]
	v_mul_f32_e32 v34, 0x37800000, v14
	v_cndmask_b32_e32 v14, v14, v34, vcc
	v_cmp_class_f32_e32 vcc, v12, v228
	s_nop 1
	v_cndmask_b32_e32 v12, v14, v12, vcc
	v_div_scale_f32 v14, s[0:1], v12, v12, 1.0
	v_rcp_f32_e32 v34, v14
	s_mov_b64 s[0:1], -1
	v_fma_f32 v36, -v14, v34, 1.0
	v_fmac_f32_e32 v34, v36, v34
	v_div_scale_f32 v36, vcc, 1.0, v12, 1.0
	v_mul_f32_e32 v38, v36, v34
	v_fma_f32 v39, -v14, v38, v36
	v_fmac_f32_e32 v38, v39, v34
	v_fma_f32 v14, -v14, v38, v36
	v_div_fmas_f32 v14, v14, v34, v38
	v_div_fixup_f32 v34, v14, v12, 1.0
	v_pk_mul_f32 v[42:43], v[0:1], v[34:35] op_sel_hi:[1,0]
	v_pk_mul_f32 v[44:45], v[2:3], v[34:35] op_sel_hi:[1,0]
	ds_read_b128 v[0:3], v190
	ds_read_b128 v[38:41], v190 offset:4096
	v_mov_b32_e32 v12, v37
	v_mov_b32_e32 v14, v35
	s_and_b64 vcc, exec, s[6:7]
	s_waitcnt lgkmcnt(0)
	v_pk_fma_f32 v[2:3], v[2:3], v[44:45], v[40:41]
	v_pk_fma_f32 v[0:1], v[0:1], v[42:43], v[38:39]
	v_pk_mul_f32 v[42:43], v[4:5], v[34:35] op_sel_hi:[1,0]
	v_pk_mul_f32 v[44:45], v[6:7], v[34:35] op_sel_hi:[1,0]
	ds_read_b128 v[4:7], v190 offset:1024
	ds_read_b128 v[38:41], v190 offset:5120
	s_waitcnt lgkmcnt(0)
	v_pk_fma_f32 v[6:7], v[6:7], v[44:45], v[40:41]
	v_pk_fma_f32 v[4:5], v[4:5], v[42:43], v[38:39]
	v_pk_mul_f32 v[42:43], v[8:9], v[34:35] op_sel_hi:[1,0]
	v_pk_mul_f32 v[44:45], v[10:11], v[34:35] op_sel_hi:[1,0]
	ds_read_b128 v[8:11], v190 offset:2048
	ds_read_b128 v[38:41], v190 offset:6144
	s_waitcnt lgkmcnt(0)
	v_pk_fma_f32 v[10:11], v[10:11], v[44:45], v[40:41]
	v_pk_fma_f32 v[8:9], v[8:9], v[42:43], v[38:39]
	v_pk_mul_f32 v[38:39], v[12:13], v[34:35] op_sel_hi:[1,0]
	v_pk_mul_f32 v[40:41], v[14:15], v[34:35] op_sel_hi:[1,0]
	ds_read_b128 v[12:15], v190 offset:3072
	ds_read_b128 v[34:37], v190 offset:7168
	s_waitcnt lgkmcnt(0)
	v_pk_fma_f32 v[14:15], v[14:15], v[40:41], v[36:37]
	v_pk_fma_f32 v[12:13], v[12:13], v[38:39], v[34:35]
	s_cbranch_vccnz .LBB0_998
	v_lshl_add_u64 v[34:35], s[10:11], 2, v[30:31]
	global_store_dwordx4 v[34:35], v[0:3], off nt
	global_store_dwordx4 v[34:35], v[4:7], off offset:1024 nt
	global_store_dwordx4 v[34:35], v[8:11], off offset:2048 nt
	global_store_dwordx4 v[34:35], v[12:15], off offset:3072 nt
	s_cbranch_execnz .LBB0_927
	s_branch .LBB0_999
